# loop-edge edit 7.11: GEMM K-loop back-edge scalar work moved before the loop-back barrier (8 loops)
# baseline (speedup 1.0000x reference)
; #define PG8_STAGE(bufoff, gbase, voff) do { _Pragma("unroll") for (int _i = 0; _i < 2; ++_i) \
;         __builtin_amdgcn_global_load_lds((const unsigned*)((const char*)(gbase) + (voff)[_i]), (LAS unsigned*)(lds + (bufoff) + ldsw + _i * 8192), 16, 0, 0); } while (0)
; #define PG8_LDA(dst, b, h) do { _Pragma("unroll") for (int m = 0; m < 4; ++m) _Pragma("unroll") for (int k = 0; k < 2; ++k) dst[m][k] = *(const LAS bf16x8*)(lds + PG8_SA(b, h) + aoff + m * 2048 + k * 1024); } while (0)
; #define PG8_LDB(dst, b, h) do { _Pragma("unroll") for (int n = 0; n < 2; ++n) _Pragma("unroll") for (int k = 0; k < 2; ++k) dst[n][k] = *(const LAS bf16x8*)(lds + PG8_SB(b, h) + boff + n * 2048 + k * 1024); } while (0)
; #define PG8_MMA(ai, bj, At, Bt) do { __builtin_amdgcn_s_setprio(1); _Pragma("unroll") for (int m = 0; m < 4; ++m) _Pragma("unroll") for (int n = 0; n < 2; ++n) _Pragma("unroll") for (int k = 0; k < 2; ++k) \
;         acc[ai][bj][m][n] = __builtin_amdgcn_mfma_f32_16x16x32_bf16(Bt[n][k], At[m][k], acc[ai][bj][m][n], 0, 0, 0); __builtin_amdgcn_s_setprio(0); } while (0)
; #define PG8_WAIT_V(n) asm volatile("s_waitcnt vmcnt(" #n ")" ::: "memory")
; #define PG8_WAIT_L(n) asm volatile("s_waitcnt lgkmcnt(" #n ")" ::: "memory")
; #define PG8_BAR __builtin_amdgcn_s_barrier()
; template <class Epi, class Sched>
; __device__ __forceinline__ void gemm_phase(LAS unsigned char* lds, const Gemm g, const Sched& S, const Epi& E) {
;     ...
;         for (int t = 0; t < nt; t += 2) {
;             if constexpr (Epi::HOOKS) { if (cur.kind == 3 && (t == 4 || t == 12)) { int fr_ = fr, fq_ = fq; asm volatile("" : "+v"(fr_), "+v"(fq_)); E.hook(acc, cur, t == 4 ? 0 : 1, wr, wc, fr_, fq_); } }
;             const bool last = (t == nt - 2);
;             const char* a1 = cA + (size_t)(t + 1) * kstep;
;             const char* a2 = last ? nA : cA + (size_t)(t + 2) * kstep; const char* b2 = last ? nB : cB + (size_t)(t + 2) * kstep;
;             const char* a3 = a2 + kstep; const char* b3 = b2 + kstep;
;             PG8_LDB(B0, 0, 0); PG8_LDB(B1, 0, 1); PG8_SCHED; PG8_LDA(At, 0, 0); PG8_STAGE(PG8_SA(1, 1), a1 + hstepA, voffA);
;             PG8_WAIT_V(8); PG8_WAIT_L(0); PG8_BAR; PG8_MMA(0, 0, At, B0); PG8_MMA(0, 1, At, B1); PG8_BAR; PG8_SCHED;
;             PG8_LDA(At, 0, 1); PG8_STAGE(PG8_SB(0, 0), b2, voffB); PG8_STAGE(PG8_SB(0, 1), b2 + hstepB, voffB); PG8_STAGE(PG8_SA(0, 0), a2, voffA);
.LBB0_101:
	s_add_i32 s68, s0, 2
	s_add_u32 s1, s20, 0xfff00080
	s_addc_u32 s42, s21, -1
	s_add_i32 s52, 0, 0x10000
	s_cmp_eq_u32 s72, s0
	s_cselect_b32 s43, s41, s42
	s_cselect_b32 s42, s48, s1
	s_cselect_b32 s1, s85, s94
	s_cselect_b32 s0, s87, s93
	s_add_i32 s53, 0, 0x14000
	s_branch .Lrot_body_1
.Lrot_head_1:
	s_barrier
.Lrot_body_1:
	v_add_u32_e32 v152, s52, v166
	v_add_u32_e32 v172, s53, v166
	ds_read_b128 v[130:133], v152
	ds_read_b128 v[134:137], v152 offset:1024
	ds_read_b128 v[138:141], v152 offset:2048
	ds_read_b128 v[152:155], v152 offset:3072
	ds_read_b128 v[156:159], v172
	ds_read_b128 v[160:163], v172 offset:1024
	ds_read_b128 v[168:171], v172 offset:2048
	ds_read_b128 v[172:175], v172 offset:3072
	v_lshl_add_u64 v[184:185], s[20:21], 0, v[150:151]
	s_add_i32 m0, s15, 0xc000
	ds_read_b128 v[176:179], v167
	ds_read_b128 v[180:183], v167 offset:1024
	ds_read_b128 v[196:199], v167 offset:2048
	ds_read_b128 v[200:203], v167 offset:3072
	ds_read_b128 v[204:207], v167 offset:4096
	ds_read_b128 v[208:211], v167 offset:5120
	ds_read_b128 v[212:215], v167 offset:6144
	ds_read_b128 v[216:219], v167 offset:7168
	global_load_lds_dwordx4 v[184:185], off
	v_lshl_add_u64 v[184:185], s[20:21], 0, v[148:149]
	s_add_i32 m0, s15, 0xe000
	s_nop 0
	global_load_lds_dwordx4 v[184:185], off
	s_waitcnt vmcnt(8)
	s_waitcnt lgkmcnt(0)
	s_barrier
	s_setprio 1
	s_waitcnt lgkmcnt(0)
	v_mfma_f32_16x16x32_bf16 v[126:129], v[130:133], v[176:179], v[126:129]
	v_mfma_f32_16x16x32_bf16 v[122:125], v[138:141], v[176:179], v[122:125]
	v_mfma_f32_16x16x32_bf16 v[110:113], v[130:133], v[196:199], v[110:113]
	v_mfma_f32_16x16x32_bf16 v[106:109], v[138:141], v[196:199], v[106:109]
	v_mfma_f32_16x16x32_bf16 v[94:97], v[130:133], v[204:207], v[94:97]
	v_mfma_f32_16x16x32_bf16 v[90:93], v[138:141], v[204:207], v[90:93]
	v_mfma_f32_16x16x32_bf16 v[78:81], v[130:133], v[212:215], v[78:81]
	v_mfma_f32_16x16x32_bf16 v[74:77], v[138:141], v[212:215], v[74:77]
	v_mfma_f32_16x16x32_bf16 v[126:129], v[134:137], v[180:183], v[126:129]
	v_mfma_f32_16x16x32_bf16 v[122:125], v[152:155], v[180:183], v[122:125]
	v_mfma_f32_16x16x32_bf16 v[110:113], v[134:137], v[200:203], v[110:113]
	v_mfma_f32_16x16x32_bf16 v[106:109], v[152:155], v[200:203], v[106:109]
	v_mfma_f32_16x16x32_bf16 v[94:97], v[134:137], v[208:211], v[94:97]
	v_mfma_f32_16x16x32_bf16 v[90:93], v[152:155], v[208:211], v[90:93]
	v_mfma_f32_16x16x32_bf16 v[78:81], v[134:137], v[216:219], v[78:81]
	v_mfma_f32_16x16x32_bf16 v[74:77], v[152:155], v[216:219], v[74:77]
	v_mfma_f32_16x16x32_bf16 v[118:121], v[156:159], v[176:179], v[118:121]
	v_mfma_f32_16x16x32_bf16 v[114:117], v[168:171], v[176:179], v[114:117]
	v_mfma_f32_16x16x32_bf16 v[102:105], v[156:159], v[196:199], v[102:105]
	v_mfma_f32_16x16x32_bf16 v[98:101], v[168:171], v[196:199], v[98:101]
	v_mfma_f32_16x16x32_bf16 v[86:89], v[156:159], v[204:207], v[86:89]
	v_mfma_f32_16x16x32_bf16 v[82:85], v[168:171], v[204:207], v[82:85]
	v_mfma_f32_16x16x32_bf16 v[70:73], v[156:159], v[212:215], v[70:73]
	v_mfma_f32_16x16x32_bf16 v[66:69], v[168:171], v[212:215], v[66:69]
	v_mfma_f32_16x16x32_bf16 v[118:121], v[160:163], v[180:183], v[118:121]
	v_mfma_f32_16x16x32_bf16 v[114:117], v[172:175], v[180:183], v[114:117]
	v_mfma_f32_16x16x32_bf16 v[102:105], v[160:163], v[200:203], v[102:105]
	v_mfma_f32_16x16x32_bf16 v[98:101], v[172:175], v[200:203], v[98:101]
	v_mfma_f32_16x16x32_bf16 v[86:89], v[160:163], v[208:211], v[86:89]
	v_mfma_f32_16x16x32_bf16 v[82:85], v[172:175], v[208:211], v[82:85]
	v_mfma_f32_16x16x32_bf16 v[70:73], v[160:163], v[216:219], v[70:73]
	v_mfma_f32_16x16x32_bf16 v[66:69], v[172:175], v[216:219], v[66:69]
	s_setprio 0
	s_barrier
	s_add_i32 s52, s52, s14
	v_lshl_add_u64 v[184:185], s[0:1], 0, v[0:1]
	s_mov_b32 m0, s52
	ds_read_b128 v[176:179], v167 offset:16384
	ds_read_b128 v[180:183], v167 offset:17408
	ds_read_b128 v[196:199], v167 offset:18432
	ds_read_b128 v[200:203], v167 offset:19456
	ds_read_b128 v[204:207], v167 offset:20480
	ds_read_b128 v[208:211], v167 offset:21504
	ds_read_b128 v[212:215], v167 offset:22528
	ds_read_b128 v[216:219], v167 offset:23552
	global_load_lds_dwordx4 v[184:185], off
	s_add_i32 m0, s52, 0x2000
	s_add_u32 s96, s0, 0x100000
	v_lshl_add_u64 v[220:221], s[0:1], 0, v[146:147]
	s_addc_u32 s97, s1, 0
	s_add_i32 s52, s53, s14
	global_load_lds_dwordx4 v[220:221], off
	v_lshl_add_u64 v[232:233], s[96:97], 0, v[0:1]
	s_mov_b32 m0, s52
	v_lshl_add_u64 v[234:235], s[42:43], 0, v[144:145]
	global_load_lds_dwordx4 v[232:233], off
	v_lshl_add_u64 v[232:233], s[96:97], 0, v[146:147]
	s_add_i32 m0, s52, 0x2000
	s_nop 0
	global_load_lds_dwordx4 v[232:233], off
	v_lshl_add_u64 v[232:233], s[42:43], 0, v[142:143]
	s_mov_b32 m0, s15
	s_nop 0
	global_load_lds_dwordx4 v[232:233], off
	s_mov_b32 m0, s16
	s_nop 0
	global_load_lds_dwordx4 v[234:235], off
	s_waitcnt vmcnt(8)
	s_waitcnt lgkmcnt(0)
	s_barrier
; #define PG8_STAGE(bufoff, gbase, voff) do { _Pragma("unroll") for (int _i = 0; _i < 2; ++_i) \
;         __builtin_amdgcn_global_load_lds((const unsigned*)((const char*)(gbase) + (voff)[_i]), (LAS unsigned*)(lds + (bufoff) + ldsw + _i * 8192), 16, 0, 0); } while (0)
; #define PG8_LDA(dst, b, h) do { _Pragma("unroll") for (int m = 0; m < 4; ++m) _Pragma("unroll") for (int k = 0; k < 2; ++k) dst[m][k] = *(const LAS bf16x8*)(lds + PG8_SA(b, h) + aoff + m * 2048 + k * 1024); } while (0)
; #define PG8_LDB(dst, b, h) do { _Pragma("unroll") for (int n = 0; n < 2; ++n) _Pragma("unroll") for (int k = 0; k < 2; ++k) dst[n][k] = *(const LAS bf16x8*)(lds + PG8_SB(b, h) + boff + n * 2048 + k * 1024); } while (0)
; #define PG8_MMA(ai, bj, At, Bt) do { __builtin_amdgcn_s_setprio(1); _Pragma("unroll") for (int m = 0; m < 4; ++m) _Pragma("unroll") for (int n = 0; n < 2; ++n) _Pragma("unroll") for (int k = 0; k < 2; ++k) \
;         acc[ai][bj][m][n] = __builtin_amdgcn_mfma_f32_16x16x32_bf16(Bt[n][k], At[m][k], acc[ai][bj][m][n], 0, 0, 0); __builtin_amdgcn_s_setprio(0); } while (0)
; #define PG8_WAIT_V(n) asm volatile("s_waitcnt vmcnt(" #n ")" ::: "memory")
; #define PG8_WAIT_L(n) asm volatile("s_waitcnt lgkmcnt(" #n ")" ::: "memory")
; #define PG8_BAR __builtin_amdgcn_s_barrier()
; #define PG8_SCHED __builtin_amdgcn_sched_barrier(0)
; template <class Epi, class Sched>
; __device__ __forceinline__ void gemm_phase(LAS unsigned char* lds, const Gemm g, const Sched& S, const Epi& E) {
;     ...
;             PG8_WAIT_V(8); PG8_WAIT_L(0); PG8_BAR; PG8_MMA(0, 0, At, B0); PG8_MMA(0, 1, At, B1); PG8_BAR; PG8_SCHED;
;             PG8_LDA(At, 0, 1); PG8_STAGE(PG8_SB(0, 0), b2, voffB); PG8_STAGE(PG8_SB(0, 1), b2 + hstepB, voffB); PG8_STAGE(PG8_SA(0, 0), a2, voffA);
;             PG8_WAIT_V(8); PG8_WAIT_L(0); PG8_BAR; PG8_MMA(1, 0, At, B0); PG8_MMA(1, 1, At, B1); PG8_BAR; PG8_SCHED;
;             PG8_LDB(B0, 1, 0); PG8_LDB(B1, 1, 1); PG8_SCHED; PG8_LDA(At, 1, 0); PG8_STAGE(PG8_SA(0, 1), a2 + hstepA, voffA);
;             PG8_WAIT_V(8); PG8_WAIT_L(0); PG8_BAR; PG8_MMA(0, 0, At, B0); PG8_MMA(0, 1, At, B1); PG8_BAR; PG8_SCHED;
	s_setprio 1
	s_waitcnt lgkmcnt(0)
	v_mfma_f32_16x16x32_bf16 v[62:65], v[130:133], v[176:179], v[62:65]
	v_mfma_f32_16x16x32_bf16 v[58:61], v[138:141], v[176:179], v[58:61]
	v_mfma_f32_16x16x32_bf16 v[46:49], v[130:133], v[196:199], v[46:49]
	v_mfma_f32_16x16x32_bf16 v[42:45], v[138:141], v[196:199], v[42:45]
	v_mfma_f32_16x16x32_bf16 v[30:33], v[130:133], v[204:207], v[30:33]
	v_mfma_f32_16x16x32_bf16 v[26:29], v[138:141], v[204:207], v[26:29]
	v_mfma_f32_16x16x32_bf16 v[14:17], v[130:133], v[212:215], v[14:17]
	v_mfma_f32_16x16x32_bf16 v[10:13], v[138:141], v[212:215], v[10:13]
	v_mfma_f32_16x16x32_bf16 v[62:65], v[134:137], v[180:183], v[62:65]
	v_mfma_f32_16x16x32_bf16 v[58:61], v[152:155], v[180:183], v[58:61]
	v_mfma_f32_16x16x32_bf16 v[46:49], v[134:137], v[200:203], v[46:49]
	v_mfma_f32_16x16x32_bf16 v[42:45], v[152:155], v[200:203], v[42:45]
	v_mfma_f32_16x16x32_bf16 v[30:33], v[134:137], v[208:211], v[30:33]
	v_mfma_f32_16x16x32_bf16 v[26:29], v[152:155], v[208:211], v[26:29]
	v_mfma_f32_16x16x32_bf16 v[14:17], v[134:137], v[216:219], v[14:17]
	v_mfma_f32_16x16x32_bf16 v[10:13], v[152:155], v[216:219], v[10:13]
	v_mfma_f32_16x16x32_bf16 v[54:57], v[156:159], v[176:179], v[54:57]
	v_mfma_f32_16x16x32_bf16 v[50:53], v[168:171], v[176:179], v[50:53]
	v_mfma_f32_16x16x32_bf16 v[38:41], v[156:159], v[196:199], v[38:41]
	v_mfma_f32_16x16x32_bf16 v[34:37], v[168:171], v[196:199], v[34:37]
	v_mfma_f32_16x16x32_bf16 v[22:25], v[156:159], v[204:207], v[22:25]
	v_mfma_f32_16x16x32_bf16 v[18:21], v[168:171], v[204:207], v[18:21]
	v_mfma_f32_16x16x32_bf16 v[6:9], v[156:159], v[212:215], v[6:9]
	v_mfma_f32_16x16x32_bf16 v[2:5], v[168:171], v[212:215], v[2:5]
	v_mfma_f32_16x16x32_bf16 v[54:57], v[160:163], v[180:183], v[54:57]
	v_mfma_f32_16x16x32_bf16 v[50:53], v[172:175], v[180:183], v[50:53]
	v_mfma_f32_16x16x32_bf16 v[38:41], v[160:163], v[200:203], v[38:41]
	v_mfma_f32_16x16x32_bf16 v[34:37], v[172:175], v[200:203], v[34:37]
	v_mfma_f32_16x16x32_bf16 v[22:25], v[160:163], v[208:211], v[22:25]
	v_mfma_f32_16x16x32_bf16 v[18:21], v[172:175], v[208:211], v[18:21]
	v_mfma_f32_16x16x32_bf16 v[6:9], v[160:163], v[216:219], v[6:9]
	v_mfma_f32_16x16x32_bf16 v[2:5], v[172:175], v[216:219], v[2:5]
	s_setprio 0
	s_barrier
	s_add_i32 s52, 0, 0x18000
	s_add_i32 s53, 0, 0x1c000
	v_add_u32_e32 v152, s52, v166
	v_add_u32_e32 v172, s53, v166
	ds_read_b128 v[130:133], v152
	ds_read_b128 v[134:137], v152 offset:1024
	ds_read_b128 v[138:141], v152 offset:2048
	ds_read_b128 v[152:155], v152 offset:3072
	ds_read_b128 v[156:159], v172
	ds_read_b128 v[160:163], v172 offset:1024
	ds_read_b128 v[168:171], v172 offset:2048
	ds_read_b128 v[172:175], v172 offset:3072
	s_add_u32 s42, s42, 0x100000
	s_addc_u32 s43, s43, 0
	s_mov_b32 m0, s17
	v_lshl_add_u64 v[236:237], s[42:43], 0, v[142:143]
	ds_read_b128 v[176:179], v167 offset:32768
	ds_read_b128 v[180:183], v167 offset:33792
	ds_read_b128 v[196:199], v167 offset:34816
	ds_read_b128 v[200:203], v167 offset:35840
	ds_read_b128 v[204:207], v167 offset:36864
	ds_read_b128 v[208:211], v167 offset:37888
	ds_read_b128 v[212:215], v167 offset:38912
	ds_read_b128 v[216:219], v167 offset:39936
	global_load_lds_dwordx4 v[236:237], off
	v_lshl_add_u64 v[236:237], s[42:43], 0, v[144:145]
	s_mov_b32 m0, s19
	s_nop 0
	global_load_lds_dwordx4 v[236:237], off
	s_waitcnt vmcnt(8)
	s_waitcnt lgkmcnt(0)
	s_barrier
	s_setprio 1
	s_waitcnt lgkmcnt(0)
	v_mfma_f32_16x16x32_bf16 v[126:129], v[130:133], v[176:179], v[126:129]
	v_mfma_f32_16x16x32_bf16 v[122:125], v[138:141], v[176:179], v[122:125]
	v_mfma_f32_16x16x32_bf16 v[110:113], v[130:133], v[196:199], v[110:113]
	v_mfma_f32_16x16x32_bf16 v[106:109], v[138:141], v[196:199], v[106:109]
	v_mfma_f32_16x16x32_bf16 v[94:97], v[130:133], v[204:207], v[94:97]
	v_mfma_f32_16x16x32_bf16 v[90:93], v[138:141], v[204:207], v[90:93]
	v_mfma_f32_16x16x32_bf16 v[78:81], v[130:133], v[212:215], v[78:81]
	v_mfma_f32_16x16x32_bf16 v[74:77], v[138:141], v[212:215], v[74:77]
	v_mfma_f32_16x16x32_bf16 v[126:129], v[134:137], v[180:183], v[126:129]
	v_mfma_f32_16x16x32_bf16 v[122:125], v[152:155], v[180:183], v[122:125]
	v_mfma_f32_16x16x32_bf16 v[110:113], v[134:137], v[200:203], v[110:113]
	v_mfma_f32_16x16x32_bf16 v[106:109], v[152:155], v[200:203], v[106:109]
	v_mfma_f32_16x16x32_bf16 v[94:97], v[134:137], v[208:211], v[94:97]
	v_mfma_f32_16x16x32_bf16 v[90:93], v[152:155], v[208:211], v[90:93]
	v_mfma_f32_16x16x32_bf16 v[78:81], v[134:137], v[216:219], v[78:81]
	v_mfma_f32_16x16x32_bf16 v[74:77], v[152:155], v[216:219], v[74:77]
	v_mfma_f32_16x16x32_bf16 v[118:121], v[156:159], v[176:179], v[118:121]
	v_mfma_f32_16x16x32_bf16 v[114:117], v[168:171], v[176:179], v[114:117]
	v_mfma_f32_16x16x32_bf16 v[102:105], v[156:159], v[196:199], v[102:105]
	v_mfma_f32_16x16x32_bf16 v[98:101], v[168:171], v[196:199], v[98:101]
	v_mfma_f32_16x16x32_bf16 v[86:89], v[156:159], v[204:207], v[86:89]
	v_mfma_f32_16x16x32_bf16 v[82:85], v[168:171], v[204:207], v[82:85]
	v_mfma_f32_16x16x32_bf16 v[70:73], v[156:159], v[212:215], v[70:73]
	v_mfma_f32_16x16x32_bf16 v[66:69], v[168:171], v[212:215], v[66:69]
	v_mfma_f32_16x16x32_bf16 v[118:121], v[160:163], v[180:183], v[118:121]
	v_mfma_f32_16x16x32_bf16 v[114:117], v[172:175], v[180:183], v[114:117]
	v_mfma_f32_16x16x32_bf16 v[102:105], v[160:163], v[200:203], v[102:105]
	v_mfma_f32_16x16x32_bf16 v[98:101], v[172:175], v[200:203], v[98:101]
	v_mfma_f32_16x16x32_bf16 v[86:89], v[160:163], v[208:211], v[86:89]
	v_mfma_f32_16x16x32_bf16 v[82:85], v[172:175], v[208:211], v[82:85]
	v_mfma_f32_16x16x32_bf16 v[70:73], v[160:163], v[216:219], v[70:73]
	v_mfma_f32_16x16x32_bf16 v[66:69], v[172:175], v[216:219], v[66:69]
	s_setprio 0
	s_barrier
; #define PG8_STAGE(bufoff, gbase, voff) do { _Pragma("unroll") for (int _i = 0; _i < 2; ++_i) \
;         __builtin_amdgcn_global_load_lds((const unsigned*)((const char*)(gbase) + (voff)[_i]), (LAS unsigned*)(lds + (bufoff) + ldsw + _i * 8192), 16, 0, 0); } while (0)
; #define PG8_LDA(dst, b, h) do { _Pragma("unroll") for (int m = 0; m < 4; ++m) _Pragma("unroll") for (int k = 0; k < 2; ++k) dst[m][k] = *(const LAS bf16x8*)(lds + PG8_SA(b, h) + aoff + m * 2048 + k * 1024); } while (0)
; #define PG8_WAIT_V(n) asm volatile("s_waitcnt vmcnt(" #n ")" ::: "memory")
; #define PG8_BAR __builtin_amdgcn_s_barrier()
; template <class Epi, class Sched>
; __device__ __forceinline__ void gemm_phase(LAS unsigned char* lds, const Gemm g, const Sched& S, const Epi& E) {
;     ...
;         for (int t = 0; t < nt; t += 2) {
;             if constexpr (Epi::HOOKS) { if (cur.kind == 3 && (t == 4 || t == 12)) { int fr_ = fr, fq_ = fq; asm volatile("" : "+v"(fr_), "+v"(fq_)); E.hook(acc, cur, t == 4 ? 0 : 1, wr, wc, fr_, fq_); } }
;             const bool last = (t == nt - 2);
;             const char* a1 = cA + (size_t)(t + 1) * kstep;
;             const char* a2 = last ? nA : cA + (size_t)(t + 2) * kstep; const char* b2 = last ? nB : cB + (size_t)(t + 2) * kstep;
;             const char* a3 = a2 + kstep; const char* b3 = b2 + kstep;
;             PG8_LDB(B0, 0, 0); PG8_LDB(B1, 0, 1); PG8_SCHED; PG8_LDA(At, 0, 0); PG8_STAGE(PG8_SA(1, 1), a1 + hstepA, voffA);
;             PG8_WAIT_V(8); PG8_WAIT_L(0); PG8_BAR; PG8_MMA(0, 0, At, B0); PG8_MMA(0, 1, At, B1); PG8_BAR; PG8_SCHED;
;             PG8_LDA(At, 0, 1); PG8_STAGE(PG8_SB(0, 0), b2, voffB); PG8_STAGE(PG8_SB(0, 1), b2 + hstepB, voffB); PG8_STAGE(PG8_SA(0, 0), a2, voffA);
;             PG8_WAIT_V(8); PG8_WAIT_L(0); PG8_BAR; PG8_MMA(1, 0, At, B0); PG8_MMA(1, 1, At, B1); PG8_BAR; PG8_SCHED;
;             PG8_LDB(B0, 1, 0); PG8_LDB(B1, 1, 1); PG8_SCHED; PG8_LDA(At, 1, 0); PG8_STAGE(PG8_SA(0, 1), a2 + hstepA, voffA);
;             PG8_WAIT_V(8); PG8_WAIT_L(0); PG8_BAR; PG8_MMA(0, 0, At, B0); PG8_MMA(0, 1, At, B1); PG8_BAR; PG8_SCHED;
;             PG8_LDA(At, 1, 1); PG8_STAGE(PG8_SB(1, 0), b3, voffB); PG8_STAGE(PG8_SB(1, 1), b3 + hstepB, voffB); PG8_STAGE(PG8_SA(1, 0), a3, voffA);
;             PG8_WAIT_V(8); PG8_WAIT_L(0); PG8_BAR; PG8_MMA(1, 0, At, B0); PG8_MMA(1, 1, At, B1); PG8_BAR; PG8_SCHED;
;         }
	s_add_i32 s42, s52, s14
	v_lshl_add_u64 v[184:185], v[184:185], 0, s[26:27]
	s_mov_b32 m0, s42
	ds_read_b128 v[176:179], v167 offset:49152
	ds_read_b128 v[180:183], v167 offset:50176
	ds_read_b128 v[196:199], v167 offset:51200
	ds_read_b128 v[200:203], v167 offset:52224
	ds_read_b128 v[204:207], v167 offset:53248
	ds_read_b128 v[208:211], v167 offset:54272
	ds_read_b128 v[212:215], v167 offset:55296
	ds_read_b128 v[216:219], v167 offset:56320
	global_load_lds_dwordx4 v[184:185], off
	s_add_i32 m0, s42, 0x2000
	s_add_u32 s0, s0, 0x100080
	v_lshl_add_u64 v[184:185], v[220:221], 0, s[26:27]
	s_addc_u32 s1, s1, 0
	s_add_i32 s42, s53, s14
	global_load_lds_dwordx4 v[184:185], off
	v_lshl_add_u64 v[184:185], s[0:1], 0, v[0:1]
	s_mov_b32 m0, s42
	s_nop 0
	global_load_lds_dwordx4 v[184:185], off
	v_lshl_add_u64 v[184:185], s[0:1], 0, v[146:147]
	s_add_i32 m0, s42, 0x2000
	s_nop 0
	global_load_lds_dwordx4 v[184:185], off
	v_lshl_add_u64 v[184:185], v[232:233], 0, s[26:27]
	s_mov_b32 m0, s67
	s_nop 0
	global_load_lds_dwordx4 v[184:185], off
	v_lshl_add_u64 v[184:185], v[234:235], 0, s[26:27]
	s_mov_b32 m0, s69
	s_nop 0
	global_load_lds_dwordx4 v[184:185], off
	s_waitcnt vmcnt(8)
	s_waitcnt lgkmcnt(0)
	s_barrier
	s_setprio 1
	s_waitcnt lgkmcnt(0)
	v_mfma_f32_16x16x32_bf16 v[62:65], v[130:133], v[176:179], v[62:65]
	v_mfma_f32_16x16x32_bf16 v[58:61], v[138:141], v[176:179], v[58:61]
	v_mfma_f32_16x16x32_bf16 v[46:49], v[130:133], v[196:199], v[46:49]
	v_mfma_f32_16x16x32_bf16 v[42:45], v[138:141], v[196:199], v[42:45]
	v_mfma_f32_16x16x32_bf16 v[30:33], v[130:133], v[204:207], v[30:33]
	v_mfma_f32_16x16x32_bf16 v[26:29], v[138:141], v[204:207], v[26:29]
	v_mfma_f32_16x16x32_bf16 v[14:17], v[130:133], v[212:215], v[14:17]
	v_mfma_f32_16x16x32_bf16 v[10:13], v[138:141], v[212:215], v[10:13]
	v_mfma_f32_16x16x32_bf16 v[62:65], v[134:137], v[180:183], v[62:65]
	v_mfma_f32_16x16x32_bf16 v[58:61], v[152:155], v[180:183], v[58:61]
	v_mfma_f32_16x16x32_bf16 v[46:49], v[134:137], v[200:203], v[46:49]
	v_mfma_f32_16x16x32_bf16 v[42:45], v[152:155], v[200:203], v[42:45]
	v_mfma_f32_16x16x32_bf16 v[30:33], v[134:137], v[208:211], v[30:33]
	v_mfma_f32_16x16x32_bf16 v[26:29], v[152:155], v[208:211], v[26:29]
	v_mfma_f32_16x16x32_bf16 v[14:17], v[134:137], v[216:219], v[14:17]
	v_mfma_f32_16x16x32_bf16 v[10:13], v[152:155], v[216:219], v[10:13]
	v_mfma_f32_16x16x32_bf16 v[54:57], v[156:159], v[176:179], v[54:57]
	v_mfma_f32_16x16x32_bf16 v[50:53], v[168:171], v[176:179], v[50:53]
	v_mfma_f32_16x16x32_bf16 v[38:41], v[156:159], v[196:199], v[38:41]
	v_mfma_f32_16x16x32_bf16 v[34:37], v[168:171], v[196:199], v[34:37]
	v_mfma_f32_16x16x32_bf16 v[22:25], v[156:159], v[204:207], v[22:25]
	v_mfma_f32_16x16x32_bf16 v[18:21], v[168:171], v[204:207], v[18:21]
	v_mfma_f32_16x16x32_bf16 v[6:9], v[156:159], v[212:215], v[6:9]
	v_mfma_f32_16x16x32_bf16 v[2:5], v[168:171], v[212:215], v[2:5]
	v_mfma_f32_16x16x32_bf16 v[54:57], v[160:163], v[180:183], v[54:57]
	v_mfma_f32_16x16x32_bf16 v[50:53], v[172:175], v[180:183], v[50:53]
	v_mfma_f32_16x16x32_bf16 v[38:41], v[160:163], v[200:203], v[38:41]
	v_mfma_f32_16x16x32_bf16 v[34:37], v[172:175], v[200:203], v[34:37]
	v_mfma_f32_16x16x32_bf16 v[22:25], v[160:163], v[208:211], v[22:25]
	v_mfma_f32_16x16x32_bf16 v[18:21], v[172:175], v[208:211], v[18:21]
	v_mfma_f32_16x16x32_bf16 v[6:9], v[160:163], v[216:219], v[6:9]
	v_mfma_f32_16x16x32_bf16 v[2:5], v[172:175], v[216:219], v[2:5]
	s_setprio 0
	s_add_u32 s93, s93, 0x100
	s_addc_u32 s94, s94, 0
	s_add_u32 s20, s20, 0x100
	s_addc_u32 s21, s21, 0
	s_cmp_ge_i32 s68, s46
	s_mov_b32 s0, s68
	s_cbranch_scc1 .Lrot_exit_1
	s_add_i32 s68, s0, 2
	s_add_u32 s1, s20, 0xfff00080
	s_addc_u32 s42, s21, -1
	s_add_i32 s52, 0, 0x10000
	s_cmp_eq_u32 s72, s0
	s_cselect_b32 s43, s41, s42
	s_cselect_b32 s42, s48, s1
	s_cselect_b32 s1, s85, s94
	s_cselect_b32 s0, s87, s93
	s_add_i32 s53, 0, 0x14000
	s_branch .Lrot_head_1
.Lrot_exit_1:
	s_barrier
	v_readlane_b32 s94, v255, 0
	v_readlane_b32 s95, v255, 1

; template <class Epi, class Sched>
; __device__ __forceinline__ void gemm_phase(LAS unsigned char* lds, const Gemm g, const Sched& S, const Epi& E) {
;     ...
;             const bool last = (t == nt - 2);
;             const char* a1 = cA + (size_t)(t + 1) * kstep;
;             const char* a2 = last ? nA : cA + (size_t)(t + 2) * kstep; const char* b2 = last ? nB : cB + (size_t)(t + 2) * kstep;
;             const char* a3 = a2 + kstep; const char* b3 = b2 + kstep;
.LBB0_209:
	s_add_i32 s68, s0, 2
	s_add_u32 s1, s20, 0xfffc0080
	s_addc_u32 s52, s21, -1
	s_add_i32 s53, 0, 0x10000
	s_cmp_eq_u32 s72, s0
	s_cselect_b32 s85, s43, s52
	s_cselect_b32 s84, s59, s1
	s_cselect_b32 s1, s86, s89
	s_cselect_b32 s0, s87, s88
	s_add_i32 s52, 0, 0x14000
	s_branch .Lrot_body_2

; #define PG8_STAGE(bufoff, gbase, voff) do { _Pragma("unroll") for (int _i = 0; _i < 2; ++_i) \
;         __builtin_amdgcn_global_load_lds((const unsigned*)((const char*)(gbase) + (voff)[_i]), (LAS unsigned*)(lds + (bufoff) + ldsw + _i * 8192), 16, 0, 0); } while (0)
; #define PG8_LDA(dst, b, h) do { _Pragma("unroll") for (int m = 0; m < 4; ++m) _Pragma("unroll") for (int k = 0; k < 2; ++k) dst[m][k] = *(const LAS bf16x8*)(lds + PG8_SA(b, h) + aoff + m * 2048 + k * 1024); } while (0)
; #define PG8_LDB(dst, b, h) do { _Pragma("unroll") for (int n = 0; n < 2; ++n) _Pragma("unroll") for (int k = 0; k < 2; ++k) dst[n][k] = *(const LAS bf16x8*)(lds + PG8_SB(b, h) + boff + n * 2048 + k * 1024); } while (0)
; #define PG8_MMA(ai, bj, At, Bt) do { __builtin_amdgcn_s_setprio(1); _Pragma("unroll") for (int m = 0; m < 4; ++m) _Pragma("unroll") for (int n = 0; n < 2; ++n) _Pragma("unroll") for (int k = 0; k < 2; ++k) \
;         acc[ai][bj][m][n] = __builtin_amdgcn_mfma_f32_16x16x32_bf16(Bt[n][k], At[m][k], acc[ai][bj][m][n], 0, 0, 0); __builtin_amdgcn_s_setprio(0); } while (0)
; #define PG8_WAIT_V(n) asm volatile("s_waitcnt vmcnt(" #n ")" ::: "memory")
; #define PG8_WAIT_L(n) asm volatile("s_waitcnt lgkmcnt(" #n ")" ::: "memory")
; #define PG8_BAR __builtin_amdgcn_s_barrier()
; #define PG8_SCHED __builtin_amdgcn_sched_barrier(0)
; template <class Epi, class Sched>
; __device__ __forceinline__ void gemm_phase(LAS unsigned char* lds, const Gemm g, const Sched& S, const Epi& E) {
;     ...
;             PG8_LDB(B0, 0, 0); PG8_LDB(B1, 0, 1); PG8_SCHED; PG8_LDA(At, 0, 0); PG8_STAGE(PG8_SA(1, 1), a1 + hstepA, voffA);
;             PG8_WAIT_V(8); PG8_WAIT_L(0); PG8_BAR; PG8_MMA(0, 0, At, B0); PG8_MMA(0, 1, At, B1); PG8_BAR; PG8_SCHED;
;             PG8_LDA(At, 0, 1); PG8_STAGE(PG8_SB(0, 0), b2, voffB); PG8_STAGE(PG8_SB(0, 1), b2 + hstepB, voffB); PG8_STAGE(PG8_SA(0, 0), a2, voffA);
.Lrot_body_2:
	v_add_u32_e32 v142, s53, v177
	v_add_u32_e32 v168, s52, v177
	ds_read_b128 v[130:133], v142
	ds_read_b128 v[134:137], v142 offset:1024
	ds_read_b128 v[138:141], v142 offset:2048
	ds_read_b128 v[142:145], v142 offset:3072
	ds_read_b128 v[156:159], v168
	ds_read_b128 v[160:163], v168 offset:1024
	ds_read_b128 v[164:167], v168 offset:2048
	ds_read_b128 v[180:183], v168 offset:3072
	v_lshl_add_u64 v[168:169], s[20:21], 0, v[154:155]
	s_add_i32 m0, s19, 0xc000
	ds_read_b128 v[196:199], v179
	ds_read_b128 v[200:203], v179 offset:1024
	ds_read_b128 v[204:207], v179 offset:2048
	ds_read_b128 v[208:211], v179 offset:3072
	ds_read_b128 v[212:215], v179 offset:4096
	ds_read_b128 v[216:219], v179 offset:5120
	ds_read_b128 v[232:235], v179 offset:6144
	ds_read_b128 v[248:251], v179 offset:7168
	global_load_lds_dwordx4 v[168:169], off
	v_lshl_add_u64 v[168:169], s[20:21], 0, v[152:153]
	s_add_i32 m0, s19, 0xe000
	s_nop 0
	global_load_lds_dwordx4 v[168:169], off
	s_waitcnt vmcnt(8)
	s_waitcnt lgkmcnt(0)
	s_barrier
	s_setprio 1
	s_waitcnt lgkmcnt(0)
	v_mfma_f32_16x16x32_bf16 v[126:129], v[130:133], v[196:199], v[126:129]
	v_mfma_f32_16x16x32_bf16 v[122:125], v[138:141], v[196:199], v[122:125]
	v_mfma_f32_16x16x32_bf16 v[110:113], v[130:133], v[204:207], v[110:113]
	v_mfma_f32_16x16x32_bf16 v[106:109], v[138:141], v[204:207], v[106:109]
	v_mfma_f32_16x16x32_bf16 v[94:97], v[130:133], v[212:215], v[94:97]
	v_mfma_f32_16x16x32_bf16 v[90:93], v[138:141], v[212:215], v[90:93]
	v_mfma_f32_16x16x32_bf16 v[78:81], v[130:133], v[232:235], v[78:81]
	v_mfma_f32_16x16x32_bf16 v[74:77], v[138:141], v[232:235], v[74:77]
	v_mfma_f32_16x16x32_bf16 v[126:129], v[134:137], v[200:203], v[126:129]
	v_mfma_f32_16x16x32_bf16 v[122:125], v[142:145], v[200:203], v[122:125]
	v_mfma_f32_16x16x32_bf16 v[110:113], v[134:137], v[208:211], v[110:113]
	v_mfma_f32_16x16x32_bf16 v[106:109], v[142:145], v[208:211], v[106:109]
	v_mfma_f32_16x16x32_bf16 v[94:97], v[134:137], v[216:219], v[94:97]
	v_mfma_f32_16x16x32_bf16 v[90:93], v[142:145], v[216:219], v[90:93]
	v_mfma_f32_16x16x32_bf16 v[78:81], v[134:137], v[248:251], v[78:81]
	v_mfma_f32_16x16x32_bf16 v[74:77], v[142:145], v[248:251], v[74:77]
	v_mfma_f32_16x16x32_bf16 v[118:121], v[156:159], v[196:199], v[118:121]
	v_mfma_f32_16x16x32_bf16 v[114:117], v[164:167], v[196:199], v[114:117]
	v_mfma_f32_16x16x32_bf16 v[102:105], v[156:159], v[204:207], v[102:105]
	v_mfma_f32_16x16x32_bf16 v[98:101], v[164:167], v[204:207], v[98:101]
	v_mfma_f32_16x16x32_bf16 v[86:89], v[156:159], v[212:215], v[86:89]
	v_mfma_f32_16x16x32_bf16 v[82:85], v[164:167], v[212:215], v[82:85]
	v_mfma_f32_16x16x32_bf16 v[70:73], v[156:159], v[232:235], v[70:73]
	v_mfma_f32_16x16x32_bf16 v[66:69], v[164:167], v[232:235], v[66:69]
	v_mfma_f32_16x16x32_bf16 v[118:121], v[160:163], v[200:203], v[118:121]
	v_mfma_f32_16x16x32_bf16 v[114:117], v[180:183], v[200:203], v[114:117]
	v_mfma_f32_16x16x32_bf16 v[102:105], v[160:163], v[208:211], v[102:105]
	v_mfma_f32_16x16x32_bf16 v[98:101], v[180:183], v[208:211], v[98:101]
	v_mfma_f32_16x16x32_bf16 v[86:89], v[160:163], v[216:219], v[86:89]
	v_mfma_f32_16x16x32_bf16 v[82:85], v[180:183], v[216:219], v[82:85]
	v_mfma_f32_16x16x32_bf16 v[70:73], v[160:163], v[248:251], v[70:73]
	v_mfma_f32_16x16x32_bf16 v[66:69], v[180:183], v[248:251], v[66:69]
	s_setprio 0
	s_barrier
	s_add_i32 s53, s53, s17
	v_lshl_add_u64 v[168:169], s[0:1], 0, v[0:1]
	s_mov_b32 m0, s53
	ds_read_b128 v[196:199], v179 offset:16384
	ds_read_b128 v[200:203], v179 offset:17408
	ds_read_b128 v[204:207], v179 offset:18432
	ds_read_b128 v[208:211], v179 offset:19456
	ds_read_b128 v[212:215], v179 offset:20480
	ds_read_b128 v[216:219], v179 offset:21504
	ds_read_b128 v[232:235], v179 offset:22528
	ds_read_b128 v[248:251], v179 offset:23552
	global_load_lds_dwordx4 v[168:169], off
	s_add_i32 m0, s53, 0x2000
	s_add_u32 s90, s0, 0x40000
	v_lshl_add_u64 v[174:175], s[0:1], 0, v[150:151]
	s_addc_u32 s91, s1, 0
	s_add_i32 s52, s52, s17
	global_load_lds_dwordx4 v[174:175], off
	v_lshl_add_u64 v[184:185], s[90:91], 0, v[0:1]
	s_mov_b32 m0, s52
	v_lshl_add_u64 v[220:221], s[84:85], 0, v[148:149]
	global_load_lds_dwordx4 v[184:185], off
	v_lshl_add_u64 v[184:185], s[90:91], 0, v[150:151]
	s_add_i32 m0, s52, 0x2000
	s_nop 0
	global_load_lds_dwordx4 v[184:185], off
	v_lshl_add_u64 v[184:185], s[84:85], 0, v[146:147]
	s_mov_b32 m0, s19
	s_nop 0
	global_load_lds_dwordx4 v[184:185], off
	s_mov_b32 m0, s44
	s_nop 0
	global_load_lds_dwordx4 v[220:221], off
	s_waitcnt vmcnt(8)
	s_waitcnt lgkmcnt(0)
	s_barrier
; #define PG8_STAGE(bufoff, gbase, voff) do { _Pragma("unroll") for (int _i = 0; _i < 2; ++_i) \
;         __builtin_amdgcn_global_load_lds((const unsigned*)((const char*)(gbase) + (voff)[_i]), (LAS unsigned*)(lds + (bufoff) + ldsw + _i * 8192), 16, 0, 0); } while (0)
; #define PG8_LDA(dst, b, h) do { _Pragma("unroll") for (int m = 0; m < 4; ++m) _Pragma("unroll") for (int k = 0; k < 2; ++k) dst[m][k] = *(const LAS bf16x8*)(lds + PG8_SA(b, h) + aoff + m * 2048 + k * 1024); } while (0)
; #define PG8_LDB(dst, b, h) do { _Pragma("unroll") for (int n = 0; n < 2; ++n) _Pragma("unroll") for (int k = 0; k < 2; ++k) dst[n][k] = *(const LAS bf16x8*)(lds + PG8_SB(b, h) + boff + n * 2048 + k * 1024); } while (0)
; #define PG8_MMA(ai, bj, At, Bt) do { __builtin_amdgcn_s_setprio(1); _Pragma("unroll") for (int m = 0; m < 4; ++m) _Pragma("unroll") for (int n = 0; n < 2; ++n) _Pragma("unroll") for (int k = 0; k < 2; ++k) \
;         acc[ai][bj][m][n] = __builtin_amdgcn_mfma_f32_16x16x32_bf16(Bt[n][k], At[m][k], acc[ai][bj][m][n], 0, 0, 0); __builtin_amdgcn_s_setprio(0); } while (0)
; #define PG8_WAIT_V(n) asm volatile("s_waitcnt vmcnt(" #n ")" ::: "memory")
; #define PG8_WAIT_L(n) asm volatile("s_waitcnt lgkmcnt(" #n ")" ::: "memory")
; #define PG8_BAR __builtin_amdgcn_s_barrier()
; #define PG8_SCHED __builtin_amdgcn_sched_barrier(0)
; template <class Epi, class Sched>
; __device__ __forceinline__ void gemm_phase(LAS unsigned char* lds, const Gemm g, const Sched& S, const Epi& E) {
;     ...
;             PG8_WAIT_V(8); PG8_WAIT_L(0); PG8_BAR; PG8_MMA(1, 0, At, B0); PG8_MMA(1, 1, At, B1); PG8_BAR; PG8_SCHED;
;             PG8_LDB(B0, 1, 0); PG8_LDB(B1, 1, 1); PG8_SCHED; PG8_LDA(At, 1, 0); PG8_STAGE(PG8_SA(0, 1), a2 + hstepA, voffA);
;             PG8_WAIT_V(8); PG8_WAIT_L(0); PG8_BAR; PG8_MMA(0, 0, At, B0); PG8_MMA(0, 1, At, B1); PG8_BAR; PG8_SCHED;
	s_setprio 1
	s_waitcnt lgkmcnt(0)
	v_mfma_f32_16x16x32_bf16 v[62:65], v[130:133], v[196:199], v[62:65]
	v_mfma_f32_16x16x32_bf16 v[58:61], v[138:141], v[196:199], v[58:61]
	v_mfma_f32_16x16x32_bf16 v[46:49], v[130:133], v[204:207], v[46:49]
	v_mfma_f32_16x16x32_bf16 v[42:45], v[138:141], v[204:207], v[42:45]
	v_mfma_f32_16x16x32_bf16 v[30:33], v[130:133], v[212:215], v[30:33]
	v_mfma_f32_16x16x32_bf16 v[26:29], v[138:141], v[212:215], v[26:29]
	v_mfma_f32_16x16x32_bf16 v[14:17], v[130:133], v[232:235], v[14:17]
	v_mfma_f32_16x16x32_bf16 v[10:13], v[138:141], v[232:235], v[10:13]
	v_mfma_f32_16x16x32_bf16 v[62:65], v[134:137], v[200:203], v[62:65]
	v_mfma_f32_16x16x32_bf16 v[58:61], v[142:145], v[200:203], v[58:61]
	v_mfma_f32_16x16x32_bf16 v[46:49], v[134:137], v[208:211], v[46:49]
	v_mfma_f32_16x16x32_bf16 v[42:45], v[142:145], v[208:211], v[42:45]
	v_mfma_f32_16x16x32_bf16 v[30:33], v[134:137], v[216:219], v[30:33]
	v_mfma_f32_16x16x32_bf16 v[26:29], v[142:145], v[216:219], v[26:29]
	v_mfma_f32_16x16x32_bf16 v[14:17], v[134:137], v[248:251], v[14:17]
	v_mfma_f32_16x16x32_bf16 v[10:13], v[142:145], v[248:251], v[10:13]
	v_mfma_f32_16x16x32_bf16 v[54:57], v[156:159], v[196:199], v[54:57]
	v_mfma_f32_16x16x32_bf16 v[50:53], v[164:167], v[196:199], v[50:53]
	v_mfma_f32_16x16x32_bf16 v[38:41], v[156:159], v[204:207], v[38:41]
	v_mfma_f32_16x16x32_bf16 v[34:37], v[164:167], v[204:207], v[34:37]
	v_mfma_f32_16x16x32_bf16 v[22:25], v[156:159], v[212:215], v[22:25]
	v_mfma_f32_16x16x32_bf16 v[18:21], v[164:167], v[212:215], v[18:21]
	v_mfma_f32_16x16x32_bf16 v[6:9], v[156:159], v[232:235], v[6:9]
	v_mfma_f32_16x16x32_bf16 v[2:5], v[164:167], v[232:235], v[2:5]
	v_mfma_f32_16x16x32_bf16 v[54:57], v[160:163], v[200:203], v[54:57]
	v_mfma_f32_16x16x32_bf16 v[50:53], v[180:183], v[200:203], v[50:53]
	v_mfma_f32_16x16x32_bf16 v[38:41], v[160:163], v[208:211], v[38:41]
	v_mfma_f32_16x16x32_bf16 v[34:37], v[180:183], v[208:211], v[34:37]
	v_mfma_f32_16x16x32_bf16 v[22:25], v[160:163], v[216:219], v[22:25]
	v_mfma_f32_16x16x32_bf16 v[18:21], v[180:183], v[216:219], v[18:21]
	v_mfma_f32_16x16x32_bf16 v[6:9], v[160:163], v[248:251], v[6:9]
	v_mfma_f32_16x16x32_bf16 v[2:5], v[180:183], v[248:251], v[2:5]
	s_setprio 0
	s_barrier
	s_add_i32 s52, 0, 0x18000
	s_add_i32 s53, 0, 0x1c000
	v_add_u32_e32 v142, s52, v177
	v_add_u32_e32 v170, s53, v177
	ds_read_b128 v[130:133], v142
	ds_read_b128 v[134:137], v142 offset:1024
	ds_read_b128 v[138:141], v142 offset:2048
	ds_read_b128 v[142:145], v142 offset:3072
	ds_read_b128 v[156:159], v170
	ds_read_b128 v[160:163], v170 offset:1024
	ds_read_b128 v[164:167], v170 offset:2048
	ds_read_b128 v[180:183], v170 offset:3072
	s_add_u32 s84, s84, 0x40000
	s_addc_u32 s85, s85, 0
	s_mov_b32 m0, s46
	v_lshl_add_u64 v[236:237], s[84:85], 0, v[146:147]
	ds_read_b128 v[196:199], v179 offset:32768
	ds_read_b128 v[200:203], v179 offset:33792
	ds_read_b128 v[204:207], v179 offset:34816
	ds_read_b128 v[208:211], v179 offset:35840
	ds_read_b128 v[212:215], v179 offset:36864
	ds_read_b128 v[216:219], v179 offset:37888
	ds_read_b128 v[232:235], v179 offset:38912
	ds_read_b128 v[248:251], v179 offset:39936
	global_load_lds_dwordx4 v[236:237], off
	v_lshl_add_u64 v[236:237], s[84:85], 0, v[148:149]
	s_mov_b32 m0, s47
	s_nop 0
	global_load_lds_dwordx4 v[236:237], off
	s_waitcnt vmcnt(8)
	s_waitcnt lgkmcnt(0)
	s_barrier
	s_setprio 1
	s_waitcnt lgkmcnt(0)
	v_mfma_f32_16x16x32_bf16 v[126:129], v[130:133], v[196:199], v[126:129]
	v_mfma_f32_16x16x32_bf16 v[122:125], v[138:141], v[196:199], v[122:125]
	v_mfma_f32_16x16x32_bf16 v[110:113], v[130:133], v[204:207], v[110:113]
	v_mfma_f32_16x16x32_bf16 v[106:109], v[138:141], v[204:207], v[106:109]
	v_mfma_f32_16x16x32_bf16 v[94:97], v[130:133], v[212:215], v[94:97]
	v_mfma_f32_16x16x32_bf16 v[90:93], v[138:141], v[212:215], v[90:93]
	v_mfma_f32_16x16x32_bf16 v[78:81], v[130:133], v[232:235], v[78:81]
	v_mfma_f32_16x16x32_bf16 v[74:77], v[138:141], v[232:235], v[74:77]
	v_mfma_f32_16x16x32_bf16 v[126:129], v[134:137], v[200:203], v[126:129]
	v_mfma_f32_16x16x32_bf16 v[122:125], v[142:145], v[200:203], v[122:125]
	v_mfma_f32_16x16x32_bf16 v[110:113], v[134:137], v[208:211], v[110:113]
	v_mfma_f32_16x16x32_bf16 v[106:109], v[142:145], v[208:211], v[106:109]
	v_mfma_f32_16x16x32_bf16 v[94:97], v[134:137], v[216:219], v[94:97]
	v_mfma_f32_16x16x32_bf16 v[90:93], v[142:145], v[216:219], v[90:93]
	v_mfma_f32_16x16x32_bf16 v[78:81], v[134:137], v[248:251], v[78:81]
	v_mfma_f32_16x16x32_bf16 v[74:77], v[142:145], v[248:251], v[74:77]
	v_mfma_f32_16x16x32_bf16 v[118:121], v[156:159], v[196:199], v[118:121]
	v_mfma_f32_16x16x32_bf16 v[114:117], v[164:167], v[196:199], v[114:117]
	v_mfma_f32_16x16x32_bf16 v[102:105], v[156:159], v[204:207], v[102:105]
	v_mfma_f32_16x16x32_bf16 v[98:101], v[164:167], v[204:207], v[98:101]
	v_mfma_f32_16x16x32_bf16 v[86:89], v[156:159], v[212:215], v[86:89]
	v_mfma_f32_16x16x32_bf16 v[82:85], v[164:167], v[212:215], v[82:85]
	v_mfma_f32_16x16x32_bf16 v[70:73], v[156:159], v[232:235], v[70:73]
	v_mfma_f32_16x16x32_bf16 v[66:69], v[164:167], v[232:235], v[66:69]
	v_mfma_f32_16x16x32_bf16 v[118:121], v[160:163], v[200:203], v[118:121]
	v_mfma_f32_16x16x32_bf16 v[114:117], v[180:183], v[200:203], v[114:117]
	v_mfma_f32_16x16x32_bf16 v[102:105], v[160:163], v[208:211], v[102:105]
	v_mfma_f32_16x16x32_bf16 v[98:101], v[180:183], v[208:211], v[98:101]
	v_mfma_f32_16x16x32_bf16 v[86:89], v[160:163], v[216:219], v[86:89]
	v_mfma_f32_16x16x32_bf16 v[82:85], v[180:183], v[216:219], v[82:85]
	v_mfma_f32_16x16x32_bf16 v[70:73], v[160:163], v[248:251], v[70:73]
	v_mfma_f32_16x16x32_bf16 v[66:69], v[180:183], v[248:251], v[66:69]
	s_setprio 0
	s_barrier
; #define PG8_STAGE(bufoff, gbase, voff) do { _Pragma("unroll") for (int _i = 0; _i < 2; ++_i) \
;         __builtin_amdgcn_global_load_lds((const unsigned*)((const char*)(gbase) + (voff)[_i]), (LAS unsigned*)(lds + (bufoff) + ldsw + _i * 8192), 16, 0, 0); } while (0)
; #define PG8_LDA(dst, b, h) do { _Pragma("unroll") for (int m = 0; m < 4; ++m) _Pragma("unroll") for (int k = 0; k < 2; ++k) dst[m][k] = *(const LAS bf16x8*)(lds + PG8_SA(b, h) + aoff + m * 2048 + k * 1024); } while (0)
; #define PG8_LDB(dst, b, h) do { _Pragma("unroll") for (int n = 0; n < 2; ++n) _Pragma("unroll") for (int k = 0; k < 2; ++k) dst[n][k] = *(const LAS bf16x8*)(lds + PG8_SB(b, h) + boff + n * 2048 + k * 1024); } while (0)
; #define PG8_WAIT_V(n) asm volatile("s_waitcnt vmcnt(" #n ")" ::: "memory")
; #define PG8_WAIT_L(n) asm volatile("s_waitcnt lgkmcnt(" #n ")" ::: "memory")
; template <class Epi, class Sched>
; __device__ __forceinline__ void gemm_phase(LAS unsigned char* lds, const Gemm g, const Sched& S, const Epi& E) {
;     ...
;             const bool last = (t == nt - 2);
;             const char* a1 = cA + (size_t)(t + 1) * kstep;
;             const char* a2 = last ? nA : cA + (size_t)(t + 2) * kstep; const char* b2 = last ? nB : cB + (size_t)(t + 2) * kstep;
;             const char* a3 = a2 + kstep; const char* b3 = b2 + kstep;
;             PG8_LDB(B0, 0, 0); PG8_LDB(B1, 0, 1); PG8_SCHED; PG8_LDA(At, 0, 0); PG8_STAGE(PG8_SA(1, 1), a1 + hstepA, voffA);
;             PG8_WAIT_V(8); PG8_WAIT_L(0); PG8_BAR; PG8_MMA(0, 0, At, B0); PG8_MMA(0, 1, At, B1); PG8_BAR; PG8_SCHED;
;             PG8_LDA(At, 0, 1); PG8_STAGE(PG8_SB(0, 0), b2, voffB); PG8_STAGE(PG8_SB(0, 1), b2 + hstepB, voffB); PG8_STAGE(PG8_SA(0, 0), a2, voffA);
;             PG8_WAIT_V(8); PG8_WAIT_L(0); PG8_BAR; PG8_MMA(1, 0, At, B0); PG8_MMA(1, 1, At, B1); PG8_BAR; PG8_SCHED;
;             PG8_LDB(B0, 1, 0); PG8_LDB(B1, 1, 1); PG8_SCHED; PG8_LDA(At, 1, 0); PG8_STAGE(PG8_SA(0, 1), a2 + hstepA, voffA);
;             PG8_WAIT_V(8); PG8_WAIT_L(0); PG8_BAR; PG8_MMA(0, 0, At, B0); PG8_MMA(0, 1, At, B1); PG8_BAR; PG8_SCHED;
;             PG8_LDA(At, 1, 1); PG8_STAGE(PG8_SB(1, 0), b3, voffB); PG8_STAGE(PG8_SB(1, 1), b3 + hstepB, voffB); PG8_STAGE(PG8_SA(1, 0), a3, voffA);
;             PG8_WAIT_V(8); PG8_WAIT_L(0); PG8_BAR; PG8_MMA(1, 0, At, B0); PG8_MMA(1, 1, At, B1); PG8_BAR; PG8_SCHED;
;         }
	s_add_i32 s52, s52, s17
	v_lshl_add_u64 v[168:169], v[168:169], 0, s[26:27]
	s_mov_b32 m0, s52
	ds_read_b128 v[196:199], v179 offset:49152
	ds_read_b128 v[200:203], v179 offset:50176
	ds_read_b128 v[204:207], v179 offset:51200
	ds_read_b128 v[208:211], v179 offset:52224
	ds_read_b128 v[212:215], v179 offset:53248
	ds_read_b128 v[216:219], v179 offset:54272
	ds_read_b128 v[232:235], v179 offset:55296
	ds_read_b128 v[248:251], v179 offset:56320
	global_load_lds_dwordx4 v[168:169], off
	s_add_i32 m0, s52, 0x2000
	s_add_u32 s0, s0, 0x40080
	v_lshl_add_u64 v[168:169], v[174:175], 0, s[26:27]
	s_addc_u32 s1, s1, 0
	s_add_i32 s52, s53, s17
	global_load_lds_dwordx4 v[168:169], off
	v_lshl_add_u64 v[168:169], s[0:1], 0, v[0:1]
	s_mov_b32 m0, s52
	s_nop 0
	global_load_lds_dwordx4 v[168:169], off
	v_lshl_add_u64 v[168:169], s[0:1], 0, v[150:151]
	s_add_i32 m0, s52, 0x2000
	s_nop 0
	global_load_lds_dwordx4 v[168:169], off
	v_lshl_add_u64 v[168:169], v[184:185], 0, s[26:27]
	s_mov_b32 m0, s69
	s_nop 0
	global_load_lds_dwordx4 v[168:169], off
	v_lshl_add_u64 v[168:169], v[220:221], 0, s[26:27]
	s_mov_b32 m0, s71
	s_nop 0
	global_load_lds_dwordx4 v[168:169], off
	s_waitcnt vmcnt(8)
	s_waitcnt lgkmcnt(0)
	s_barrier
	s_setprio 1
	s_waitcnt lgkmcnt(0)
	v_mfma_f32_16x16x32_bf16 v[62:65], v[130:133], v[196:199], v[62:65]
	v_mfma_f32_16x16x32_bf16 v[58:61], v[138:141], v[196:199], v[58:61]
	v_mfma_f32_16x16x32_bf16 v[46:49], v[130:133], v[204:207], v[46:49]
	v_mfma_f32_16x16x32_bf16 v[42:45], v[138:141], v[204:207], v[42:45]
	v_mfma_f32_16x16x32_bf16 v[30:33], v[130:133], v[212:215], v[30:33]
	v_mfma_f32_16x16x32_bf16 v[26:29], v[138:141], v[212:215], v[26:29]
	v_mfma_f32_16x16x32_bf16 v[14:17], v[130:133], v[232:235], v[14:17]
	v_mfma_f32_16x16x32_bf16 v[10:13], v[138:141], v[232:235], v[10:13]
	v_mfma_f32_16x16x32_bf16 v[62:65], v[134:137], v[200:203], v[62:65]
	v_mfma_f32_16x16x32_bf16 v[58:61], v[142:145], v[200:203], v[58:61]
	v_mfma_f32_16x16x32_bf16 v[46:49], v[134:137], v[208:211], v[46:49]
	v_mfma_f32_16x16x32_bf16 v[42:45], v[142:145], v[208:211], v[42:45]
	v_mfma_f32_16x16x32_bf16 v[30:33], v[134:137], v[216:219], v[30:33]
	v_mfma_f32_16x16x32_bf16 v[26:29], v[142:145], v[216:219], v[26:29]
	v_mfma_f32_16x16x32_bf16 v[14:17], v[134:137], v[248:251], v[14:17]
	v_mfma_f32_16x16x32_bf16 v[10:13], v[142:145], v[248:251], v[10:13]
	v_mfma_f32_16x16x32_bf16 v[54:57], v[156:159], v[196:199], v[54:57]
	v_mfma_f32_16x16x32_bf16 v[50:53], v[164:167], v[196:199], v[50:53]
	v_mfma_f32_16x16x32_bf16 v[38:41], v[156:159], v[204:207], v[38:41]
	v_mfma_f32_16x16x32_bf16 v[34:37], v[164:167], v[204:207], v[34:37]
	v_mfma_f32_16x16x32_bf16 v[22:25], v[156:159], v[212:215], v[22:25]
	v_mfma_f32_16x16x32_bf16 v[18:21], v[164:167], v[212:215], v[18:21]
	v_mfma_f32_16x16x32_bf16 v[6:9], v[156:159], v[232:235], v[6:9]
	v_mfma_f32_16x16x32_bf16 v[2:5], v[164:167], v[232:235], v[2:5]
	v_mfma_f32_16x16x32_bf16 v[54:57], v[160:163], v[200:203], v[54:57]
	v_mfma_f32_16x16x32_bf16 v[50:53], v[180:183], v[200:203], v[50:53]
	v_mfma_f32_16x16x32_bf16 v[38:41], v[160:163], v[208:211], v[38:41]
	v_mfma_f32_16x16x32_bf16 v[34:37], v[180:183], v[208:211], v[34:37]
	v_mfma_f32_16x16x32_bf16 v[22:25], v[160:163], v[216:219], v[22:25]
	v_mfma_f32_16x16x32_bf16 v[18:21], v[180:183], v[216:219], v[18:21]
	v_mfma_f32_16x16x32_bf16 v[6:9], v[160:163], v[248:251], v[6:9]
	v_mfma_f32_16x16x32_bf16 v[2:5], v[180:183], v[248:251], v[2:5]
	s_setprio 0
	s_add_u32 s88, s88, 0x100
	s_addc_u32 s89, s89, 0
	s_add_u32 s20, s20, 0x100
	s_addc_u32 s21, s21, 0
	s_cmp_ge_i32 s68, s48
	s_mov_b32 s0, s68
	s_cbranch_scc1 .Lrot_exit_2
	s_add_i32 s68, s0, 2
	s_add_u32 s1, s20, 0xfffc0080
	s_addc_u32 s52, s21, -1
	s_add_i32 s53, 0, 0x10000
	s_cmp_eq_u32 s72, s0
	s_cselect_b32 s85, s43, s52
	s_cselect_b32 s84, s59, s1
	s_cselect_b32 s1, s86, s89
	s_cselect_b32 s0, s87, s88
	s_add_i32 s52, 0, 0x14000
	s_branch .Lrot_head_2

; template <class Epi, class Sched>
; __device__ __forceinline__ void gemm_phase(LAS unsigned char* lds, const Gemm g, const Sched& S, const Epi& E) {
;     ...
;             const bool last = (t == nt - 2);
;             const char* a1 = cA + (size_t)(t + 1) * kstep;
;             const char* a2 = last ? nA : cA + (size_t)(t + 2) * kstep; const char* b2 = last ? nB : cB + (size_t)(t + 2) * kstep;
;             const char* a3 = a2 + kstep; const char* b3 = b2 + kstep;
.LBB0_238:
	s_add_i32 s68, s0, 2
	s_add_u32 s1, s20, 0xfffc0080
	s_addc_u32 s52, s21, -1
	s_add_i32 s53, 0, 0x10000
	s_cmp_eq_u32 s71, s0
	s_cselect_b32 s89, s48, s52
	s_cselect_b32 s88, s59, s1
	s_cselect_b32 s1, s63, s90
	s_cselect_b32 s0, s85, s87
	s_add_i32 s52, 0, 0x14000
	s_branch .Lrot_body_3

; #define PG8_STAGE(bufoff, gbase, voff) do { _Pragma("unroll") for (int _i = 0; _i < 2; ++_i) \
;         __builtin_amdgcn_global_load_lds((const unsigned*)((const char*)(gbase) + (voff)[_i]), (LAS unsigned*)(lds + (bufoff) + ldsw + _i * 8192), 16, 0, 0); } while (0)
; #define PG8_LDA(dst, b, h) do { _Pragma("unroll") for (int m = 0; m < 4; ++m) _Pragma("unroll") for (int k = 0; k < 2; ++k) dst[m][k] = *(const LAS bf16x8*)(lds + PG8_SA(b, h) + aoff + m * 2048 + k * 1024); } while (0)
; #define PG8_LDB(dst, b, h) do { _Pragma("unroll") for (int n = 0; n < 2; ++n) _Pragma("unroll") for (int k = 0; k < 2; ++k) dst[n][k] = *(const LAS bf16x8*)(lds + PG8_SB(b, h) + boff + n * 2048 + k * 1024); } while (0)
; #define PG8_MMA(ai, bj, At, Bt) do { __builtin_amdgcn_s_setprio(1); _Pragma("unroll") for (int m = 0; m < 4; ++m) _Pragma("unroll") for (int n = 0; n < 2; ++n) _Pragma("unroll") for (int k = 0; k < 2; ++k) \
;         acc[ai][bj][m][n] = __builtin_amdgcn_mfma_f32_16x16x32_bf16(Bt[n][k], At[m][k], acc[ai][bj][m][n], 0, 0, 0); __builtin_amdgcn_s_setprio(0); } while (0)
; #define PG8_WAIT_V(n) asm volatile("s_waitcnt vmcnt(" #n ")" ::: "memory")
; #define PG8_WAIT_L(n) asm volatile("s_waitcnt lgkmcnt(" #n ")" ::: "memory")
; #define PG8_BAR __builtin_amdgcn_s_barrier()
; #define PG8_SCHED __builtin_amdgcn_sched_barrier(0)
; template <class Epi, class Sched>
; __device__ __forceinline__ void gemm_phase(LAS unsigned char* lds, const Gemm g, const Sched& S, const Epi& E) {
;     ...
;             PG8_LDB(B0, 0, 0); PG8_LDB(B1, 0, 1); PG8_SCHED; PG8_LDA(At, 0, 0); PG8_STAGE(PG8_SA(1, 1), a1 + hstepA, voffA);
;             PG8_WAIT_V(8); PG8_WAIT_L(0); PG8_BAR; PG8_MMA(0, 0, At, B0); PG8_MMA(0, 1, At, B1); PG8_BAR; PG8_SCHED;
;             PG8_LDA(At, 0, 1); PG8_STAGE(PG8_SB(0, 0), b2, voffB); PG8_STAGE(PG8_SB(0, 1), b2 + hstepB, voffB); PG8_STAGE(PG8_SA(0, 0), a2, voffA);
.Lrot_body_3:
	v_add_u32_e32 v152, s53, v164
	v_add_u32_e32 v160, s52, v164
	ds_read_b128 v[130:133], v152
	ds_read_b128 v[134:137], v152 offset:1024
	ds_read_b128 v[138:141], v152 offset:2048
	ds_read_b128 v[152:155], v152 offset:3072
	ds_read_b128 v[156:159], v160
	ds_read_b128 v[166:169], v160 offset:1024
	ds_read_b128 v[170:173], v160 offset:2048
	ds_read_b128 v[174:177], v160 offset:3072
	v_lshl_add_u64 v[160:161], s[20:21], 0, v[150:151]
	s_add_i32 m0, s15, 0xc000
	ds_read_b128 v[178:181], v165
	ds_read_b128 v[182:185], v165 offset:1024
	ds_read_b128 v[196:199], v165 offset:2048
	ds_read_b128 v[200:203], v165 offset:3072
	ds_read_b128 v[204:207], v165 offset:4096
	ds_read_b128 v[208:211], v165 offset:5120
	ds_read_b128 v[212:215], v165 offset:6144
	ds_read_b128 v[216:219], v165 offset:7168
	global_load_lds_dwordx4 v[160:161], off
	v_lshl_add_u64 v[160:161], s[20:21], 0, v[148:149]
	s_add_i32 m0, s15, 0xe000
	s_nop 0
	global_load_lds_dwordx4 v[160:161], off
	s_waitcnt vmcnt(8)
	s_waitcnt lgkmcnt(0)
	s_barrier
	s_setprio 1
	s_waitcnt lgkmcnt(0)
	v_mfma_f32_16x16x32_bf16 v[126:129], v[130:133], v[178:181], v[126:129]
	v_mfma_f32_16x16x32_bf16 v[122:125], v[138:141], v[178:181], v[122:125]
	v_mfma_f32_16x16x32_bf16 v[110:113], v[130:133], v[196:199], v[110:113]
	v_mfma_f32_16x16x32_bf16 v[106:109], v[138:141], v[196:199], v[106:109]
	v_mfma_f32_16x16x32_bf16 v[94:97], v[130:133], v[204:207], v[94:97]
	v_mfma_f32_16x16x32_bf16 v[90:93], v[138:141], v[204:207], v[90:93]
	v_mfma_f32_16x16x32_bf16 v[78:81], v[130:133], v[212:215], v[78:81]
	v_mfma_f32_16x16x32_bf16 v[74:77], v[138:141], v[212:215], v[74:77]
	v_mfma_f32_16x16x32_bf16 v[126:129], v[134:137], v[182:185], v[126:129]
	v_mfma_f32_16x16x32_bf16 v[122:125], v[152:155], v[182:185], v[122:125]
	v_mfma_f32_16x16x32_bf16 v[110:113], v[134:137], v[200:203], v[110:113]
	v_mfma_f32_16x16x32_bf16 v[106:109], v[152:155], v[200:203], v[106:109]
	v_mfma_f32_16x16x32_bf16 v[94:97], v[134:137], v[208:211], v[94:97]
	v_mfma_f32_16x16x32_bf16 v[90:93], v[152:155], v[208:211], v[90:93]
	v_mfma_f32_16x16x32_bf16 v[78:81], v[134:137], v[216:219], v[78:81]
	v_mfma_f32_16x16x32_bf16 v[74:77], v[152:155], v[216:219], v[74:77]
	v_mfma_f32_16x16x32_bf16 v[118:121], v[156:159], v[178:181], v[118:121]
	v_mfma_f32_16x16x32_bf16 v[114:117], v[170:173], v[178:181], v[114:117]
	v_mfma_f32_16x16x32_bf16 v[102:105], v[156:159], v[196:199], v[102:105]
	v_mfma_f32_16x16x32_bf16 v[98:101], v[170:173], v[196:199], v[98:101]
	v_mfma_f32_16x16x32_bf16 v[86:89], v[156:159], v[204:207], v[86:89]
	v_mfma_f32_16x16x32_bf16 v[82:85], v[170:173], v[204:207], v[82:85]
	v_mfma_f32_16x16x32_bf16 v[70:73], v[156:159], v[212:215], v[70:73]
	v_mfma_f32_16x16x32_bf16 v[66:69], v[170:173], v[212:215], v[66:69]
	v_mfma_f32_16x16x32_bf16 v[118:121], v[166:169], v[182:185], v[118:121]
	v_mfma_f32_16x16x32_bf16 v[114:117], v[174:177], v[182:185], v[114:117]
	v_mfma_f32_16x16x32_bf16 v[102:105], v[166:169], v[200:203], v[102:105]
	v_mfma_f32_16x16x32_bf16 v[98:101], v[174:177], v[200:203], v[98:101]
	v_mfma_f32_16x16x32_bf16 v[86:89], v[166:169], v[208:211], v[86:89]
	v_mfma_f32_16x16x32_bf16 v[82:85], v[174:177], v[208:211], v[82:85]
	v_mfma_f32_16x16x32_bf16 v[70:73], v[166:169], v[216:219], v[70:73]
	v_mfma_f32_16x16x32_bf16 v[66:69], v[174:177], v[216:219], v[66:69]
	s_setprio 0
	s_barrier
	s_add_i32 s53, s53, s14
	v_lshl_add_u64 v[160:161], s[0:1], 0, v[0:1]
	s_mov_b32 m0, s53
	ds_read_b128 v[178:181], v165 offset:16384
	ds_read_b128 v[182:185], v165 offset:17408
	ds_read_b128 v[196:199], v165 offset:18432
	ds_read_b128 v[200:203], v165 offset:19456
	ds_read_b128 v[204:207], v165 offset:20480
	ds_read_b128 v[208:211], v165 offset:21504
	ds_read_b128 v[212:215], v165 offset:22528
	ds_read_b128 v[216:219], v165 offset:23552
	global_load_lds_dwordx4 v[160:161], off
	s_add_i32 m0, s53, 0x2000
	s_add_u32 s92, s0, 0x40000
	v_lshl_add_u64 v[220:221], s[0:1], 0, v[146:147]
	s_addc_u32 s93, s1, 0
	s_add_i32 s52, s52, s14
	global_load_lds_dwordx4 v[220:221], off
	v_lshl_add_u64 v[232:233], s[92:93], 0, v[0:1]
	s_mov_b32 m0, s52
	v_lshl_add_u64 v[234:235], s[88:89], 0, v[144:145]
	global_load_lds_dwordx4 v[232:233], off
	v_lshl_add_u64 v[232:233], s[92:93], 0, v[146:147]
	s_add_i32 m0, s52, 0x2000
	s_nop 0
	global_load_lds_dwordx4 v[232:233], off
	v_lshl_add_u64 v[232:233], s[88:89], 0, v[142:143]
	s_mov_b32 m0, s15
	s_nop 0
	global_load_lds_dwordx4 v[232:233], off
	s_mov_b32 m0, s16
	s_nop 0
	global_load_lds_dwordx4 v[234:235], off
	s_waitcnt vmcnt(8)
	s_waitcnt lgkmcnt(0)
	s_barrier
; #define PG8_STAGE(bufoff, gbase, voff) do { _Pragma("unroll") for (int _i = 0; _i < 2; ++_i) \
;         __builtin_amdgcn_global_load_lds((const unsigned*)((const char*)(gbase) + (voff)[_i]), (LAS unsigned*)(lds + (bufoff) + ldsw + _i * 8192), 16, 0, 0); } while (0)
; #define PG8_LDA(dst, b, h) do { _Pragma("unroll") for (int m = 0; m < 4; ++m) _Pragma("unroll") for (int k = 0; k < 2; ++k) dst[m][k] = *(const LAS bf16x8*)(lds + PG8_SA(b, h) + aoff + m * 2048 + k * 1024); } while (0)
; #define PG8_LDB(dst, b, h) do { _Pragma("unroll") for (int n = 0; n < 2; ++n) _Pragma("unroll") for (int k = 0; k < 2; ++k) dst[n][k] = *(const LAS bf16x8*)(lds + PG8_SB(b, h) + boff + n * 2048 + k * 1024); } while (0)
; #define PG8_MMA(ai, bj, At, Bt) do { __builtin_amdgcn_s_setprio(1); _Pragma("unroll") for (int m = 0; m < 4; ++m) _Pragma("unroll") for (int n = 0; n < 2; ++n) _Pragma("unroll") for (int k = 0; k < 2; ++k) \
;         acc[ai][bj][m][n] = __builtin_amdgcn_mfma_f32_16x16x32_bf16(Bt[n][k], At[m][k], acc[ai][bj][m][n], 0, 0, 0); __builtin_amdgcn_s_setprio(0); } while (0)
; #define PG8_WAIT_V(n) asm volatile("s_waitcnt vmcnt(" #n ")" ::: "memory")
; #define PG8_WAIT_L(n) asm volatile("s_waitcnt lgkmcnt(" #n ")" ::: "memory")
; #define PG8_BAR __builtin_amdgcn_s_barrier()
; #define PG8_SCHED __builtin_amdgcn_sched_barrier(0)
; template <class Epi, class Sched>
; __device__ __forceinline__ void gemm_phase(LAS unsigned char* lds, const Gemm g, const Sched& S, const Epi& E) {
;     ...
;             PG8_WAIT_V(8); PG8_WAIT_L(0); PG8_BAR; PG8_MMA(1, 0, At, B0); PG8_MMA(1, 1, At, B1); PG8_BAR; PG8_SCHED;
;             PG8_LDB(B0, 1, 0); PG8_LDB(B1, 1, 1); PG8_SCHED; PG8_LDA(At, 1, 0); PG8_STAGE(PG8_SA(0, 1), a2 + hstepA, voffA);
;             PG8_WAIT_V(8); PG8_WAIT_L(0); PG8_BAR; PG8_MMA(0, 0, At, B0); PG8_MMA(0, 1, At, B1); PG8_BAR; PG8_SCHED;
	s_setprio 1
	s_waitcnt lgkmcnt(0)
	v_mfma_f32_16x16x32_bf16 v[62:65], v[130:133], v[178:181], v[62:65]
	v_mfma_f32_16x16x32_bf16 v[58:61], v[138:141], v[178:181], v[58:61]
	v_mfma_f32_16x16x32_bf16 v[46:49], v[130:133], v[196:199], v[46:49]
	v_mfma_f32_16x16x32_bf16 v[42:45], v[138:141], v[196:199], v[42:45]
	v_mfma_f32_16x16x32_bf16 v[30:33], v[130:133], v[204:207], v[30:33]
	v_mfma_f32_16x16x32_bf16 v[26:29], v[138:141], v[204:207], v[26:29]
	v_mfma_f32_16x16x32_bf16 v[14:17], v[130:133], v[212:215], v[14:17]
	v_mfma_f32_16x16x32_bf16 v[10:13], v[138:141], v[212:215], v[10:13]
	v_mfma_f32_16x16x32_bf16 v[62:65], v[134:137], v[182:185], v[62:65]
	v_mfma_f32_16x16x32_bf16 v[58:61], v[152:155], v[182:185], v[58:61]
	v_mfma_f32_16x16x32_bf16 v[46:49], v[134:137], v[200:203], v[46:49]
	v_mfma_f32_16x16x32_bf16 v[42:45], v[152:155], v[200:203], v[42:45]
	v_mfma_f32_16x16x32_bf16 v[30:33], v[134:137], v[208:211], v[30:33]
	v_mfma_f32_16x16x32_bf16 v[26:29], v[152:155], v[208:211], v[26:29]
	v_mfma_f32_16x16x32_bf16 v[14:17], v[134:137], v[216:219], v[14:17]
	v_mfma_f32_16x16x32_bf16 v[10:13], v[152:155], v[216:219], v[10:13]
	v_mfma_f32_16x16x32_bf16 v[54:57], v[156:159], v[178:181], v[54:57]
	v_mfma_f32_16x16x32_bf16 v[50:53], v[170:173], v[178:181], v[50:53]
	v_mfma_f32_16x16x32_bf16 v[38:41], v[156:159], v[196:199], v[38:41]
	v_mfma_f32_16x16x32_bf16 v[34:37], v[170:173], v[196:199], v[34:37]
	v_mfma_f32_16x16x32_bf16 v[22:25], v[156:159], v[204:207], v[22:25]
	v_mfma_f32_16x16x32_bf16 v[18:21], v[170:173], v[204:207], v[18:21]
	v_mfma_f32_16x16x32_bf16 v[6:9], v[156:159], v[212:215], v[6:9]
	v_mfma_f32_16x16x32_bf16 v[2:5], v[170:173], v[212:215], v[2:5]
	v_mfma_f32_16x16x32_bf16 v[54:57], v[166:169], v[182:185], v[54:57]
	v_mfma_f32_16x16x32_bf16 v[50:53], v[174:177], v[182:185], v[50:53]
	v_mfma_f32_16x16x32_bf16 v[38:41], v[166:169], v[200:203], v[38:41]
	v_mfma_f32_16x16x32_bf16 v[34:37], v[174:177], v[200:203], v[34:37]
	v_mfma_f32_16x16x32_bf16 v[22:25], v[166:169], v[208:211], v[22:25]
	v_mfma_f32_16x16x32_bf16 v[18:21], v[174:177], v[208:211], v[18:21]
	v_mfma_f32_16x16x32_bf16 v[6:9], v[166:169], v[216:219], v[6:9]
	v_mfma_f32_16x16x32_bf16 v[2:5], v[174:177], v[216:219], v[2:5]
	s_setprio 0
	s_barrier
	s_add_i32 s52, 0, 0x18000
	s_add_i32 s53, 0, 0x1c000
	v_add_u32_e32 v152, s52, v164
	v_add_u32_e32 v174, s53, v164
	ds_read_b128 v[130:133], v152
	ds_read_b128 v[134:137], v152 offset:1024
	ds_read_b128 v[138:141], v152 offset:2048
	ds_read_b128 v[152:155], v152 offset:3072
	ds_read_b128 v[156:159], v174
	ds_read_b128 v[166:169], v174 offset:1024
	ds_read_b128 v[170:173], v174 offset:2048
	ds_read_b128 v[174:177], v174 offset:3072
	s_add_u32 s88, s88, 0x40000
	s_addc_u32 s89, s89, 0
	s_mov_b32 m0, s17
	v_lshl_add_u64 v[236:237], s[88:89], 0, v[142:143]
	ds_read_b128 v[178:181], v165 offset:32768
	ds_read_b128 v[182:185], v165 offset:33792
	ds_read_b128 v[196:199], v165 offset:34816
	ds_read_b128 v[200:203], v165 offset:35840
	ds_read_b128 v[204:207], v165 offset:36864
	ds_read_b128 v[208:211], v165 offset:37888
	ds_read_b128 v[212:215], v165 offset:38912
	ds_read_b128 v[216:219], v165 offset:39936
	global_load_lds_dwordx4 v[236:237], off
	v_lshl_add_u64 v[236:237], s[88:89], 0, v[144:145]
	s_mov_b32 m0, s19
	s_nop 0
	global_load_lds_dwordx4 v[236:237], off
	s_waitcnt vmcnt(8)
	s_waitcnt lgkmcnt(0)
	s_barrier
	s_setprio 1
	s_waitcnt lgkmcnt(0)
	v_mfma_f32_16x16x32_bf16 v[126:129], v[130:133], v[178:181], v[126:129]
	v_mfma_f32_16x16x32_bf16 v[122:125], v[138:141], v[178:181], v[122:125]
	v_mfma_f32_16x16x32_bf16 v[110:113], v[130:133], v[196:199], v[110:113]
	v_mfma_f32_16x16x32_bf16 v[106:109], v[138:141], v[196:199], v[106:109]
	v_mfma_f32_16x16x32_bf16 v[94:97], v[130:133], v[204:207], v[94:97]
	v_mfma_f32_16x16x32_bf16 v[90:93], v[138:141], v[204:207], v[90:93]
	v_mfma_f32_16x16x32_bf16 v[78:81], v[130:133], v[212:215], v[78:81]
	v_mfma_f32_16x16x32_bf16 v[74:77], v[138:141], v[212:215], v[74:77]
	v_mfma_f32_16x16x32_bf16 v[126:129], v[134:137], v[182:185], v[126:129]
	v_mfma_f32_16x16x32_bf16 v[122:125], v[152:155], v[182:185], v[122:125]
	v_mfma_f32_16x16x32_bf16 v[110:113], v[134:137], v[200:203], v[110:113]
	v_mfma_f32_16x16x32_bf16 v[106:109], v[152:155], v[200:203], v[106:109]
	v_mfma_f32_16x16x32_bf16 v[94:97], v[134:137], v[208:211], v[94:97]
	v_mfma_f32_16x16x32_bf16 v[90:93], v[152:155], v[208:211], v[90:93]
	v_mfma_f32_16x16x32_bf16 v[78:81], v[134:137], v[216:219], v[78:81]
	v_mfma_f32_16x16x32_bf16 v[74:77], v[152:155], v[216:219], v[74:77]
	v_mfma_f32_16x16x32_bf16 v[118:121], v[156:159], v[178:181], v[118:121]
	v_mfma_f32_16x16x32_bf16 v[114:117], v[170:173], v[178:181], v[114:117]
	v_mfma_f32_16x16x32_bf16 v[102:105], v[156:159], v[196:199], v[102:105]
	v_mfma_f32_16x16x32_bf16 v[98:101], v[170:173], v[196:199], v[98:101]
	v_mfma_f32_16x16x32_bf16 v[86:89], v[156:159], v[204:207], v[86:89]
	v_mfma_f32_16x16x32_bf16 v[82:85], v[170:173], v[204:207], v[82:85]
	v_mfma_f32_16x16x32_bf16 v[70:73], v[156:159], v[212:215], v[70:73]
	v_mfma_f32_16x16x32_bf16 v[66:69], v[170:173], v[212:215], v[66:69]
	v_mfma_f32_16x16x32_bf16 v[118:121], v[166:169], v[182:185], v[118:121]
	v_mfma_f32_16x16x32_bf16 v[114:117], v[174:177], v[182:185], v[114:117]
	v_mfma_f32_16x16x32_bf16 v[102:105], v[166:169], v[200:203], v[102:105]
	v_mfma_f32_16x16x32_bf16 v[98:101], v[174:177], v[200:203], v[98:101]
	v_mfma_f32_16x16x32_bf16 v[86:89], v[166:169], v[208:211], v[86:89]
	v_mfma_f32_16x16x32_bf16 v[82:85], v[174:177], v[208:211], v[82:85]
	v_mfma_f32_16x16x32_bf16 v[70:73], v[166:169], v[216:219], v[70:73]
	v_mfma_f32_16x16x32_bf16 v[66:69], v[174:177], v[216:219], v[66:69]
	s_setprio 0
	s_barrier
; #define PG8_STAGE(bufoff, gbase, voff) do { _Pragma("unroll") for (int _i = 0; _i < 2; ++_i) \
;         __builtin_amdgcn_global_load_lds((const unsigned*)((const char*)(gbase) + (voff)[_i]), (LAS unsigned*)(lds + (bufoff) + ldsw + _i * 8192), 16, 0, 0); } while (0)
; #define PG8_LDA(dst, b, h) do { _Pragma("unroll") for (int m = 0; m < 4; ++m) _Pragma("unroll") for (int k = 0; k < 2; ++k) dst[m][k] = *(const LAS bf16x8*)(lds + PG8_SA(b, h) + aoff + m * 2048 + k * 1024); } while (0)
; #define PG8_LDB(dst, b, h) do { _Pragma("unroll") for (int n = 0; n < 2; ++n) _Pragma("unroll") for (int k = 0; k < 2; ++k) dst[n][k] = *(const LAS bf16x8*)(lds + PG8_SB(b, h) + boff + n * 2048 + k * 1024); } while (0)
; #define PG8_WAIT_V(n) asm volatile("s_waitcnt vmcnt(" #n ")" ::: "memory")
; #define PG8_WAIT_L(n) asm volatile("s_waitcnt lgkmcnt(" #n ")" ::: "memory")
; template <class Epi, class Sched>
; __device__ __forceinline__ void gemm_phase(LAS unsigned char* lds, const Gemm g, const Sched& S, const Epi& E) {
;     ...
;             const bool last = (t == nt - 2);
;             const char* a1 = cA + (size_t)(t + 1) * kstep;
;             const char* a2 = last ? nA : cA + (size_t)(t + 2) * kstep; const char* b2 = last ? nB : cB + (size_t)(t + 2) * kstep;
;             const char* a3 = a2 + kstep; const char* b3 = b2 + kstep;
;             PG8_LDB(B0, 0, 0); PG8_LDB(B1, 0, 1); PG8_SCHED; PG8_LDA(At, 0, 0); PG8_STAGE(PG8_SA(1, 1), a1 + hstepA, voffA);
;             PG8_WAIT_V(8); PG8_WAIT_L(0); PG8_BAR; PG8_MMA(0, 0, At, B0); PG8_MMA(0, 1, At, B1); PG8_BAR; PG8_SCHED;
;             PG8_LDA(At, 0, 1); PG8_STAGE(PG8_SB(0, 0), b2, voffB); PG8_STAGE(PG8_SB(0, 1), b2 + hstepB, voffB); PG8_STAGE(PG8_SA(0, 0), a2, voffA);
;             PG8_WAIT_V(8); PG8_WAIT_L(0); PG8_BAR; PG8_MMA(1, 0, At, B0); PG8_MMA(1, 1, At, B1); PG8_BAR; PG8_SCHED;
;             PG8_LDB(B0, 1, 0); PG8_LDB(B1, 1, 1); PG8_SCHED; PG8_LDA(At, 1, 0); PG8_STAGE(PG8_SA(0, 1), a2 + hstepA, voffA);
;             PG8_WAIT_V(8); PG8_WAIT_L(0); PG8_BAR; PG8_MMA(0, 0, At, B0); PG8_MMA(0, 1, At, B1); PG8_BAR; PG8_SCHED;
;             PG8_LDA(At, 1, 1); PG8_STAGE(PG8_SB(1, 0), b3, voffB); PG8_STAGE(PG8_SB(1, 1), b3 + hstepB, voffB); PG8_STAGE(PG8_SA(1, 0), a3, voffA);
;             PG8_WAIT_V(8); PG8_WAIT_L(0); PG8_BAR; PG8_MMA(1, 0, At, B0); PG8_MMA(1, 1, At, B1); PG8_BAR; PG8_SCHED;
;         }
	s_add_i32 s52, s52, s14
	v_lshl_add_u64 v[160:161], v[160:161], 0, s[26:27]
	s_mov_b32 m0, s52
	ds_read_b128 v[178:181], v165 offset:49152
	ds_read_b128 v[182:185], v165 offset:50176
	ds_read_b128 v[196:199], v165 offset:51200
	ds_read_b128 v[200:203], v165 offset:52224
	ds_read_b128 v[204:207], v165 offset:53248
	ds_read_b128 v[208:211], v165 offset:54272
	ds_read_b128 v[212:215], v165 offset:55296
	ds_read_b128 v[216:219], v165 offset:56320
	global_load_lds_dwordx4 v[160:161], off
	s_add_i32 m0, s52, 0x2000
	s_add_u32 s0, s0, 0x40080
	v_lshl_add_u64 v[160:161], v[220:221], 0, s[26:27]
	s_addc_u32 s1, s1, 0
	s_add_i32 s52, s53, s14
	global_load_lds_dwordx4 v[160:161], off
	v_lshl_add_u64 v[160:161], s[0:1], 0, v[0:1]
	s_mov_b32 m0, s52
	s_nop 0
	global_load_lds_dwordx4 v[160:161], off
	v_lshl_add_u64 v[160:161], s[0:1], 0, v[146:147]
	s_add_i32 m0, s52, 0x2000
	s_nop 0
	global_load_lds_dwordx4 v[160:161], off
	v_lshl_add_u64 v[160:161], v[232:233], 0, s[26:27]
	s_mov_b32 m0, s67
	s_nop 0
	global_load_lds_dwordx4 v[160:161], off
	v_lshl_add_u64 v[160:161], v[234:235], 0, s[26:27]
	s_mov_b32 m0, s69
	s_nop 0
	global_load_lds_dwordx4 v[160:161], off
	s_waitcnt vmcnt(8)
	s_waitcnt lgkmcnt(0)
	s_barrier
	s_setprio 1
	s_waitcnt lgkmcnt(0)
	v_mfma_f32_16x16x32_bf16 v[62:65], v[130:133], v[178:181], v[62:65]
	v_mfma_f32_16x16x32_bf16 v[58:61], v[138:141], v[178:181], v[58:61]
	v_mfma_f32_16x16x32_bf16 v[46:49], v[130:133], v[196:199], v[46:49]
	v_mfma_f32_16x16x32_bf16 v[42:45], v[138:141], v[196:199], v[42:45]
	v_mfma_f32_16x16x32_bf16 v[30:33], v[130:133], v[204:207], v[30:33]
	v_mfma_f32_16x16x32_bf16 v[26:29], v[138:141], v[204:207], v[26:29]
	v_mfma_f32_16x16x32_bf16 v[14:17], v[130:133], v[212:215], v[14:17]
	v_mfma_f32_16x16x32_bf16 v[10:13], v[138:141], v[212:215], v[10:13]
	v_mfma_f32_16x16x32_bf16 v[62:65], v[134:137], v[182:185], v[62:65]
	v_mfma_f32_16x16x32_bf16 v[58:61], v[152:155], v[182:185], v[58:61]
	v_mfma_f32_16x16x32_bf16 v[46:49], v[134:137], v[200:203], v[46:49]
	v_mfma_f32_16x16x32_bf16 v[42:45], v[152:155], v[200:203], v[42:45]
	v_mfma_f32_16x16x32_bf16 v[30:33], v[134:137], v[208:211], v[30:33]
	v_mfma_f32_16x16x32_bf16 v[26:29], v[152:155], v[208:211], v[26:29]
	v_mfma_f32_16x16x32_bf16 v[14:17], v[134:137], v[216:219], v[14:17]
	v_mfma_f32_16x16x32_bf16 v[10:13], v[152:155], v[216:219], v[10:13]
	v_mfma_f32_16x16x32_bf16 v[54:57], v[156:159], v[178:181], v[54:57]
	v_mfma_f32_16x16x32_bf16 v[50:53], v[170:173], v[178:181], v[50:53]
	v_mfma_f32_16x16x32_bf16 v[38:41], v[156:159], v[196:199], v[38:41]
	v_mfma_f32_16x16x32_bf16 v[34:37], v[170:173], v[196:199], v[34:37]
	v_mfma_f32_16x16x32_bf16 v[22:25], v[156:159], v[204:207], v[22:25]
	v_mfma_f32_16x16x32_bf16 v[18:21], v[170:173], v[204:207], v[18:21]
	v_mfma_f32_16x16x32_bf16 v[6:9], v[156:159], v[212:215], v[6:9]
	v_mfma_f32_16x16x32_bf16 v[2:5], v[170:173], v[212:215], v[2:5]
	v_mfma_f32_16x16x32_bf16 v[54:57], v[166:169], v[182:185], v[54:57]
	v_mfma_f32_16x16x32_bf16 v[50:53], v[174:177], v[182:185], v[50:53]
	v_mfma_f32_16x16x32_bf16 v[38:41], v[166:169], v[200:203], v[38:41]
	v_mfma_f32_16x16x32_bf16 v[34:37], v[174:177], v[200:203], v[34:37]
	v_mfma_f32_16x16x32_bf16 v[22:25], v[166:169], v[208:211], v[22:25]
	v_mfma_f32_16x16x32_bf16 v[18:21], v[174:177], v[208:211], v[18:21]
	v_mfma_f32_16x16x32_bf16 v[6:9], v[166:169], v[216:219], v[6:9]
	v_mfma_f32_16x16x32_bf16 v[2:5], v[174:177], v[216:219], v[2:5]
	s_setprio 0
	s_add_u32 s87, s87, 0x100
	s_addc_u32 s90, s90, 0
	s_add_u32 s20, s20, 0x100
	s_addc_u32 s21, s21, 0
	s_cmp_ge_i32 s68, s46
	s_mov_b32 s0, s68
	s_cbranch_scc1 .Lrot_exit_3
	s_add_i32 s68, s0, 2
	s_add_u32 s1, s20, 0xfffc0080
	s_addc_u32 s52, s21, -1
	s_add_i32 s53, 0, 0x10000
	s_cmp_eq_u32 s71, s0
	s_cselect_b32 s89, s48, s52
	s_cselect_b32 s88, s59, s1
	s_cselect_b32 s1, s63, s90
	s_cselect_b32 s0, s85, s87
	s_add_i32 s52, 0, 0x14000
	s_branch .Lrot_head_3

; template <class Epi, class Sched>
; __device__ __forceinline__ void gemm_phase(LAS unsigned char* lds, const Gemm g, const Sched& S, const Epi& E) {
;     ...
;             const bool last = (t == nt - 2);
;             const char* a1 = cA + (size_t)(t + 1) * kstep;
;             const char* a2 = last ? nA : cA + (size_t)(t + 2) * kstep; const char* b2 = last ? nB : cB + (size_t)(t + 2) * kstep;
;             const char* a3 = a2 + kstep; const char* b3 = b2 + kstep;
.LBB0_375:
	s_add_i32 s63, s40, 2
	s_add_u32 s0, s20, 0x100
	s_addc_u32 s1, s21, 0
	s_add_i32 s72, 0, 0x10000
	s_cmp_eq_u32 s77, s40
	s_cselect_b32 s43, s91, s1
	s_cselect_b32 s42, s90, s0
	s_branch .Lrot_body_4

; #define PG8_STAGE(bufoff, gbase, voff) do { _Pragma("unroll") for (int _i = 0; _i < 2; ++_i) \
;         __builtin_amdgcn_global_load_lds((const unsigned*)((const char*)(gbase) + (voff)[_i]), (LAS unsigned*)(lds + (bufoff) + ldsw + _i * 8192), 16, 0, 0); } while (0)
; #define PG8_LDA(dst, b, h) do { _Pragma("unroll") for (int m = 0; m < 4; ++m) _Pragma("unroll") for (int k = 0; k < 2; ++k) dst[m][k] = *(const LAS bf16x8*)(lds + PG8_SA(b, h) + aoff + m * 2048 + k * 1024); } while (0)
; #define PG8_LDB(dst, b, h) do { _Pragma("unroll") for (int n = 0; n < 2; ++n) _Pragma("unroll") for (int k = 0; k < 2; ++k) dst[n][k] = *(const LAS bf16x8*)(lds + PG8_SB(b, h) + boff + n * 2048 + k * 1024); } while (0)
; #define PG8_MMA(ai, bj, At, Bt) do { __builtin_amdgcn_s_setprio(1); _Pragma("unroll") for (int m = 0; m < 4; ++m) _Pragma("unroll") for (int n = 0; n < 2; ++n) _Pragma("unroll") for (int k = 0; k < 2; ++k) \
;         acc[ai][bj][m][n] = __builtin_amdgcn_mfma_f32_16x16x32_bf16(Bt[n][k], At[m][k], acc[ai][bj][m][n], 0, 0, 0); __builtin_amdgcn_s_setprio(0); } while (0)
; #define PG8_WAIT_V(n) asm volatile("s_waitcnt vmcnt(" #n ")" ::: "memory")
; #define PG8_WAIT_L(n) asm volatile("s_waitcnt lgkmcnt(" #n ")" ::: "memory")
; #define PG8_BAR __builtin_amdgcn_s_barrier()
; #define PG8_SCHED __builtin_amdgcn_sched_barrier(0)
; template <class Epi, class Sched>
; __device__ __forceinline__ void gemm_phase(LAS unsigned char* lds, const Gemm g, const Sched& S, const Epi& E) {
;     ...
;             PG8_LDB(B0, 0, 0); PG8_LDB(B1, 0, 1); PG8_SCHED; PG8_LDA(At, 0, 0); PG8_STAGE(PG8_SA(1, 1), a1 + hstepA, voffA);
;             PG8_WAIT_V(8); PG8_WAIT_L(0); PG8_BAR; PG8_MMA(0, 0, At, B0); PG8_MMA(0, 1, At, B1); PG8_BAR; PG8_SCHED;
;             PG8_LDA(At, 0, 1); PG8_STAGE(PG8_SB(0, 0), b2, voffB); PG8_STAGE(PG8_SB(0, 1), b2 + hstepB, voffB); PG8_STAGE(PG8_SA(0, 0), a2, voffA);
.Lrot_body_4:
	v_add_u32_e32 v0, s72, v178
	s_cselect_b32 s41, s93, s62
	s_cselect_b32 s40, s92, s68
	s_add_i32 s76, 0, 0x14000
	ds_read_b128 v[142:145], v0
	ds_read_b128 v[146:149], v0 offset:1024
	ds_read_b128 v[150:153], v0 offset:2048
	ds_read_b128 v[154:157], v0 offset:3072
	v_add_u32_e32 v0, s76, v178
	ds_read_b128 v[158:161], v0
	ds_read_b128 v[162:165], v0 offset:1024
	ds_read_b128 v[166:169], v0 offset:2048
	ds_read_b128 v[170:173], v0 offset:3072
	v_lshl_add_u64 v[174:175], s[20:21], 0, v[140:141]
	s_add_i32 m0, s17, 0xc000
	ds_read_b128 v[180:183], v179
	ds_read_b128 v[196:199], v179 offset:1024
	ds_read_b128 v[200:203], v179 offset:2048
	ds_read_b128 v[204:207], v179 offset:3072
	ds_read_b128 v[208:211], v179 offset:4096
	ds_read_b128 v[212:215], v179 offset:5120
	ds_read_b128 v[216:219], v179 offset:6144
	ds_read_b128 v[248:251], v179 offset:7168
	global_load_lds_dwordx4 v[174:175], off
	v_lshl_add_u64 v[174:175], s[20:21], 0, v[138:139]
	s_add_i32 m0, s17, 0xe000
	s_nop 0
	global_load_lds_dwordx4 v[174:175], off
	s_waitcnt vmcnt(8)
	s_waitcnt lgkmcnt(0)
	s_barrier
	s_setprio 1
	s_waitcnt lgkmcnt(0)
	v_mfma_f32_16x16x32_bf16 v[126:129], v[142:145], v[180:183], v[126:129]
	v_mfma_f32_16x16x32_bf16 v[122:125], v[150:153], v[180:183], v[122:125]
	v_mfma_f32_16x16x32_bf16 v[118:121], v[142:145], v[200:203], v[118:121]
	v_mfma_f32_16x16x32_bf16 v[114:117], v[150:153], v[200:203], v[114:117]
	v_mfma_f32_16x16x32_bf16 v[110:113], v[142:145], v[208:211], v[110:113]
	v_mfma_f32_16x16x32_bf16 v[106:109], v[150:153], v[208:211], v[106:109]
	v_mfma_f32_16x16x32_bf16 v[102:105], v[142:145], v[216:219], v[102:105]
	v_mfma_f32_16x16x32_bf16 v[98:101], v[150:153], v[216:219], v[98:101]
	v_mfma_f32_16x16x32_bf16 v[126:129], v[146:149], v[196:199], v[126:129]
	v_mfma_f32_16x16x32_bf16 v[122:125], v[154:157], v[196:199], v[122:125]
	v_mfma_f32_16x16x32_bf16 v[118:121], v[146:149], v[204:207], v[118:121]
	v_mfma_f32_16x16x32_bf16 v[114:117], v[154:157], v[204:207], v[114:117]
	v_mfma_f32_16x16x32_bf16 v[110:113], v[146:149], v[212:215], v[110:113]
	v_mfma_f32_16x16x32_bf16 v[106:109], v[154:157], v[212:215], v[106:109]
	v_mfma_f32_16x16x32_bf16 v[102:105], v[146:149], v[248:251], v[102:105]
	v_mfma_f32_16x16x32_bf16 v[98:101], v[154:157], v[248:251], v[98:101]
	v_mfma_f32_16x16x32_bf16 v[62:65], v[158:161], v[180:183], v[62:65]
	v_mfma_f32_16x16x32_bf16 v[58:61], v[166:169], v[180:183], v[58:61]
	v_mfma_f32_16x16x32_bf16 v[54:57], v[158:161], v[200:203], v[54:57]
	v_mfma_f32_16x16x32_bf16 v[50:53], v[166:169], v[200:203], v[50:53]
	v_mfma_f32_16x16x32_bf16 v[46:49], v[158:161], v[208:211], v[46:49]
	v_mfma_f32_16x16x32_bf16 v[42:45], v[166:169], v[208:211], v[42:45]
	v_mfma_f32_16x16x32_bf16 v[38:41], v[158:161], v[216:219], v[38:41]
	v_mfma_f32_16x16x32_bf16 v[34:37], v[166:169], v[216:219], v[34:37]
	v_mfma_f32_16x16x32_bf16 v[62:65], v[162:165], v[196:199], v[62:65]
	v_mfma_f32_16x16x32_bf16 v[58:61], v[170:173], v[196:199], v[58:61]
	v_mfma_f32_16x16x32_bf16 v[54:57], v[162:165], v[204:207], v[54:57]
	v_mfma_f32_16x16x32_bf16 v[50:53], v[170:173], v[204:207], v[50:53]
	v_mfma_f32_16x16x32_bf16 v[46:49], v[162:165], v[212:215], v[46:49]
	v_mfma_f32_16x16x32_bf16 v[42:45], v[170:173], v[212:215], v[42:45]
	v_mfma_f32_16x16x32_bf16 v[38:41], v[162:165], v[248:251], v[38:41]
	v_mfma_f32_16x16x32_bf16 v[34:37], v[170:173], v[248:251], v[34:37]
	s_setprio 0
	s_barrier
	s_add_i32 s20, s72, s16
	v_lshl_add_u64 v[174:175], s[40:41], 0, v[132:133]
	s_mov_b32 m0, s20
	ds_read_b128 v[180:183], v179 offset:16384
	ds_read_b128 v[196:199], v179 offset:17408
	ds_read_b128 v[200:203], v179 offset:18432
	ds_read_b128 v[204:207], v179 offset:19456
	ds_read_b128 v[208:211], v179 offset:20480
	ds_read_b128 v[212:215], v179 offset:21504
	ds_read_b128 v[216:219], v179 offset:22528
	ds_read_b128 v[248:251], v179 offset:23552
	global_load_lds_dwordx4 v[174:175], off
	s_add_i32 m0, s20, 0x2000
	s_add_u32 s20, s40, 0x18000
	v_lshl_add_u64 v[184:185], s[40:41], 0, v[136:137]
	s_addc_u32 s21, s41, 0
	s_add_i32 s72, s76, s16
	global_load_lds_dwordx4 v[184:185], off
	v_lshl_add_u64 v[220:221], s[20:21], 0, v[132:133]
	s_mov_b32 m0, s72
	v_lshl_add_u64 v[232:233], s[42:43], 0, v[134:135]
	global_load_lds_dwordx4 v[220:221], off
	v_lshl_add_u64 v[220:221], s[20:21], 0, v[136:137]
	s_add_i32 m0, s72, 0x2000
	s_nop 0
	global_load_lds_dwordx4 v[220:221], off
	v_lshl_add_u64 v[220:221], s[42:43], 0, v[130:131]
	s_mov_b32 m0, s17
	s_nop 0
	global_load_lds_dwordx4 v[220:221], off
	s_mov_b32 m0, s44
	s_nop 0
	global_load_lds_dwordx4 v[232:233], off
	s_waitcnt vmcnt(8)
	s_waitcnt lgkmcnt(0)
	s_barrier
; #define PG8_STAGE(bufoff, gbase, voff) do { _Pragma("unroll") for (int _i = 0; _i < 2; ++_i) \
;         __builtin_amdgcn_global_load_lds((const unsigned*)((const char*)(gbase) + (voff)[_i]), (LAS unsigned*)(lds + (bufoff) + ldsw + _i * 8192), 16, 0, 0); } while (0)
; #define PG8_LDA(dst, b, h) do { _Pragma("unroll") for (int m = 0; m < 4; ++m) _Pragma("unroll") for (int k = 0; k < 2; ++k) dst[m][k] = *(const LAS bf16x8*)(lds + PG8_SA(b, h) + aoff + m * 2048 + k * 1024); } while (0)
; #define PG8_LDB(dst, b, h) do { _Pragma("unroll") for (int n = 0; n < 2; ++n) _Pragma("unroll") for (int k = 0; k < 2; ++k) dst[n][k] = *(const LAS bf16x8*)(lds + PG8_SB(b, h) + boff + n * 2048 + k * 1024); } while (0)
; #define PG8_MMA(ai, bj, At, Bt) do { __builtin_amdgcn_s_setprio(1); _Pragma("unroll") for (int m = 0; m < 4; ++m) _Pragma("unroll") for (int n = 0; n < 2; ++n) _Pragma("unroll") for (int k = 0; k < 2; ++k) \
;         acc[ai][bj][m][n] = __builtin_amdgcn_mfma_f32_16x16x32_bf16(Bt[n][k], At[m][k], acc[ai][bj][m][n], 0, 0, 0); __builtin_amdgcn_s_setprio(0); } while (0)
; #define PG8_WAIT_V(n) asm volatile("s_waitcnt vmcnt(" #n ")" ::: "memory")
; #define PG8_WAIT_L(n) asm volatile("s_waitcnt lgkmcnt(" #n ")" ::: "memory")
; #define PG8_BAR __builtin_amdgcn_s_barrier()
; #define PG8_SCHED __builtin_amdgcn_sched_barrier(0)
; template <class Epi, class Sched>
; __device__ __forceinline__ void gemm_phase(LAS unsigned char* lds, const Gemm g, const Sched& S, const Epi& E) {
;     ...
;             PG8_WAIT_V(8); PG8_WAIT_L(0); PG8_BAR; PG8_MMA(1, 0, At, B0); PG8_MMA(1, 1, At, B1); PG8_BAR; PG8_SCHED;
;             PG8_LDB(B0, 1, 0); PG8_LDB(B1, 1, 1); PG8_SCHED; PG8_LDA(At, 1, 0); PG8_STAGE(PG8_SA(0, 1), a2 + hstepA, voffA);
;             PG8_WAIT_V(8); PG8_WAIT_L(0); PG8_BAR; PG8_MMA(0, 0, At, B0); PG8_MMA(0, 1, At, B1); PG8_BAR; PG8_SCHED;
	s_setprio 1
	s_waitcnt lgkmcnt(0)
	v_mfma_f32_16x16x32_bf16 v[94:97], v[142:145], v[180:183], v[94:97]
	v_mfma_f32_16x16x32_bf16 v[90:93], v[150:153], v[180:183], v[90:93]
	v_mfma_f32_16x16x32_bf16 v[86:89], v[142:145], v[200:203], v[86:89]
	v_mfma_f32_16x16x32_bf16 v[82:85], v[150:153], v[200:203], v[82:85]
	v_mfma_f32_16x16x32_bf16 v[78:81], v[142:145], v[208:211], v[78:81]
	v_mfma_f32_16x16x32_bf16 v[74:77], v[150:153], v[208:211], v[74:77]
	v_mfma_f32_16x16x32_bf16 v[70:73], v[142:145], v[216:219], v[70:73]
	v_mfma_f32_16x16x32_bf16 v[66:69], v[150:153], v[216:219], v[66:69]
	v_mfma_f32_16x16x32_bf16 v[94:97], v[146:149], v[196:199], v[94:97]
	v_mfma_f32_16x16x32_bf16 v[90:93], v[154:157], v[196:199], v[90:93]
	v_mfma_f32_16x16x32_bf16 v[86:89], v[146:149], v[204:207], v[86:89]
	v_mfma_f32_16x16x32_bf16 v[82:85], v[154:157], v[204:207], v[82:85]
	v_mfma_f32_16x16x32_bf16 v[78:81], v[146:149], v[212:215], v[78:81]
	v_mfma_f32_16x16x32_bf16 v[74:77], v[154:157], v[212:215], v[74:77]
	v_mfma_f32_16x16x32_bf16 v[70:73], v[146:149], v[248:251], v[70:73]
	v_mfma_f32_16x16x32_bf16 v[66:69], v[154:157], v[248:251], v[66:69]
	v_mfma_f32_16x16x32_bf16 v[30:33], v[158:161], v[180:183], v[30:33]
	v_mfma_f32_16x16x32_bf16 v[26:29], v[166:169], v[180:183], v[26:29]
	v_mfma_f32_16x16x32_bf16 v[22:25], v[158:161], v[200:203], v[22:25]
	v_mfma_f32_16x16x32_bf16 v[18:21], v[166:169], v[200:203], v[18:21]
	v_mfma_f32_16x16x32_bf16 v[14:17], v[158:161], v[208:211], v[14:17]
	v_mfma_f32_16x16x32_bf16 v[10:13], v[166:169], v[208:211], v[10:13]
	v_mfma_f32_16x16x32_bf16 v[6:9], v[158:161], v[216:219], v[6:9]
	v_mfma_f32_16x16x32_bf16 v[2:5], v[166:169], v[216:219], v[2:5]
	v_mfma_f32_16x16x32_bf16 v[30:33], v[162:165], v[196:199], v[30:33]
	v_mfma_f32_16x16x32_bf16 v[26:29], v[170:173], v[196:199], v[26:29]
	v_mfma_f32_16x16x32_bf16 v[22:25], v[162:165], v[204:207], v[22:25]
	v_mfma_f32_16x16x32_bf16 v[18:21], v[170:173], v[204:207], v[18:21]
	v_mfma_f32_16x16x32_bf16 v[14:17], v[162:165], v[212:215], v[14:17]
	v_mfma_f32_16x16x32_bf16 v[10:13], v[170:173], v[212:215], v[10:13]
	v_mfma_f32_16x16x32_bf16 v[6:9], v[162:165], v[248:251], v[6:9]
	v_mfma_f32_16x16x32_bf16 v[2:5], v[170:173], v[248:251], v[2:5]
	s_setprio 0
	s_barrier
	s_add_i32 s72, 0, 0x18000
	v_add_u32_e32 v0, s72, v178
	s_add_i32 s76, 0, 0x1c000
	ds_read_b128 v[142:145], v0
	ds_read_b128 v[146:149], v0 offset:1024
	ds_read_b128 v[150:153], v0 offset:2048
	ds_read_b128 v[154:157], v0 offset:3072
	v_add_u32_e32 v0, s76, v178
	ds_read_b128 v[158:161], v0
	ds_read_b128 v[162:165], v0 offset:1024
	ds_read_b128 v[166:169], v0 offset:2048
	ds_read_b128 v[170:173], v0 offset:3072
	s_add_u32 s20, s42, 0x50000
	s_addc_u32 s21, s43, 0
	s_mov_b32 m0, s45
	v_lshl_add_u64 v[234:235], s[20:21], 0, v[130:131]
	ds_read_b128 v[180:183], v179 offset:32768
	ds_read_b128 v[196:199], v179 offset:33792
	ds_read_b128 v[200:203], v179 offset:34816
	ds_read_b128 v[204:207], v179 offset:35840
	ds_read_b128 v[208:211], v179 offset:36864
	ds_read_b128 v[212:215], v179 offset:37888
	ds_read_b128 v[216:219], v179 offset:38912
	ds_read_b128 v[248:251], v179 offset:39936
	global_load_lds_dwordx4 v[234:235], off
	v_lshl_add_u64 v[234:235], s[20:21], 0, v[134:135]
	s_mov_b32 m0, s46
	s_nop 0
	global_load_lds_dwordx4 v[234:235], off
	s_waitcnt vmcnt(8)
	s_waitcnt lgkmcnt(0)
	s_barrier
	s_setprio 1
	s_waitcnt lgkmcnt(0)
	v_mfma_f32_16x16x32_bf16 v[126:129], v[142:145], v[180:183], v[126:129]
	v_mfma_f32_16x16x32_bf16 v[122:125], v[150:153], v[180:183], v[122:125]
	v_mfma_f32_16x16x32_bf16 v[118:121], v[142:145], v[200:203], v[118:121]
	v_mfma_f32_16x16x32_bf16 v[114:117], v[150:153], v[200:203], v[114:117]
	v_mfma_f32_16x16x32_bf16 v[110:113], v[142:145], v[208:211], v[110:113]
	v_mfma_f32_16x16x32_bf16 v[106:109], v[150:153], v[208:211], v[106:109]
	v_mfma_f32_16x16x32_bf16 v[102:105], v[142:145], v[216:219], v[102:105]
	v_mfma_f32_16x16x32_bf16 v[98:101], v[150:153], v[216:219], v[98:101]
	v_mfma_f32_16x16x32_bf16 v[126:129], v[146:149], v[196:199], v[126:129]
	v_mfma_f32_16x16x32_bf16 v[122:125], v[154:157], v[196:199], v[122:125]
	v_mfma_f32_16x16x32_bf16 v[118:121], v[146:149], v[204:207], v[118:121]
	v_mfma_f32_16x16x32_bf16 v[114:117], v[154:157], v[204:207], v[114:117]
	v_mfma_f32_16x16x32_bf16 v[110:113], v[146:149], v[212:215], v[110:113]
	v_mfma_f32_16x16x32_bf16 v[106:109], v[154:157], v[212:215], v[106:109]
	v_mfma_f32_16x16x32_bf16 v[102:105], v[146:149], v[248:251], v[102:105]
	v_mfma_f32_16x16x32_bf16 v[98:101], v[154:157], v[248:251], v[98:101]
	v_mfma_f32_16x16x32_bf16 v[62:65], v[158:161], v[180:183], v[62:65]
	v_mfma_f32_16x16x32_bf16 v[58:61], v[166:169], v[180:183], v[58:61]
	v_mfma_f32_16x16x32_bf16 v[54:57], v[158:161], v[200:203], v[54:57]
	v_mfma_f32_16x16x32_bf16 v[50:53], v[166:169], v[200:203], v[50:53]
	v_mfma_f32_16x16x32_bf16 v[46:49], v[158:161], v[208:211], v[46:49]
	v_mfma_f32_16x16x32_bf16 v[42:45], v[166:169], v[208:211], v[42:45]
	v_mfma_f32_16x16x32_bf16 v[38:41], v[158:161], v[216:219], v[38:41]
	v_mfma_f32_16x16x32_bf16 v[34:37], v[166:169], v[216:219], v[34:37]
	v_mfma_f32_16x16x32_bf16 v[62:65], v[162:165], v[196:199], v[62:65]
	v_mfma_f32_16x16x32_bf16 v[58:61], v[170:173], v[196:199], v[58:61]
	v_mfma_f32_16x16x32_bf16 v[54:57], v[162:165], v[204:207], v[54:57]
	v_mfma_f32_16x16x32_bf16 v[50:53], v[170:173], v[204:207], v[50:53]
	v_mfma_f32_16x16x32_bf16 v[46:49], v[162:165], v[212:215], v[46:49]
	v_mfma_f32_16x16x32_bf16 v[42:45], v[170:173], v[212:215], v[42:45]
	v_mfma_f32_16x16x32_bf16 v[38:41], v[162:165], v[248:251], v[38:41]
	v_mfma_f32_16x16x32_bf16 v[34:37], v[170:173], v[248:251], v[34:37]
	s_setprio 0
	s_barrier
; #define PG8_STAGE(bufoff, gbase, voff) do { _Pragma("unroll") for (int _i = 0; _i < 2; ++_i) \
;         __builtin_amdgcn_global_load_lds((const unsigned*)((const char*)(gbase) + (voff)[_i]), (LAS unsigned*)(lds + (bufoff) + ldsw + _i * 8192), 16, 0, 0); } while (0)
; #define PG8_LDA(dst, b, h) do { _Pragma("unroll") for (int m = 0; m < 4; ++m) _Pragma("unroll") for (int k = 0; k < 2; ++k) dst[m][k] = *(const LAS bf16x8*)(lds + PG8_SA(b, h) + aoff + m * 2048 + k * 1024); } while (0)
; #define PG8_MMA(ai, bj, At, Bt) do { __builtin_amdgcn_s_setprio(1); _Pragma("unroll") for (int m = 0; m < 4; ++m) _Pragma("unroll") for (int n = 0; n < 2; ++n) _Pragma("unroll") for (int k = 0; k < 2; ++k) \
;         acc[ai][bj][m][n] = __builtin_amdgcn_mfma_f32_16x16x32_bf16(Bt[n][k], At[m][k], acc[ai][bj][m][n], 0, 0, 0); __builtin_amdgcn_s_setprio(0); } while (0)
; #define PG8_WAIT_V(n) asm volatile("s_waitcnt vmcnt(" #n ")" ::: "memory")
; #define PG8_WAIT_L(n) asm volatile("s_waitcnt lgkmcnt(" #n ")" ::: "memory")
; #define PG8_BAR __builtin_amdgcn_s_barrier()
; #define PG8_SCHED __builtin_amdgcn_sched_barrier(0)
; template <class Epi, class Sched>
; __device__ __forceinline__ void gemm_phase(LAS unsigned char* lds, const Gemm g, const Sched& S, const Epi& E) {
;     ...
;         for (int t = 0; t < nt; t += 2) {
;             if constexpr (Epi::HOOKS) { if (cur.kind == 3 && (t == 4 || t == 12)) { int fr_ = fr, fq_ = fq; asm volatile("" : "+v"(fr_), "+v"(fq_)); E.hook(acc, cur, t == 4 ? 0 : 1, wr, wc, fr_, fq_); } }
;             const bool last = (t == nt - 2);
;             const char* a1 = cA + (size_t)(t + 1) * kstep;
;             const char* a2 = last ? nA : cA + (size_t)(t + 2) * kstep; const char* b2 = last ? nB : cB + (size_t)(t + 2) * kstep;
;             const char* a3 = a2 + kstep; const char* b3 = b2 + kstep;
;     ...
;             PG8_LDA(At, 1, 1); PG8_STAGE(PG8_SB(1, 0), b3, voffB); PG8_STAGE(PG8_SB(1, 1), b3 + hstepB, voffB); PG8_STAGE(PG8_SA(1, 0), a3, voffA);
;             PG8_WAIT_V(8); PG8_WAIT_L(0); PG8_BAR; PG8_MMA(1, 0, At, B0); PG8_MMA(1, 1, At, B1); PG8_BAR; PG8_SCHED;
	s_add_i32 s20, s72, s16
	v_lshl_add_u64 v[174:175], v[174:175], 0, s[26:27]
	s_mov_b32 m0, s20
	ds_read_b128 v[180:183], v179 offset:49152
	ds_read_b128 v[196:199], v179 offset:50176
	ds_read_b128 v[200:203], v179 offset:51200
	ds_read_b128 v[204:207], v179 offset:52224
	ds_read_b128 v[208:211], v179 offset:53248
	ds_read_b128 v[212:215], v179 offset:54272
	ds_read_b128 v[216:219], v179 offset:55296
	ds_read_b128 v[248:251], v179 offset:56320
	global_load_lds_dwordx4 v[174:175], off
	s_add_i32 m0, s20, 0x2000
	s_add_u32 s20, s40, 0x18080
	v_lshl_add_u64 v[174:175], v[184:185], 0, s[26:27]
	s_addc_u32 s21, s41, 0
	s_add_i32 s40, s76, s16
	global_load_lds_dwordx4 v[174:175], off
	v_lshl_add_u64 v[174:175], s[20:21], 0, v[132:133]
	s_mov_b32 m0, s40
	s_nop 0
	global_load_lds_dwordx4 v[174:175], off
	v_lshl_add_u64 v[174:175], s[20:21], 0, v[136:137]
	s_add_i32 m0, s40, 0x2000
	s_nop 0
	global_load_lds_dwordx4 v[174:175], off
	v_lshl_add_u64 v[174:175], v[220:221], 0, s[26:27]
	s_mov_b32 m0, s71
	s_nop 0
	global_load_lds_dwordx4 v[174:175], off
	v_lshl_add_u64 v[174:175], v[232:233], 0, s[26:27]
	s_mov_b32 m0, s74
	s_nop 0
	global_load_lds_dwordx4 v[174:175], off
	s_waitcnt vmcnt(8)
	s_waitcnt lgkmcnt(0)
	s_barrier
	s_setprio 1
	s_waitcnt lgkmcnt(0)
	v_mfma_f32_16x16x32_bf16 v[94:97], v[142:145], v[180:183], v[94:97]
	v_mfma_f32_16x16x32_bf16 v[90:93], v[150:153], v[180:183], v[90:93]
	v_mfma_f32_16x16x32_bf16 v[86:89], v[142:145], v[200:203], v[86:89]
	v_mfma_f32_16x16x32_bf16 v[82:85], v[150:153], v[200:203], v[82:85]
	v_mfma_f32_16x16x32_bf16 v[78:81], v[142:145], v[208:211], v[78:81]
	v_mfma_f32_16x16x32_bf16 v[74:77], v[150:153], v[208:211], v[74:77]
	v_mfma_f32_16x16x32_bf16 v[70:73], v[142:145], v[216:219], v[70:73]
	v_mfma_f32_16x16x32_bf16 v[66:69], v[150:153], v[216:219], v[66:69]
	v_mfma_f32_16x16x32_bf16 v[94:97], v[146:149], v[196:199], v[94:97]
	v_mfma_f32_16x16x32_bf16 v[90:93], v[154:157], v[196:199], v[90:93]
	v_mfma_f32_16x16x32_bf16 v[86:89], v[146:149], v[204:207], v[86:89]
	v_mfma_f32_16x16x32_bf16 v[82:85], v[154:157], v[204:207], v[82:85]
	v_mfma_f32_16x16x32_bf16 v[78:81], v[146:149], v[212:215], v[78:81]
	v_mfma_f32_16x16x32_bf16 v[74:77], v[154:157], v[212:215], v[74:77]
	v_mfma_f32_16x16x32_bf16 v[70:73], v[146:149], v[248:251], v[70:73]
	v_mfma_f32_16x16x32_bf16 v[66:69], v[154:157], v[248:251], v[66:69]
	v_mfma_f32_16x16x32_bf16 v[30:33], v[158:161], v[180:183], v[30:33]
	v_mfma_f32_16x16x32_bf16 v[26:29], v[166:169], v[180:183], v[26:29]
	v_mfma_f32_16x16x32_bf16 v[22:25], v[158:161], v[200:203], v[22:25]
	v_mfma_f32_16x16x32_bf16 v[18:21], v[166:169], v[200:203], v[18:21]
	v_mfma_f32_16x16x32_bf16 v[14:17], v[158:161], v[208:211], v[14:17]
	v_mfma_f32_16x16x32_bf16 v[10:13], v[166:169], v[208:211], v[10:13]
	v_mfma_f32_16x16x32_bf16 v[6:9], v[158:161], v[216:219], v[6:9]
	v_mfma_f32_16x16x32_bf16 v[2:5], v[166:169], v[216:219], v[2:5]
	v_mfma_f32_16x16x32_bf16 v[30:33], v[162:165], v[196:199], v[30:33]
	v_mfma_f32_16x16x32_bf16 v[26:29], v[170:173], v[196:199], v[26:29]
	v_mfma_f32_16x16x32_bf16 v[22:25], v[162:165], v[204:207], v[22:25]
	v_mfma_f32_16x16x32_bf16 v[18:21], v[170:173], v[204:207], v[18:21]
	v_mfma_f32_16x16x32_bf16 v[14:17], v[162:165], v[212:215], v[14:17]
	v_mfma_f32_16x16x32_bf16 v[10:13], v[170:173], v[212:215], v[10:13]
	v_mfma_f32_16x16x32_bf16 v[6:9], v[162:165], v[248:251], v[6:9]
	v_mfma_f32_16x16x32_bf16 v[2:5], v[170:173], v[248:251], v[2:5]
	s_setprio 0
	s_add_u32 s68, s68, 0x100
	s_addc_u32 s62, s62, 0
	s_cmp_ge_i32 s63, s48
	s_mov_b64 s[20:21], s[0:1]
	s_mov_b32 s40, s63
	s_cbranch_scc1 .Lrot_exit_4
	s_add_i32 s63, s40, 2
	s_add_u32 s0, s20, 0x100
	s_addc_u32 s1, s21, 0
	s_add_i32 s72, 0, 0x10000
	s_cmp_eq_u32 s77, s40
	s_cselect_b32 s43, s91, s1
	s_cselect_b32 s42, s90, s0
	s_branch .Lrot_head_4

; template <class Epi, class Sched>
; __device__ __forceinline__ void gemm_phase(LAS unsigned char* lds, const Gemm g, const Sched& S, const Epi& E) {
;     ...
;         for (int t = 0; t < nt; t += 2) {
;             if constexpr (Epi::HOOKS) { if (cur.kind == 3 && (t == 4 || t == 12)) { int fr_ = fr, fq_ = fq; asm volatile("" : "+v"(fr_), "+v"(fq_)); E.hook(acc, cur, t == 4 ? 0 : 1, wr, wc, fr_, fq_); } }
;             const bool last = (t == nt - 2);
;             const char* a1 = cA + (size_t)(t + 1) * kstep;
;             const char* a2 = last ? nA : cA + (size_t)(t + 2) * kstep; const char* b2 = last ? nB : cB + (size_t)(t + 2) * kstep;
;             const char* a3 = a2 + kstep; const char* b3 = b2 + kstep;
.LBB0_499:
	s_add_i32 s76, s94, 2
	s_add_u32 s40, s92, 0x100
	s_addc_u32 s41, s93, 0
	s_add_i32 s52, 0, 0x10000
	s_cmp_eq_u32 s71, s94
	s_cselect_b32 vcc_hi, s21, s41
	s_cselect_b32 vcc_lo, s20, s40
	s_branch .Lrot_body_5

; #define PG8_STAGE(bufoff, gbase, voff) do { _Pragma("unroll") for (int _i = 0; _i < 2; ++_i) \
;         __builtin_amdgcn_global_load_lds((const unsigned*)((const char*)(gbase) + (voff)[_i]), (LAS unsigned*)(lds + (bufoff) + ldsw + _i * 8192), 16, 0, 0); } while (0)
; #define PG8_LDA(dst, b, h) do { _Pragma("unroll") for (int m = 0; m < 4; ++m) _Pragma("unroll") for (int k = 0; k < 2; ++k) dst[m][k] = *(const LAS bf16x8*)(lds + PG8_SA(b, h) + aoff + m * 2048 + k * 1024); } while (0)
; #define PG8_LDB(dst, b, h) do { _Pragma("unroll") for (int n = 0; n < 2; ++n) _Pragma("unroll") for (int k = 0; k < 2; ++k) dst[n][k] = *(const LAS bf16x8*)(lds + PG8_SB(b, h) + boff + n * 2048 + k * 1024); } while (0)
; #define PG8_MMA(ai, bj, At, Bt) do { __builtin_amdgcn_s_setprio(1); _Pragma("unroll") for (int m = 0; m < 4; ++m) _Pragma("unroll") for (int n = 0; n < 2; ++n) _Pragma("unroll") for (int k = 0; k < 2; ++k) \
;         acc[ai][bj][m][n] = __builtin_amdgcn_mfma_f32_16x16x32_bf16(Bt[n][k], At[m][k], acc[ai][bj][m][n], 0, 0, 0); __builtin_amdgcn_s_setprio(0); } while (0)
; #define PG8_WAIT_V(n) asm volatile("s_waitcnt vmcnt(" #n ")" ::: "memory")
; #define PG8_WAIT_L(n) asm volatile("s_waitcnt lgkmcnt(" #n ")" ::: "memory")
; #define PG8_BAR __builtin_amdgcn_s_barrier()
; #define PG8_SCHED __builtin_amdgcn_sched_barrier(0)
; template <class Epi, class Sched>
; __device__ __forceinline__ void gemm_phase(LAS unsigned char* lds, const Gemm g, const Sched& S, const Epi& E) {
;     ...
;             const char* a1 = cA + (size_t)(t + 1) * kstep;
;             const char* a2 = last ? nA : cA + (size_t)(t + 2) * kstep; const char* b2 = last ? nB : cB + (size_t)(t + 2) * kstep;
;             const char* a3 = a2 + kstep; const char* b3 = b2 + kstep;
;             PG8_LDB(B0, 0, 0); PG8_LDB(B1, 0, 1); PG8_SCHED; PG8_LDA(At, 0, 0); PG8_STAGE(PG8_SA(1, 1), a1 + hstepA, voffA);
;             PG8_WAIT_V(8); PG8_WAIT_L(0); PG8_BAR; PG8_MMA(0, 0, At, B0); PG8_MMA(0, 1, At, B1); PG8_BAR; PG8_SCHED;
;             PG8_LDA(At, 0, 1); PG8_STAGE(PG8_SB(0, 0), b2, voffB); PG8_STAGE(PG8_SB(0, 1), b2 + hstepB, voffB); PG8_STAGE(PG8_SA(0, 0), a2, voffA);
;             PG8_WAIT_V(8); PG8_WAIT_L(0); PG8_BAR; PG8_MMA(1, 0, At, B0); PG8_MMA(1, 1, At, B1); PG8_BAR; PG8_SCHED;
.Lrot_body_5:
	v_add_u32_e32 v0, s52, v169
	s_cselect_b32 s95, s91, s63
	s_cselect_b32 s94, s68, s62
	s_add_i32 s53, 0, 0x14000
	ds_read_b128 v[130:133], v0
	ds_read_b128 v[134:137], v0 offset:1024
	ds_read_b128 v[150:153], v0 offset:2048
	ds_read_b128 v[154:157], v0 offset:3072
	v_add_u32_e32 v0, s53, v169
	ds_read_b128 v[158:161], v0
	ds_read_b128 v[174:177], v0 offset:1024
	ds_read_b128 v[178:181], v0 offset:2048
	ds_read_b128 v[182:185], v0 offset:3072
	v_lshl_add_u64 v[164:165], s[92:93], 0, v[148:149]
	s_add_i32 m0, s19, 0xc000
	ds_read_b128 v[196:199], v173
	ds_read_b128 v[200:203], v173 offset:1024
	ds_read_b128 v[204:207], v173 offset:2048
	ds_read_b128 v[208:211], v173 offset:3072
	ds_read_b128 v[212:215], v173 offset:4096
	ds_read_b128 v[216:219], v173 offset:5120
	ds_read_b128 v[248:251], v173 offset:6144
	ds_read_b128 v[232:235], v173 offset:7168
	global_load_lds_dwordx4 v[164:165], off
	v_lshl_add_u64 v[164:165], s[92:93], 0, v[146:147]
	s_add_i32 m0, s19, 0xe000
	s_nop 0
	global_load_lds_dwordx4 v[164:165], off
	s_waitcnt vmcnt(8)
	s_waitcnt lgkmcnt(0)
	s_barrier
	s_setprio 1
	s_waitcnt lgkmcnt(0)
	v_mfma_f32_16x16x32_bf16 v[126:129], v[130:133], v[196:199], v[126:129]
	v_mfma_f32_16x16x32_bf16 v[122:125], v[150:153], v[196:199], v[122:125]
	v_mfma_f32_16x16x32_bf16 v[110:113], v[130:133], v[204:207], v[110:113]
	v_mfma_f32_16x16x32_bf16 v[106:109], v[150:153], v[204:207], v[106:109]
	v_mfma_f32_16x16x32_bf16 v[94:97], v[130:133], v[212:215], v[94:97]
	v_mfma_f32_16x16x32_bf16 v[90:93], v[150:153], v[212:215], v[90:93]
	v_mfma_f32_16x16x32_bf16 v[78:81], v[130:133], v[248:251], v[78:81]
	v_mfma_f32_16x16x32_bf16 v[74:77], v[150:153], v[248:251], v[74:77]
	v_mfma_f32_16x16x32_bf16 v[126:129], v[134:137], v[200:203], v[126:129]
	v_mfma_f32_16x16x32_bf16 v[122:125], v[154:157], v[200:203], v[122:125]
	v_mfma_f32_16x16x32_bf16 v[110:113], v[134:137], v[208:211], v[110:113]
	v_mfma_f32_16x16x32_bf16 v[106:109], v[154:157], v[208:211], v[106:109]
	v_mfma_f32_16x16x32_bf16 v[94:97], v[134:137], v[216:219], v[94:97]
	v_mfma_f32_16x16x32_bf16 v[90:93], v[154:157], v[216:219], v[90:93]
	v_mfma_f32_16x16x32_bf16 v[78:81], v[134:137], v[232:235], v[78:81]
	v_mfma_f32_16x16x32_bf16 v[74:77], v[154:157], v[232:235], v[74:77]
	v_mfma_f32_16x16x32_bf16 v[118:121], v[158:161], v[196:199], v[118:121]
	v_mfma_f32_16x16x32_bf16 v[114:117], v[178:181], v[196:199], v[114:117]
	v_mfma_f32_16x16x32_bf16 v[102:105], v[158:161], v[204:207], v[102:105]
	v_mfma_f32_16x16x32_bf16 v[98:101], v[178:181], v[204:207], v[98:101]
	v_mfma_f32_16x16x32_bf16 v[86:89], v[158:161], v[212:215], v[86:89]
	v_mfma_f32_16x16x32_bf16 v[82:85], v[178:181], v[212:215], v[82:85]
	v_mfma_f32_16x16x32_bf16 v[70:73], v[158:161], v[248:251], v[70:73]
	v_mfma_f32_16x16x32_bf16 v[66:69], v[178:181], v[248:251], v[66:69]
	v_mfma_f32_16x16x32_bf16 v[118:121], v[174:177], v[200:203], v[118:121]
	v_mfma_f32_16x16x32_bf16 v[114:117], v[182:185], v[200:203], v[114:117]
	v_mfma_f32_16x16x32_bf16 v[102:105], v[174:177], v[208:211], v[102:105]
	v_mfma_f32_16x16x32_bf16 v[98:101], v[182:185], v[208:211], v[98:101]
	v_mfma_f32_16x16x32_bf16 v[86:89], v[174:177], v[216:219], v[86:89]
	v_mfma_f32_16x16x32_bf16 v[82:85], v[182:185], v[216:219], v[82:85]
	v_mfma_f32_16x16x32_bf16 v[70:73], v[174:177], v[232:235], v[70:73]
	v_mfma_f32_16x16x32_bf16 v[66:69], v[182:185], v[232:235], v[66:69]
	s_setprio 0
	s_barrier
	s_add_i32 s52, s52, s17
	v_lshl_add_u64 v[164:165], s[94:95], 0, v[140:141]
	s_mov_b32 m0, s52
	ds_read_b128 v[196:199], v173 offset:16384
	ds_read_b128 v[200:203], v173 offset:17408
	ds_read_b128 v[204:207], v173 offset:18432
	ds_read_b128 v[208:211], v173 offset:19456
	ds_read_b128 v[212:215], v173 offset:20480
	ds_read_b128 v[216:219], v173 offset:21504
	ds_read_b128 v[232:235], v173 offset:22528
	ds_read_b128 v[248:251], v173 offset:23552
	global_load_lds_dwordx4 v[164:165], off
	s_add_i32 m0, s52, 0x2000
	s_add_u32 s92, s94, 0x10000
	v_lshl_add_u64 v[170:171], s[94:95], 0, v[144:145]
	s_addc_u32 s93, s95, 0
	s_add_i32 s52, s53, s17
	global_load_lds_dwordx4 v[170:171], off
	v_lshl_add_u64 v[220:221], s[92:93], 0, v[140:141]
	s_mov_b32 m0, s52
	v_lshl_add_u64 v[246:247], vcc, 0, v[142:143]
	global_load_lds_dwordx4 v[220:221], off
	v_lshl_add_u64 v[220:221], s[92:93], 0, v[144:145]
	s_add_i32 m0, s52, 0x2000
	s_nop 0
	global_load_lds_dwordx4 v[220:221], off
	v_lshl_add_u64 v[220:221], vcc, 0, v[138:139]
	s_mov_b32 m0, s19
	s_nop 0
	global_load_lds_dwordx4 v[220:221], off
	s_mov_b32 m0, s44
	s_nop 0
	global_load_lds_dwordx4 v[246:247], off
	s_waitcnt vmcnt(8)
	s_waitcnt lgkmcnt(0)
	s_barrier
; #define PG8_STAGE(bufoff, gbase, voff) do { _Pragma("unroll") for (int _i = 0; _i < 2; ++_i) \
;         __builtin_amdgcn_global_load_lds((const unsigned*)((const char*)(gbase) + (voff)[_i]), (LAS unsigned*)(lds + (bufoff) + ldsw + _i * 8192), 16, 0, 0); } while (0)
; #define PG8_LDA(dst, b, h) do { _Pragma("unroll") for (int m = 0; m < 4; ++m) _Pragma("unroll") for (int k = 0; k < 2; ++k) dst[m][k] = *(const LAS bf16x8*)(lds + PG8_SA(b, h) + aoff + m * 2048 + k * 1024); } while (0)
; #define PG8_LDB(dst, b, h) do { _Pragma("unroll") for (int n = 0; n < 2; ++n) _Pragma("unroll") for (int k = 0; k < 2; ++k) dst[n][k] = *(const LAS bf16x8*)(lds + PG8_SB(b, h) + boff + n * 2048 + k * 1024); } while (0)
; #define PG8_MMA(ai, bj, At, Bt) do { __builtin_amdgcn_s_setprio(1); _Pragma("unroll") for (int m = 0; m < 4; ++m) _Pragma("unroll") for (int n = 0; n < 2; ++n) _Pragma("unroll") for (int k = 0; k < 2; ++k) \
;         acc[ai][bj][m][n] = __builtin_amdgcn_mfma_f32_16x16x32_bf16(Bt[n][k], At[m][k], acc[ai][bj][m][n], 0, 0, 0); __builtin_amdgcn_s_setprio(0); } while (0)
; #define PG8_WAIT_V(n) asm volatile("s_waitcnt vmcnt(" #n ")" ::: "memory")
; #define PG8_WAIT_L(n) asm volatile("s_waitcnt lgkmcnt(" #n ")" ::: "memory")
; #define PG8_BAR __builtin_amdgcn_s_barrier()
; #define PG8_SCHED __builtin_amdgcn_sched_barrier(0)
; template <class Epi, class Sched>
; __device__ __forceinline__ void gemm_phase(LAS unsigned char* lds, const Gemm g, const Sched& S, const Epi& E) {
;     ...
;             PG8_WAIT_V(8); PG8_WAIT_L(0); PG8_BAR; PG8_MMA(1, 0, At, B0); PG8_MMA(1, 1, At, B1); PG8_BAR; PG8_SCHED;
;             PG8_LDB(B0, 1, 0); PG8_LDB(B1, 1, 1); PG8_SCHED; PG8_LDA(At, 1, 0); PG8_STAGE(PG8_SA(0, 1), a2 + hstepA, voffA);
;             PG8_WAIT_V(8); PG8_WAIT_L(0); PG8_BAR; PG8_MMA(0, 0, At, B0); PG8_MMA(0, 1, At, B1); PG8_BAR; PG8_SCHED;
	s_setprio 1
	s_waitcnt lgkmcnt(0)
	v_mfma_f32_16x16x32_bf16 v[62:65], v[130:133], v[196:199], v[62:65]
	v_mfma_f32_16x16x32_bf16 v[58:61], v[150:153], v[196:199], v[58:61]
	v_mfma_f32_16x16x32_bf16 v[46:49], v[130:133], v[204:207], v[46:49]
	v_mfma_f32_16x16x32_bf16 v[42:45], v[150:153], v[204:207], v[42:45]
	v_mfma_f32_16x16x32_bf16 v[30:33], v[130:133], v[212:215], v[30:33]
	v_mfma_f32_16x16x32_bf16 v[26:29], v[150:153], v[212:215], v[26:29]
	v_mfma_f32_16x16x32_bf16 v[14:17], v[130:133], v[232:235], v[14:17]
	v_mfma_f32_16x16x32_bf16 v[10:13], v[150:153], v[232:235], v[10:13]
	v_mfma_f32_16x16x32_bf16 v[62:65], v[134:137], v[200:203], v[62:65]
	v_mfma_f32_16x16x32_bf16 v[58:61], v[154:157], v[200:203], v[58:61]
	v_mfma_f32_16x16x32_bf16 v[46:49], v[134:137], v[208:211], v[46:49]
	v_mfma_f32_16x16x32_bf16 v[42:45], v[154:157], v[208:211], v[42:45]
	v_mfma_f32_16x16x32_bf16 v[30:33], v[134:137], v[216:219], v[30:33]
	v_mfma_f32_16x16x32_bf16 v[26:29], v[154:157], v[216:219], v[26:29]
	v_mfma_f32_16x16x32_bf16 v[14:17], v[134:137], v[248:251], v[14:17]
	v_mfma_f32_16x16x32_bf16 v[10:13], v[154:157], v[248:251], v[10:13]
	v_mfma_f32_16x16x32_bf16 v[54:57], v[158:161], v[196:199], v[54:57]
	v_mfma_f32_16x16x32_bf16 v[50:53], v[178:181], v[196:199], v[50:53]
	v_mfma_f32_16x16x32_bf16 v[38:41], v[158:161], v[204:207], v[38:41]
	v_mfma_f32_16x16x32_bf16 v[34:37], v[178:181], v[204:207], v[34:37]
	v_mfma_f32_16x16x32_bf16 v[22:25], v[158:161], v[212:215], v[22:25]
	v_mfma_f32_16x16x32_bf16 v[18:21], v[178:181], v[212:215], v[18:21]
	v_mfma_f32_16x16x32_bf16 v[6:9], v[158:161], v[232:235], v[6:9]
	v_mfma_f32_16x16x32_bf16 v[2:5], v[178:181], v[232:235], v[2:5]
	v_mfma_f32_16x16x32_bf16 v[54:57], v[174:177], v[200:203], v[54:57]
	v_mfma_f32_16x16x32_bf16 v[50:53], v[182:185], v[200:203], v[50:53]
	v_mfma_f32_16x16x32_bf16 v[38:41], v[174:177], v[208:211], v[38:41]
	v_mfma_f32_16x16x32_bf16 v[34:37], v[182:185], v[208:211], v[34:37]
	v_mfma_f32_16x16x32_bf16 v[22:25], v[174:177], v[216:219], v[22:25]
	v_mfma_f32_16x16x32_bf16 v[18:21], v[182:185], v[216:219], v[18:21]
	v_mfma_f32_16x16x32_bf16 v[6:9], v[174:177], v[248:251], v[6:9]
	v_mfma_f32_16x16x32_bf16 v[2:5], v[182:185], v[248:251], v[2:5]
	s_setprio 0
	s_barrier
	s_add_i32 s52, 0, 0x18000
	v_add_u32_e32 v0, s52, v169
	s_add_i32 s53, 0, 0x1c000
	ds_read_b128 v[130:133], v0
	ds_read_b128 v[134:137], v0 offset:1024
	ds_read_b128 v[150:153], v0 offset:2048
	ds_read_b128 v[154:157], v0 offset:3072
	v_add_u32_e32 v0, s53, v169
	ds_read_b128 v[158:161], v0
	ds_read_b128 v[174:177], v0 offset:1024
	ds_read_b128 v[178:181], v0 offset:2048
	ds_read_b128 v[182:185], v0 offset:3072
	s_add_u32 s92, vcc_lo, 0x50000
	s_addc_u32 s93, vcc_hi, 0
	s_mov_b32 m0, s45
	v_lshl_add_u64 v[236:237], s[92:93], 0, v[138:139]
	ds_read_b128 v[196:199], v173 offset:32768
	ds_read_b128 v[200:203], v173 offset:33792
	ds_read_b128 v[204:207], v173 offset:34816
	ds_read_b128 v[208:211], v173 offset:35840
	ds_read_b128 v[212:215], v173 offset:36864
	ds_read_b128 v[216:219], v173 offset:37888
	ds_read_b128 v[232:235], v173 offset:38912
	ds_read_b128 v[248:251], v173 offset:39936
	global_load_lds_dwordx4 v[236:237], off
	v_lshl_add_u64 v[236:237], s[92:93], 0, v[142:143]
	s_mov_b32 m0, s46
	s_nop 0
	global_load_lds_dwordx4 v[236:237], off
	s_waitcnt vmcnt(8)
	s_waitcnt lgkmcnt(0)
	s_barrier
	s_setprio 1
	s_waitcnt lgkmcnt(0)
	v_mfma_f32_16x16x32_bf16 v[126:129], v[130:133], v[196:199], v[126:129]
	v_mfma_f32_16x16x32_bf16 v[122:125], v[150:153], v[196:199], v[122:125]
	v_mfma_f32_16x16x32_bf16 v[110:113], v[130:133], v[204:207], v[110:113]
	v_mfma_f32_16x16x32_bf16 v[106:109], v[150:153], v[204:207], v[106:109]
	v_mfma_f32_16x16x32_bf16 v[94:97], v[130:133], v[212:215], v[94:97]
	v_mfma_f32_16x16x32_bf16 v[90:93], v[150:153], v[212:215], v[90:93]
	v_mfma_f32_16x16x32_bf16 v[78:81], v[130:133], v[232:235], v[78:81]
	v_mfma_f32_16x16x32_bf16 v[74:77], v[150:153], v[232:235], v[74:77]
	v_mfma_f32_16x16x32_bf16 v[126:129], v[134:137], v[200:203], v[126:129]
	v_mfma_f32_16x16x32_bf16 v[122:125], v[154:157], v[200:203], v[122:125]
	v_mfma_f32_16x16x32_bf16 v[110:113], v[134:137], v[208:211], v[110:113]
	v_mfma_f32_16x16x32_bf16 v[106:109], v[154:157], v[208:211], v[106:109]
	v_mfma_f32_16x16x32_bf16 v[94:97], v[134:137], v[216:219], v[94:97]
	v_mfma_f32_16x16x32_bf16 v[90:93], v[154:157], v[216:219], v[90:93]
	v_mfma_f32_16x16x32_bf16 v[78:81], v[134:137], v[248:251], v[78:81]
	v_mfma_f32_16x16x32_bf16 v[74:77], v[154:157], v[248:251], v[74:77]
	v_mfma_f32_16x16x32_bf16 v[118:121], v[158:161], v[196:199], v[118:121]
	v_mfma_f32_16x16x32_bf16 v[114:117], v[178:181], v[196:199], v[114:117]
	v_mfma_f32_16x16x32_bf16 v[102:105], v[158:161], v[204:207], v[102:105]
	v_mfma_f32_16x16x32_bf16 v[98:101], v[178:181], v[204:207], v[98:101]
	v_mfma_f32_16x16x32_bf16 v[86:89], v[158:161], v[212:215], v[86:89]
	v_mfma_f32_16x16x32_bf16 v[82:85], v[178:181], v[212:215], v[82:85]
	v_mfma_f32_16x16x32_bf16 v[70:73], v[158:161], v[232:235], v[70:73]
	v_mfma_f32_16x16x32_bf16 v[66:69], v[178:181], v[232:235], v[66:69]
	v_mfma_f32_16x16x32_bf16 v[118:121], v[174:177], v[200:203], v[118:121]
	v_mfma_f32_16x16x32_bf16 v[114:117], v[182:185], v[200:203], v[114:117]
	v_mfma_f32_16x16x32_bf16 v[102:105], v[174:177], v[208:211], v[102:105]
	v_mfma_f32_16x16x32_bf16 v[98:101], v[182:185], v[208:211], v[98:101]
	v_mfma_f32_16x16x32_bf16 v[86:89], v[174:177], v[216:219], v[86:89]
	v_mfma_f32_16x16x32_bf16 v[82:85], v[182:185], v[216:219], v[82:85]
	v_mfma_f32_16x16x32_bf16 v[70:73], v[174:177], v[248:251], v[70:73]
	v_mfma_f32_16x16x32_bf16 v[66:69], v[182:185], v[248:251], v[66:69]
	s_setprio 0
	s_barrier
; #define PG8_STAGE(bufoff, gbase, voff) do { _Pragma("unroll") for (int _i = 0; _i < 2; ++_i) \
;         __builtin_amdgcn_global_load_lds((const unsigned*)((const char*)(gbase) + (voff)[_i]), (LAS unsigned*)(lds + (bufoff) + ldsw + _i * 8192), 16, 0, 0); } while (0)
; #define PG8_LDA(dst, b, h) do { _Pragma("unroll") for (int m = 0; m < 4; ++m) _Pragma("unroll") for (int k = 0; k < 2; ++k) dst[m][k] = *(const LAS bf16x8*)(lds + PG8_SA(b, h) + aoff + m * 2048 + k * 1024); } while (0)
; #define PG8_MMA(ai, bj, At, Bt) do { __builtin_amdgcn_s_setprio(1); _Pragma("unroll") for (int m = 0; m < 4; ++m) _Pragma("unroll") for (int n = 0; n < 2; ++n) _Pragma("unroll") for (int k = 0; k < 2; ++k) \
;         acc[ai][bj][m][n] = __builtin_amdgcn_mfma_f32_16x16x32_bf16(Bt[n][k], At[m][k], acc[ai][bj][m][n], 0, 0, 0); __builtin_amdgcn_s_setprio(0); } while (0)
; #define PG8_WAIT_V(n) asm volatile("s_waitcnt vmcnt(" #n ")" ::: "memory")
; #define PG8_WAIT_L(n) asm volatile("s_waitcnt lgkmcnt(" #n ")" ::: "memory")
; #define PG8_BAR __builtin_amdgcn_s_barrier()
; #define PG8_SCHED __builtin_amdgcn_sched_barrier(0)
; template <class Epi, class Sched>
; __device__ __forceinline__ void gemm_phase(LAS unsigned char* lds, const Gemm g, const Sched& S, const Epi& E) {
;     ...
;         for (int t = 0; t < nt; t += 2) {
;             if constexpr (Epi::HOOKS) { if (cur.kind == 3 && (t == 4 || t == 12)) { int fr_ = fr, fq_ = fq; asm volatile("" : "+v"(fr_), "+v"(fq_)); E.hook(acc, cur, t == 4 ? 0 : 1, wr, wc, fr_, fq_); } }
;             const bool last = (t == nt - 2);
;             const char* a1 = cA + (size_t)(t + 1) * kstep;
;             const char* a2 = last ? nA : cA + (size_t)(t + 2) * kstep; const char* b2 = last ? nB : cB + (size_t)(t + 2) * kstep;
;             const char* a3 = a2 + kstep; const char* b3 = b2 + kstep;
;     ...
;             PG8_LDA(At, 1, 1); PG8_STAGE(PG8_SB(1, 0), b3, voffB); PG8_STAGE(PG8_SB(1, 1), b3 + hstepB, voffB); PG8_STAGE(PG8_SA(1, 0), a3, voffA);
;             PG8_WAIT_V(8); PG8_WAIT_L(0); PG8_BAR; PG8_MMA(1, 0, At, B0); PG8_MMA(1, 1, At, B1); PG8_BAR; PG8_SCHED;
	s_add_i32 s52, s52, s17
	v_lshl_add_u64 v[164:165], v[164:165], 0, s[26:27]
	s_mov_b32 m0, s52
	ds_read_b128 v[196:199], v173 offset:49152
	ds_read_b128 v[200:203], v173 offset:50176
	ds_read_b128 v[204:207], v173 offset:51200
	ds_read_b128 v[208:211], v173 offset:52224
	ds_read_b128 v[212:215], v173 offset:53248
	ds_read_b128 v[216:219], v173 offset:54272
	ds_read_b128 v[232:235], v173 offset:55296
	ds_read_b128 v[248:251], v173 offset:56320
	global_load_lds_dwordx4 v[164:165], off
	s_add_i32 m0, s52, 0x2000
	s_add_u32 s92, s94, 0x10080
	v_lshl_add_u64 v[164:165], v[170:171], 0, s[26:27]
	s_addc_u32 s93, s95, 0
	s_add_i32 s52, s53, s17
	global_load_lds_dwordx4 v[164:165], off
	v_lshl_add_u64 v[164:165], s[92:93], 0, v[140:141]
	s_mov_b32 m0, s52
	s_nop 0
	global_load_lds_dwordx4 v[164:165], off
	v_lshl_add_u64 v[164:165], s[92:93], 0, v[144:145]
	s_add_i32 m0, s52, 0x2000
	s_nop 0
	global_load_lds_dwordx4 v[164:165], off
	v_lshl_add_u64 v[164:165], v[220:221], 0, s[26:27]
	s_mov_b32 m0, s67
	s_nop 0
	global_load_lds_dwordx4 v[164:165], off
	v_lshl_add_u64 v[164:165], v[246:247], 0, s[26:27]
	s_mov_b32 m0, s69
	s_nop 0
	global_load_lds_dwordx4 v[164:165], off
	s_waitcnt vmcnt(8)
	s_waitcnt lgkmcnt(0)
	s_barrier
	s_setprio 1
	s_waitcnt lgkmcnt(0)
	v_mfma_f32_16x16x32_bf16 v[62:65], v[130:133], v[196:199], v[62:65]
	v_mfma_f32_16x16x32_bf16 v[58:61], v[150:153], v[196:199], v[58:61]
	v_mfma_f32_16x16x32_bf16 v[46:49], v[130:133], v[204:207], v[46:49]
	v_mfma_f32_16x16x32_bf16 v[42:45], v[150:153], v[204:207], v[42:45]
	v_mfma_f32_16x16x32_bf16 v[30:33], v[130:133], v[212:215], v[30:33]
	v_mfma_f32_16x16x32_bf16 v[26:29], v[150:153], v[212:215], v[26:29]
	v_mfma_f32_16x16x32_bf16 v[14:17], v[130:133], v[232:235], v[14:17]
	v_mfma_f32_16x16x32_bf16 v[10:13], v[150:153], v[232:235], v[10:13]
	v_mfma_f32_16x16x32_bf16 v[62:65], v[134:137], v[200:203], v[62:65]
	v_mfma_f32_16x16x32_bf16 v[58:61], v[154:157], v[200:203], v[58:61]
	v_mfma_f32_16x16x32_bf16 v[46:49], v[134:137], v[208:211], v[46:49]
	v_mfma_f32_16x16x32_bf16 v[42:45], v[154:157], v[208:211], v[42:45]
	v_mfma_f32_16x16x32_bf16 v[30:33], v[134:137], v[216:219], v[30:33]
	v_mfma_f32_16x16x32_bf16 v[26:29], v[154:157], v[216:219], v[26:29]
	v_mfma_f32_16x16x32_bf16 v[14:17], v[134:137], v[248:251], v[14:17]
	v_mfma_f32_16x16x32_bf16 v[10:13], v[154:157], v[248:251], v[10:13]
	v_mfma_f32_16x16x32_bf16 v[54:57], v[158:161], v[196:199], v[54:57]
	v_mfma_f32_16x16x32_bf16 v[50:53], v[178:181], v[196:199], v[50:53]
	v_mfma_f32_16x16x32_bf16 v[38:41], v[158:161], v[204:207], v[38:41]
	v_mfma_f32_16x16x32_bf16 v[34:37], v[178:181], v[204:207], v[34:37]
	v_mfma_f32_16x16x32_bf16 v[22:25], v[158:161], v[212:215], v[22:25]
	v_mfma_f32_16x16x32_bf16 v[18:21], v[178:181], v[212:215], v[18:21]
	v_mfma_f32_16x16x32_bf16 v[6:9], v[158:161], v[232:235], v[6:9]
	v_mfma_f32_16x16x32_bf16 v[2:5], v[178:181], v[232:235], v[2:5]
	v_mfma_f32_16x16x32_bf16 v[54:57], v[174:177], v[200:203], v[54:57]
	v_mfma_f32_16x16x32_bf16 v[50:53], v[182:185], v[200:203], v[50:53]
	v_mfma_f32_16x16x32_bf16 v[38:41], v[174:177], v[208:211], v[38:41]
	v_mfma_f32_16x16x32_bf16 v[34:37], v[182:185], v[208:211], v[34:37]
	v_mfma_f32_16x16x32_bf16 v[22:25], v[174:177], v[216:219], v[22:25]
	v_mfma_f32_16x16x32_bf16 v[18:21], v[182:185], v[216:219], v[18:21]
	v_mfma_f32_16x16x32_bf16 v[6:9], v[174:177], v[248:251], v[6:9]
	v_mfma_f32_16x16x32_bf16 v[2:5], v[182:185], v[248:251], v[2:5]
	s_setprio 0
	s_add_u32 s62, s62, 0x100
	s_addc_u32 s63, s63, 0
	s_cmp_ge_i32 s76, s47
	s_mov_b64 s[92:93], s[40:41]
	s_mov_b32 s94, s76
	s_cbranch_scc1 .Lrot_exit_5
	s_add_i32 s76, s94, 2
	s_add_u32 s40, s92, 0x100
	s_addc_u32 s41, s93, 0
	s_add_i32 s52, 0, 0x10000
	s_cmp_eq_u32 s71, s94
	s_cselect_b32 vcc_hi, s21, s41
	s_cselect_b32 vcc_lo, s20, s40
	s_branch .Lrot_head_5

; template <class Epi, class Sched>
; __device__ __forceinline__ void gemm_phase(LAS unsigned char* lds, const Gemm g, const Sched& S, const Epi& E) {
;     ...
;         for (int t = 0; t < nt; t += 2) {
;             if constexpr (Epi::HOOKS) { if (cur.kind == 3 && (t == 4 || t == 12)) { int fr_ = fr, fq_ = fq; asm volatile("" : "+v"(fr_), "+v"(fq_)); E.hook(acc, cur, t == 4 ? 0 : 1, wr, wc, fr_, fq_); } }
;             const bool last = (t == nt - 2);
;             const char* a1 = cA + (size_t)(t + 1) * kstep;
;             const char* a2 = last ? nA : cA + (size_t)(t + 2) * kstep; const char* b2 = last ? nB : cB + (size_t)(t + 2) * kstep;
;             const char* a3 = a2 + kstep; const char* b3 = b2 + kstep;
.LBB0_526:
	s_add_i32 s62, s0, 2
	s_add_u32 s1, s20, 0xffff0080
	s_addc_u32 s38, s21, -1
	s_add_i32 s39, 0, 0x10000
	s_cmp_eq_u32 s71, s0
	s_cselect_b32 s43, s61, s38
	s_cselect_b32 s42, s96, s1
	s_branch .Lrot_body_6

; #define PG8_STAGE(bufoff, gbase, voff) do { _Pragma("unroll") for (int _i = 0; _i < 2; ++_i) \
;         __builtin_amdgcn_global_load_lds((const unsigned*)((const char*)(gbase) + (voff)[_i]), (LAS unsigned*)(lds + (bufoff) + ldsw + _i * 8192), 16, 0, 0); } while (0)
; #define PG8_LDA(dst, b, h) do { _Pragma("unroll") for (int m = 0; m < 4; ++m) _Pragma("unroll") for (int k = 0; k < 2; ++k) dst[m][k] = *(const LAS bf16x8*)(lds + PG8_SA(b, h) + aoff + m * 2048 + k * 1024); } while (0)
; #define PG8_LDB(dst, b, h) do { _Pragma("unroll") for (int n = 0; n < 2; ++n) _Pragma("unroll") for (int k = 0; k < 2; ++k) dst[n][k] = *(const LAS bf16x8*)(lds + PG8_SB(b, h) + boff + n * 2048 + k * 1024); } while (0)
; #define PG8_MMA(ai, bj, At, Bt) do { __builtin_amdgcn_s_setprio(1); _Pragma("unroll") for (int m = 0; m < 4; ++m) _Pragma("unroll") for (int n = 0; n < 2; ++n) _Pragma("unroll") for (int k = 0; k < 2; ++k) \
;         acc[ai][bj][m][n] = __builtin_amdgcn_mfma_f32_16x16x32_bf16(Bt[n][k], At[m][k], acc[ai][bj][m][n], 0, 0, 0); __builtin_amdgcn_s_setprio(0); } while (0)
; #define PG8_WAIT_V(n) asm volatile("s_waitcnt vmcnt(" #n ")" ::: "memory")
; #define PG8_WAIT_L(n) asm volatile("s_waitcnt lgkmcnt(" #n ")" ::: "memory")
; #define PG8_BAR __builtin_amdgcn_s_barrier()
; #define PG8_SCHED __builtin_amdgcn_sched_barrier(0)
; template <class Epi, class Sched>
; __device__ __forceinline__ void gemm_phase(LAS unsigned char* lds, const Gemm g, const Sched& S, const Epi& E) {
;     ...
;             const char* a1 = cA + (size_t)(t + 1) * kstep;
;             const char* a2 = last ? nA : cA + (size_t)(t + 2) * kstep; const char* b2 = last ? nB : cB + (size_t)(t + 2) * kstep;
;             const char* a3 = a2 + kstep; const char* b3 = b2 + kstep;
;             PG8_LDB(B0, 0, 0); PG8_LDB(B1, 0, 1); PG8_SCHED; PG8_LDA(At, 0, 0); PG8_STAGE(PG8_SA(1, 1), a1 + hstepA, voffA);
;             PG8_WAIT_V(8); PG8_WAIT_L(0); PG8_BAR; PG8_MMA(0, 0, At, B0); PG8_MMA(0, 1, At, B1); PG8_BAR; PG8_SCHED;
;             PG8_LDA(At, 0, 1); PG8_STAGE(PG8_SB(0, 0), b2, voffB); PG8_STAGE(PG8_SB(0, 1), b2 + hstepB, voffB); PG8_STAGE(PG8_SA(0, 0), a2, voffA);
;             PG8_WAIT_V(8); PG8_WAIT_L(0); PG8_BAR; PG8_MMA(1, 0, At, B0); PG8_MMA(1, 1, At, B1); PG8_BAR; PG8_SCHED;
.Lrot_body_6:
	v_add_u32_e32 v0, s39, v201
	s_cselect_b32 s1, s91, vcc_lo
	s_cselect_b32 s0, s90, s97
	s_add_i32 s52, 0, 0x14000
	ds_read_b128 v[130:133], v0
	ds_read_b128 v[134:137], v0 offset:1024
	ds_read_b128 v[138:141], v0 offset:2048
	ds_read_b128 v[142:145], v0 offset:3072
	v_add_u32_e32 v0, s52, v201
	ds_read_b128 v[146:149], v0
	ds_read_b128 v[150:153], v0 offset:1024
	ds_read_b128 v[154:157], v0 offset:2048
	ds_read_b128 v[158:161], v0 offset:3072
	v_lshl_add_u64 v[220:221], s[20:21], 0, v[176:177]
	s_add_i32 m0, s19, 0xc000
	ds_read_b128 v[162:165], v202
	ds_read_b128 v[178:181], v202 offset:1024
	ds_read_b128 v[182:185], v202 offset:2048
	ds_read_b128 v[196:199], v202 offset:3072
	ds_read_b128 v[204:207], v202 offset:4096
	ds_read_b128 v[208:211], v202 offset:5120
	ds_read_b128 v[212:215], v202 offset:6144
	ds_read_b128 v[216:219], v202 offset:7168
	global_load_lds_dwordx4 v[220:221], off
	v_lshl_add_u64 v[220:221], s[20:21], 0, v[174:175]
	s_add_i32 m0, s19, 0xe000
	s_nop 0
	global_load_lds_dwordx4 v[220:221], off
	s_waitcnt vmcnt(8)
	s_waitcnt lgkmcnt(0)
	s_barrier
	s_setprio 1
	s_waitcnt lgkmcnt(0)
	v_mfma_f32_16x16x32_bf16 v[126:129], v[130:133], v[162:165], v[126:129]
	v_mfma_f32_16x16x32_bf16 v[122:125], v[138:141], v[162:165], v[122:125]
	v_mfma_f32_16x16x32_bf16 v[110:113], v[130:133], v[182:185], v[110:113]
	v_mfma_f32_16x16x32_bf16 v[106:109], v[138:141], v[182:185], v[106:109]
	v_mfma_f32_16x16x32_bf16 v[94:97], v[130:133], v[204:207], v[94:97]
	v_mfma_f32_16x16x32_bf16 v[90:93], v[138:141], v[204:207], v[90:93]
	v_mfma_f32_16x16x32_bf16 v[78:81], v[130:133], v[212:215], v[78:81]
	v_mfma_f32_16x16x32_bf16 v[74:77], v[138:141], v[212:215], v[74:77]
	v_mfma_f32_16x16x32_bf16 v[126:129], v[134:137], v[178:181], v[126:129]
	v_mfma_f32_16x16x32_bf16 v[122:125], v[142:145], v[178:181], v[122:125]
	v_mfma_f32_16x16x32_bf16 v[110:113], v[134:137], v[196:199], v[110:113]
	v_mfma_f32_16x16x32_bf16 v[106:109], v[142:145], v[196:199], v[106:109]
	v_mfma_f32_16x16x32_bf16 v[94:97], v[134:137], v[208:211], v[94:97]
	v_mfma_f32_16x16x32_bf16 v[90:93], v[142:145], v[208:211], v[90:93]
	v_mfma_f32_16x16x32_bf16 v[78:81], v[134:137], v[216:219], v[78:81]
	v_mfma_f32_16x16x32_bf16 v[74:77], v[142:145], v[216:219], v[74:77]
	v_mfma_f32_16x16x32_bf16 v[118:121], v[146:149], v[162:165], v[118:121]
	v_mfma_f32_16x16x32_bf16 v[114:117], v[154:157], v[162:165], v[114:117]
	v_mfma_f32_16x16x32_bf16 v[102:105], v[146:149], v[182:185], v[102:105]
	v_mfma_f32_16x16x32_bf16 v[98:101], v[154:157], v[182:185], v[98:101]
	v_mfma_f32_16x16x32_bf16 v[86:89], v[146:149], v[204:207], v[86:89]
	v_mfma_f32_16x16x32_bf16 v[82:85], v[154:157], v[204:207], v[82:85]
	v_mfma_f32_16x16x32_bf16 v[70:73], v[146:149], v[212:215], v[70:73]
	v_mfma_f32_16x16x32_bf16 v[66:69], v[154:157], v[212:215], v[66:69]
	v_mfma_f32_16x16x32_bf16 v[118:121], v[150:153], v[178:181], v[118:121]
	v_mfma_f32_16x16x32_bf16 v[114:117], v[158:161], v[178:181], v[114:117]
	v_mfma_f32_16x16x32_bf16 v[102:105], v[150:153], v[196:199], v[102:105]
	v_mfma_f32_16x16x32_bf16 v[98:101], v[158:161], v[196:199], v[98:101]
	v_mfma_f32_16x16x32_bf16 v[86:89], v[150:153], v[208:211], v[86:89]
	v_mfma_f32_16x16x32_bf16 v[82:85], v[158:161], v[208:211], v[82:85]
	v_mfma_f32_16x16x32_bf16 v[70:73], v[150:153], v[216:219], v[70:73]
	v_mfma_f32_16x16x32_bf16 v[66:69], v[158:161], v[216:219], v[66:69]
	s_setprio 0
	s_barrier
	s_add_i32 s38, s39, s17
	v_lshl_add_u64 v[220:221], s[0:1], 0, v[168:169]
	s_mov_b32 m0, s38
	ds_read_b128 v[162:165], v202 offset:16384
	ds_read_b128 v[178:181], v202 offset:17408
	ds_read_b128 v[182:185], v202 offset:18432
	ds_read_b128 v[196:199], v202 offset:19456
	ds_read_b128 v[204:207], v202 offset:20480
	ds_read_b128 v[208:211], v202 offset:21504
	ds_read_b128 v[212:215], v202 offset:22528
	ds_read_b128 v[216:219], v202 offset:23552
	global_load_lds_dwordx4 v[220:221], off
	s_add_i32 m0, s38, 0x2000
	s_add_u32 s38, s0, 0x50000
	v_lshl_add_u64 v[232:233], s[0:1], 0, v[172:173]
	s_addc_u32 s39, s1, 0
	s_add_i32 s52, s52, s17
	global_load_lds_dwordx4 v[232:233], off
	v_lshl_add_u64 v[234:235], s[38:39], 0, v[168:169]
	s_mov_b32 m0, s52
	v_lshl_add_u64 v[236:237], s[42:43], 0, v[170:171]
	global_load_lds_dwordx4 v[234:235], off
	v_lshl_add_u64 v[234:235], s[38:39], 0, v[172:173]
	s_add_i32 m0, s52, 0x2000
	s_nop 0
	global_load_lds_dwordx4 v[234:235], off
	v_lshl_add_u64 v[234:235], s[42:43], 0, v[166:167]
	s_mov_b32 m0, s19
	s_nop 0
	global_load_lds_dwordx4 v[234:235], off
	s_mov_b32 m0, s44
	s_nop 0
	global_load_lds_dwordx4 v[236:237], off
	s_waitcnt vmcnt(8)
	s_waitcnt lgkmcnt(0)
	s_barrier
; #define PG8_STAGE(bufoff, gbase, voff) do { _Pragma("unroll") for (int _i = 0; _i < 2; ++_i) \
;         __builtin_amdgcn_global_load_lds((const unsigned*)((const char*)(gbase) + (voff)[_i]), (LAS unsigned*)(lds + (bufoff) + ldsw + _i * 8192), 16, 0, 0); } while (0)
; #define PG8_LDA(dst, b, h) do { _Pragma("unroll") for (int m = 0; m < 4; ++m) _Pragma("unroll") for (int k = 0; k < 2; ++k) dst[m][k] = *(const LAS bf16x8*)(lds + PG8_SA(b, h) + aoff + m * 2048 + k * 1024); } while (0)
; #define PG8_LDB(dst, b, h) do { _Pragma("unroll") for (int n = 0; n < 2; ++n) _Pragma("unroll") for (int k = 0; k < 2; ++k) dst[n][k] = *(const LAS bf16x8*)(lds + PG8_SB(b, h) + boff + n * 2048 + k * 1024); } while (0)
; #define PG8_MMA(ai, bj, At, Bt) do { __builtin_amdgcn_s_setprio(1); _Pragma("unroll") for (int m = 0; m < 4; ++m) _Pragma("unroll") for (int n = 0; n < 2; ++n) _Pragma("unroll") for (int k = 0; k < 2; ++k) \
;         acc[ai][bj][m][n] = __builtin_amdgcn_mfma_f32_16x16x32_bf16(Bt[n][k], At[m][k], acc[ai][bj][m][n], 0, 0, 0); __builtin_amdgcn_s_setprio(0); } while (0)
; #define PG8_WAIT_V(n) asm volatile("s_waitcnt vmcnt(" #n ")" ::: "memory")
; #define PG8_WAIT_L(n) asm volatile("s_waitcnt lgkmcnt(" #n ")" ::: "memory")
; #define PG8_BAR __builtin_amdgcn_s_barrier()
; #define PG8_SCHED __builtin_amdgcn_sched_barrier(0)
; template <class Epi, class Sched>
; __device__ __forceinline__ void gemm_phase(LAS unsigned char* lds, const Gemm g, const Sched& S, const Epi& E) {
;     ...
;             PG8_WAIT_V(8); PG8_WAIT_L(0); PG8_BAR; PG8_MMA(1, 0, At, B0); PG8_MMA(1, 1, At, B1); PG8_BAR; PG8_SCHED;
;             PG8_LDB(B0, 1, 0); PG8_LDB(B1, 1, 1); PG8_SCHED; PG8_LDA(At, 1, 0); PG8_STAGE(PG8_SA(0, 1), a2 + hstepA, voffA);
;             PG8_WAIT_V(8); PG8_WAIT_L(0); PG8_BAR; PG8_MMA(0, 0, At, B0); PG8_MMA(0, 1, At, B1); PG8_BAR; PG8_SCHED;
	s_setprio 1
	s_waitcnt lgkmcnt(0)
	v_mfma_f32_16x16x32_bf16 v[62:65], v[130:133], v[162:165], v[62:65]
	v_mfma_f32_16x16x32_bf16 v[58:61], v[138:141], v[162:165], v[58:61]
	v_mfma_f32_16x16x32_bf16 v[46:49], v[130:133], v[182:185], v[46:49]
	v_mfma_f32_16x16x32_bf16 v[42:45], v[138:141], v[182:185], v[42:45]
	v_mfma_f32_16x16x32_bf16 v[30:33], v[130:133], v[204:207], v[30:33]
	v_mfma_f32_16x16x32_bf16 v[26:29], v[138:141], v[204:207], v[26:29]
	v_mfma_f32_16x16x32_bf16 v[14:17], v[130:133], v[212:215], v[14:17]
	v_mfma_f32_16x16x32_bf16 v[10:13], v[138:141], v[212:215], v[10:13]
	v_mfma_f32_16x16x32_bf16 v[62:65], v[134:137], v[178:181], v[62:65]
	v_mfma_f32_16x16x32_bf16 v[58:61], v[142:145], v[178:181], v[58:61]
	v_mfma_f32_16x16x32_bf16 v[46:49], v[134:137], v[196:199], v[46:49]
	v_mfma_f32_16x16x32_bf16 v[42:45], v[142:145], v[196:199], v[42:45]
	v_mfma_f32_16x16x32_bf16 v[30:33], v[134:137], v[208:211], v[30:33]
	v_mfma_f32_16x16x32_bf16 v[26:29], v[142:145], v[208:211], v[26:29]
	v_mfma_f32_16x16x32_bf16 v[14:17], v[134:137], v[216:219], v[14:17]
	v_mfma_f32_16x16x32_bf16 v[10:13], v[142:145], v[216:219], v[10:13]
	v_mfma_f32_16x16x32_bf16 v[54:57], v[146:149], v[162:165], v[54:57]
	v_mfma_f32_16x16x32_bf16 v[50:53], v[154:157], v[162:165], v[50:53]
	v_mfma_f32_16x16x32_bf16 v[38:41], v[146:149], v[182:185], v[38:41]
	v_mfma_f32_16x16x32_bf16 v[34:37], v[154:157], v[182:185], v[34:37]
	v_mfma_f32_16x16x32_bf16 v[22:25], v[146:149], v[204:207], v[22:25]
	v_mfma_f32_16x16x32_bf16 v[18:21], v[154:157], v[204:207], v[18:21]
	v_mfma_f32_16x16x32_bf16 v[6:9], v[146:149], v[212:215], v[6:9]
	v_mfma_f32_16x16x32_bf16 v[2:5], v[154:157], v[212:215], v[2:5]
	v_mfma_f32_16x16x32_bf16 v[54:57], v[150:153], v[178:181], v[54:57]
	v_mfma_f32_16x16x32_bf16 v[50:53], v[158:161], v[178:181], v[50:53]
	v_mfma_f32_16x16x32_bf16 v[38:41], v[150:153], v[196:199], v[38:41]
	v_mfma_f32_16x16x32_bf16 v[34:37], v[158:161], v[196:199], v[34:37]
	v_mfma_f32_16x16x32_bf16 v[22:25], v[150:153], v[208:211], v[22:25]
	v_mfma_f32_16x16x32_bf16 v[18:21], v[158:161], v[208:211], v[18:21]
	v_mfma_f32_16x16x32_bf16 v[6:9], v[150:153], v[216:219], v[6:9]
	v_mfma_f32_16x16x32_bf16 v[2:5], v[158:161], v[216:219], v[2:5]
	s_setprio 0
	s_barrier
	s_add_i32 s52, 0, 0x18000
	v_add_u32_e32 v0, s52, v201
	s_add_i32 s53, 0, 0x1c000
	ds_read_b128 v[130:133], v0
	ds_read_b128 v[134:137], v0 offset:1024
	ds_read_b128 v[138:141], v0 offset:2048
	ds_read_b128 v[142:145], v0 offset:3072
	v_add_u32_e32 v0, s53, v201
	ds_read_b128 v[146:149], v0
	ds_read_b128 v[150:153], v0 offset:1024
	ds_read_b128 v[154:157], v0 offset:2048
	ds_read_b128 v[158:161], v0 offset:3072
	s_add_u32 s38, s42, 0x10000
	s_addc_u32 s39, s43, 0
	s_mov_b32 m0, s45
	v_lshl_add_u64 v[246:247], s[38:39], 0, v[166:167]
	ds_read_b128 v[162:165], v202 offset:32768
	ds_read_b128 v[178:181], v202 offset:33792
	ds_read_b128 v[182:185], v202 offset:34816
	ds_read_b128 v[196:199], v202 offset:35840
	ds_read_b128 v[204:207], v202 offset:36864
	ds_read_b128 v[208:211], v202 offset:37888
	ds_read_b128 v[212:215], v202 offset:38912
	ds_read_b128 v[216:219], v202 offset:39936
	global_load_lds_dwordx4 v[246:247], off
	v_lshl_add_u64 v[246:247], s[38:39], 0, v[170:171]
	s_mov_b32 m0, s46
	s_nop 0
	global_load_lds_dwordx4 v[246:247], off
	s_waitcnt vmcnt(8)
	s_waitcnt lgkmcnt(0)
	s_barrier
	s_setprio 1
	s_waitcnt lgkmcnt(0)
	v_mfma_f32_16x16x32_bf16 v[126:129], v[130:133], v[162:165], v[126:129]
	v_mfma_f32_16x16x32_bf16 v[122:125], v[138:141], v[162:165], v[122:125]
	v_mfma_f32_16x16x32_bf16 v[110:113], v[130:133], v[182:185], v[110:113]
	v_mfma_f32_16x16x32_bf16 v[106:109], v[138:141], v[182:185], v[106:109]
	v_mfma_f32_16x16x32_bf16 v[94:97], v[130:133], v[204:207], v[94:97]
	v_mfma_f32_16x16x32_bf16 v[90:93], v[138:141], v[204:207], v[90:93]
	v_mfma_f32_16x16x32_bf16 v[78:81], v[130:133], v[212:215], v[78:81]
	v_mfma_f32_16x16x32_bf16 v[74:77], v[138:141], v[212:215], v[74:77]
	v_mfma_f32_16x16x32_bf16 v[126:129], v[134:137], v[178:181], v[126:129]
	v_mfma_f32_16x16x32_bf16 v[122:125], v[142:145], v[178:181], v[122:125]
	v_mfma_f32_16x16x32_bf16 v[110:113], v[134:137], v[196:199], v[110:113]
	v_mfma_f32_16x16x32_bf16 v[106:109], v[142:145], v[196:199], v[106:109]
	v_mfma_f32_16x16x32_bf16 v[94:97], v[134:137], v[208:211], v[94:97]
	v_mfma_f32_16x16x32_bf16 v[90:93], v[142:145], v[208:211], v[90:93]
	v_mfma_f32_16x16x32_bf16 v[78:81], v[134:137], v[216:219], v[78:81]
	v_mfma_f32_16x16x32_bf16 v[74:77], v[142:145], v[216:219], v[74:77]
	v_mfma_f32_16x16x32_bf16 v[118:121], v[146:149], v[162:165], v[118:121]
	v_mfma_f32_16x16x32_bf16 v[114:117], v[154:157], v[162:165], v[114:117]
	v_mfma_f32_16x16x32_bf16 v[102:105], v[146:149], v[182:185], v[102:105]
	v_mfma_f32_16x16x32_bf16 v[98:101], v[154:157], v[182:185], v[98:101]
	v_mfma_f32_16x16x32_bf16 v[86:89], v[146:149], v[204:207], v[86:89]
	v_mfma_f32_16x16x32_bf16 v[82:85], v[154:157], v[204:207], v[82:85]
	v_mfma_f32_16x16x32_bf16 v[70:73], v[146:149], v[212:215], v[70:73]
	v_mfma_f32_16x16x32_bf16 v[66:69], v[154:157], v[212:215], v[66:69]
	v_mfma_f32_16x16x32_bf16 v[118:121], v[150:153], v[178:181], v[118:121]
	v_mfma_f32_16x16x32_bf16 v[114:117], v[158:161], v[178:181], v[114:117]
	v_mfma_f32_16x16x32_bf16 v[102:105], v[150:153], v[196:199], v[102:105]
	v_mfma_f32_16x16x32_bf16 v[98:101], v[158:161], v[196:199], v[98:101]
	v_mfma_f32_16x16x32_bf16 v[86:89], v[150:153], v[208:211], v[86:89]
	v_mfma_f32_16x16x32_bf16 v[82:85], v[158:161], v[208:211], v[82:85]
	v_mfma_f32_16x16x32_bf16 v[70:73], v[150:153], v[216:219], v[70:73]
	v_mfma_f32_16x16x32_bf16 v[66:69], v[158:161], v[216:219], v[66:69]
	s_setprio 0
	s_barrier
; #define PG8_STAGE(bufoff, gbase, voff) do { _Pragma("unroll") for (int _i = 0; _i < 2; ++_i) \
;         __builtin_amdgcn_global_load_lds((const unsigned*)((const char*)(gbase) + (voff)[_i]), (LAS unsigned*)(lds + (bufoff) + ldsw + _i * 8192), 16, 0, 0); } while (0)
; #define PG8_LDA(dst, b, h) do { _Pragma("unroll") for (int m = 0; m < 4; ++m) _Pragma("unroll") for (int k = 0; k < 2; ++k) dst[m][k] = *(const LAS bf16x8*)(lds + PG8_SA(b, h) + aoff + m * 2048 + k * 1024); } while (0)
; #define PG8_MMA(ai, bj, At, Bt) do { __builtin_amdgcn_s_setprio(1); _Pragma("unroll") for (int m = 0; m < 4; ++m) _Pragma("unroll") for (int n = 0; n < 2; ++n) _Pragma("unroll") for (int k = 0; k < 2; ++k) \
;         acc[ai][bj][m][n] = __builtin_amdgcn_mfma_f32_16x16x32_bf16(Bt[n][k], At[m][k], acc[ai][bj][m][n], 0, 0, 0); __builtin_amdgcn_s_setprio(0); } while (0)
; #define PG8_WAIT_V(n) asm volatile("s_waitcnt vmcnt(" #n ")" ::: "memory")
; #define PG8_WAIT_L(n) asm volatile("s_waitcnt lgkmcnt(" #n ")" ::: "memory")
; #define PG8_BAR __builtin_amdgcn_s_barrier()
; #define PG8_SCHED __builtin_amdgcn_sched_barrier(0)
; template <class Epi, class Sched>
; __device__ __forceinline__ void gemm_phase(LAS unsigned char* lds, const Gemm g, const Sched& S, const Epi& E) {
;     ...
;         for (int t = 0; t < nt; t += 2) {
;             if constexpr (Epi::HOOKS) { if (cur.kind == 3 && (t == 4 || t == 12)) { int fr_ = fr, fq_ = fq; asm volatile("" : "+v"(fr_), "+v"(fq_)); E.hook(acc, cur, t == 4 ? 0 : 1, wr, wc, fr_, fq_); } }
;             const bool last = (t == nt - 2);
;             const char* a1 = cA + (size_t)(t + 1) * kstep;
;             const char* a2 = last ? nA : cA + (size_t)(t + 2) * kstep; const char* b2 = last ? nB : cB + (size_t)(t + 2) * kstep;
;             const char* a3 = a2 + kstep; const char* b3 = b2 + kstep;
;     ...
;             PG8_LDA(At, 1, 1); PG8_STAGE(PG8_SB(1, 0), b3, voffB); PG8_STAGE(PG8_SB(1, 1), b3 + hstepB, voffB); PG8_STAGE(PG8_SA(1, 0), a3, voffA);
;             PG8_WAIT_V(8); PG8_WAIT_L(0); PG8_BAR; PG8_MMA(1, 0, At, B0); PG8_MMA(1, 1, At, B1); PG8_BAR; PG8_SCHED;
	s_add_i32 s38, s52, s17
	v_lshl_add_u64 v[220:221], v[220:221], 0, s[26:27]
	s_mov_b32 m0, s38
	ds_read_b128 v[162:165], v202 offset:49152
	ds_read_b128 v[178:181], v202 offset:50176
	ds_read_b128 v[182:185], v202 offset:51200
	ds_read_b128 v[196:199], v202 offset:52224
	ds_read_b128 v[204:207], v202 offset:53248
	ds_read_b128 v[208:211], v202 offset:54272
	ds_read_b128 v[212:215], v202 offset:55296
	ds_read_b128 v[216:219], v202 offset:56320
	global_load_lds_dwordx4 v[220:221], off
	s_add_i32 m0, s38, 0x2000
	s_add_u32 s0, s0, 0x50080
	v_lshl_add_u64 v[220:221], v[232:233], 0, s[26:27]
	s_addc_u32 s1, s1, 0
	s_add_i32 s38, s53, s17
	global_load_lds_dwordx4 v[220:221], off
	v_lshl_add_u64 v[220:221], s[0:1], 0, v[168:169]
	s_mov_b32 m0, s38
	s_nop 0
	global_load_lds_dwordx4 v[220:221], off
	v_lshl_add_u64 v[220:221], s[0:1], 0, v[172:173]
	s_add_i32 m0, s38, 0x2000
	s_nop 0
	global_load_lds_dwordx4 v[220:221], off
	v_lshl_add_u64 v[220:221], v[234:235], 0, s[26:27]
	s_mov_b32 m0, s67
	s_nop 0
	global_load_lds_dwordx4 v[220:221], off
	v_lshl_add_u64 v[220:221], v[236:237], 0, s[26:27]
	s_mov_b32 m0, s69
	s_nop 0
	global_load_lds_dwordx4 v[220:221], off
	s_waitcnt vmcnt(8)
	s_waitcnt lgkmcnt(0)
	s_barrier
	s_setprio 1
	s_waitcnt lgkmcnt(0)
	v_mfma_f32_16x16x32_bf16 v[62:65], v[130:133], v[162:165], v[62:65]
	v_mfma_f32_16x16x32_bf16 v[58:61], v[138:141], v[162:165], v[58:61]
	v_mfma_f32_16x16x32_bf16 v[46:49], v[130:133], v[182:185], v[46:49]
	v_mfma_f32_16x16x32_bf16 v[42:45], v[138:141], v[182:185], v[42:45]
	v_mfma_f32_16x16x32_bf16 v[30:33], v[130:133], v[204:207], v[30:33]
	v_mfma_f32_16x16x32_bf16 v[26:29], v[138:141], v[204:207], v[26:29]
	v_mfma_f32_16x16x32_bf16 v[14:17], v[130:133], v[212:215], v[14:17]
	v_mfma_f32_16x16x32_bf16 v[10:13], v[138:141], v[212:215], v[10:13]
	v_mfma_f32_16x16x32_bf16 v[62:65], v[134:137], v[178:181], v[62:65]
	v_mfma_f32_16x16x32_bf16 v[58:61], v[142:145], v[178:181], v[58:61]
	v_mfma_f32_16x16x32_bf16 v[46:49], v[134:137], v[196:199], v[46:49]
	v_mfma_f32_16x16x32_bf16 v[42:45], v[142:145], v[196:199], v[42:45]
	v_mfma_f32_16x16x32_bf16 v[30:33], v[134:137], v[208:211], v[30:33]
	v_mfma_f32_16x16x32_bf16 v[26:29], v[142:145], v[208:211], v[26:29]
	v_mfma_f32_16x16x32_bf16 v[14:17], v[134:137], v[216:219], v[14:17]
	v_mfma_f32_16x16x32_bf16 v[10:13], v[142:145], v[216:219], v[10:13]
	v_mfma_f32_16x16x32_bf16 v[54:57], v[146:149], v[162:165], v[54:57]
	v_mfma_f32_16x16x32_bf16 v[50:53], v[154:157], v[162:165], v[50:53]
	v_mfma_f32_16x16x32_bf16 v[38:41], v[146:149], v[182:185], v[38:41]
	v_mfma_f32_16x16x32_bf16 v[34:37], v[154:157], v[182:185], v[34:37]
	v_mfma_f32_16x16x32_bf16 v[22:25], v[146:149], v[204:207], v[22:25]
	v_mfma_f32_16x16x32_bf16 v[18:21], v[154:157], v[204:207], v[18:21]
	v_mfma_f32_16x16x32_bf16 v[6:9], v[146:149], v[212:215], v[6:9]
	v_mfma_f32_16x16x32_bf16 v[2:5], v[154:157], v[212:215], v[2:5]
	v_mfma_f32_16x16x32_bf16 v[54:57], v[150:153], v[178:181], v[54:57]
	v_mfma_f32_16x16x32_bf16 v[50:53], v[158:161], v[178:181], v[50:53]
	v_mfma_f32_16x16x32_bf16 v[38:41], v[150:153], v[196:199], v[38:41]
	v_mfma_f32_16x16x32_bf16 v[34:37], v[158:161], v[196:199], v[34:37]
	v_mfma_f32_16x16x32_bf16 v[22:25], v[150:153], v[208:211], v[22:25]
	v_mfma_f32_16x16x32_bf16 v[18:21], v[158:161], v[208:211], v[18:21]
	v_mfma_f32_16x16x32_bf16 v[6:9], v[150:153], v[216:219], v[6:9]
	v_mfma_f32_16x16x32_bf16 v[2:5], v[158:161], v[216:219], v[2:5]
	s_setprio 0
	s_add_u32 s97, s97, 0x100
	s_addc_u32 vcc_lo, vcc_lo, 0
	s_add_u32 s20, s20, 0x100
	s_addc_u32 s21, s21, 0
	s_cmp_ge_i32 s62, s47
	s_mov_b32 s0, s62
	s_cbranch_scc1 .Lrot_exit_6
	s_add_i32 s62, s0, 2
	s_add_u32 s1, s20, 0xffff0080
	s_addc_u32 s38, s21, -1
	s_add_i32 s39, 0, 0x10000
	s_cmp_eq_u32 s71, s0
	s_cselect_b32 s43, s61, s38
	s_cselect_b32 s42, s96, s1
	s_branch .Lrot_head_6

; template <class Epi, class Sched>
; __device__ __forceinline__ void gemm_phase(LAS unsigned char* lds, const Gemm g, const Sched& S, const Epi& E) {
;     ...
;         for (int t = 0; t < nt; t += 2) {
;             if constexpr (Epi::HOOKS) { if (cur.kind == 3 && (t == 4 || t == 12)) { int fr_ = fr, fq_ = fq; asm volatile("" : "+v"(fr_), "+v"(fq_)); E.hook(acc, cur, t == 4 ? 0 : 1, wr, wc, fr_, fq_); } }
;             const bool last = (t == nt - 2);
;             const char* a1 = cA + (size_t)(t + 1) * kstep;
;             const char* a2 = last ? nA : cA + (size_t)(t + 2) * kstep; const char* b2 = last ? nB : cB + (size_t)(t + 2) * kstep;
;             const char* a3 = a2 + kstep; const char* b3 = b2 + kstep;
.LBB0_551:
	s_add_i32 s62, s0, 2
	s_add_u32 s1, s20, 0xffff0080
	s_addc_u32 s42, s21, -1
	s_add_i32 s43, 0, 0x10000
	s_cmp_eq_u32 s71, s0
	s_cselect_b32 vcc_hi, s19, s42
	s_cselect_b32 vcc_lo, s25, s1
	s_cselect_b32 s1, s41, s72
	s_cselect_b32 s0, s67, s69
	s_add_i32 s52, 0, 0x14000
	s_branch .Lrot_body_7

; #define PG8_STAGE(bufoff, gbase, voff) do { _Pragma("unroll") for (int _i = 0; _i < 2; ++_i) \
;         __builtin_amdgcn_global_load_lds((const unsigned*)((const char*)(gbase) + (voff)[_i]), (LAS unsigned*)(lds + (bufoff) + ldsw + _i * 8192), 16, 0, 0); } while (0)
; #define PG8_LDA(dst, b, h) do { _Pragma("unroll") for (int m = 0; m < 4; ++m) _Pragma("unroll") for (int k = 0; k < 2; ++k) dst[m][k] = *(const LAS bf16x8*)(lds + PG8_SA(b, h) + aoff + m * 2048 + k * 1024); } while (0)
; #define PG8_LDB(dst, b, h) do { _Pragma("unroll") for (int n = 0; n < 2; ++n) _Pragma("unroll") for (int k = 0; k < 2; ++k) dst[n][k] = *(const LAS bf16x8*)(lds + PG8_SB(b, h) + boff + n * 2048 + k * 1024); } while (0)
; #define PG8_MMA(ai, bj, At, Bt) do { __builtin_amdgcn_s_setprio(1); _Pragma("unroll") for (int m = 0; m < 4; ++m) _Pragma("unroll") for (int n = 0; n < 2; ++n) _Pragma("unroll") for (int k = 0; k < 2; ++k) \
;         acc[ai][bj][m][n] = __builtin_amdgcn_mfma_f32_16x16x32_bf16(Bt[n][k], At[m][k], acc[ai][bj][m][n], 0, 0, 0); __builtin_amdgcn_s_setprio(0); } while (0)
; #define PG8_WAIT_V(n) asm volatile("s_waitcnt vmcnt(" #n ")" ::: "memory")
; #define PG8_WAIT_L(n) asm volatile("s_waitcnt lgkmcnt(" #n ")" ::: "memory")
; #define PG8_BAR __builtin_amdgcn_s_barrier()
; #define PG8_SCHED __builtin_amdgcn_sched_barrier(0)
; template <class Epi, class Sched>
; __device__ __forceinline__ void gemm_phase(LAS unsigned char* lds, const Gemm g, const Sched& S, const Epi& E) {
;     ...
;             const char* a1 = cA + (size_t)(t + 1) * kstep;
;             const char* a2 = last ? nA : cA + (size_t)(t + 2) * kstep; const char* b2 = last ? nB : cB + (size_t)(t + 2) * kstep;
;             const char* a3 = a2 + kstep; const char* b3 = b2 + kstep;
;             PG8_LDB(B0, 0, 0); PG8_LDB(B1, 0, 1); PG8_SCHED; PG8_LDA(At, 0, 0); PG8_STAGE(PG8_SA(1, 1), a1 + hstepA, voffA);
;             PG8_WAIT_V(8); PG8_WAIT_L(0); PG8_BAR; PG8_MMA(0, 0, At, B0); PG8_MMA(0, 1, At, B1); PG8_BAR; PG8_SCHED;
;             PG8_LDA(At, 0, 1); PG8_STAGE(PG8_SB(0, 0), b2, voffB); PG8_STAGE(PG8_SB(0, 1), b2 + hstepB, voffB); PG8_STAGE(PG8_SA(0, 0), a2, voffA);
;             PG8_WAIT_V(8); PG8_WAIT_L(0); PG8_BAR; PG8_MMA(1, 0, At, B0); PG8_MMA(1, 1, At, B1); PG8_BAR; PG8_SCHED;
.Lrot_body_7:
	v_add_u32_e32 v38, s43, v251
	v_add_u32_e32 v70, s52, v251
	ds_read_b128 v[26:29], v38
	ds_read_b128 v[30:33], v38 offset:1024
	ds_read_b128 v[34:37], v38 offset:2048
	ds_read_b128 v[38:41], v38 offset:3072
	ds_read_b128 v[50:53], v70
	ds_read_b128 v[54:57], v70 offset:1024
	ds_read_b128 v[58:61], v70 offset:2048
	ds_read_b128 v[70:73], v70 offset:3072
	v_lshl_add_u64 v[214:215], s[20:21], 0, v[204:205]
	s_add_i32 m0, s46, 0xc000
	ds_read_b128 v[90:93], v252
	ds_read_b128 v[110:113], v252 offset:1024
	ds_read_b128 v[126:129], v252 offset:2048
	ds_read_b128 v[142:145], v252 offset:3072
	ds_read_b128 v[162:165], v252 offset:4096
	ds_read_b128 v[182:185], v252 offset:5120
	ds_read_b128 v[206:209], v252 offset:6144
	ds_read_b128 v[210:213], v252 offset:7168
	global_load_lds_dwordx4 v[214:215], off
	v_lshl_add_u64 v[214:215], s[20:21], 0, v[202:203]
	s_add_i32 m0, s46, 0xe000
	s_nop 0
	global_load_lds_dwordx4 v[214:215], off
	s_waitcnt vmcnt(8)
	s_waitcnt lgkmcnt(0)
	s_barrier
	s_setprio 1
	s_waitcnt lgkmcnt(0)
	v_mfma_f32_16x16x32_bf16 v[178:181], v[26:29], v[90:93], v[178:181]
	v_mfma_f32_16x16x32_bf16 v[170:173], v[34:37], v[90:93], v[170:173]
	v_mfma_f32_16x16x32_bf16 v[158:161], v[26:29], v[126:129], v[158:161]
	v_mfma_f32_16x16x32_bf16 v[150:153], v[34:37], v[126:129], v[150:153]
	v_mfma_f32_16x16x32_bf16 v[138:141], v[26:29], v[162:165], v[138:141]
	v_mfma_f32_16x16x32_bf16 v[130:133], v[34:37], v[162:165], v[130:133]
	v_mfma_f32_16x16x32_bf16 v[118:121], v[26:29], v[206:209], v[118:121]
	v_mfma_f32_16x16x32_bf16 v[106:109], v[34:37], v[206:209], v[106:109]
	v_mfma_f32_16x16x32_bf16 v[178:181], v[30:33], v[110:113], v[178:181]
	v_mfma_f32_16x16x32_bf16 v[170:173], v[38:41], v[110:113], v[170:173]
	v_mfma_f32_16x16x32_bf16 v[158:161], v[30:33], v[142:145], v[158:161]
	v_mfma_f32_16x16x32_bf16 v[150:153], v[38:41], v[142:145], v[150:153]
	v_mfma_f32_16x16x32_bf16 v[138:141], v[30:33], v[182:185], v[138:141]
	v_mfma_f32_16x16x32_bf16 v[130:133], v[38:41], v[182:185], v[130:133]
	v_mfma_f32_16x16x32_bf16 v[118:121], v[30:33], v[210:213], v[118:121]
	v_mfma_f32_16x16x32_bf16 v[106:109], v[38:41], v[210:213], v[106:109]
	v_mfma_f32_16x16x32_bf16 v[174:177], v[50:53], v[90:93], v[174:177]
	v_mfma_f32_16x16x32_bf16 v[90:93], v[58:61], v[90:93], v[166:169]
	v_mfma_f32_16x16x32_bf16 v[134:137], v[50:53], v[162:165], v[134:137]
	v_mfma_f32_16x16x32_bf16 v[122:125], v[58:61], v[162:165], v[122:125]
	v_mfma_f32_16x16x32_bf16 v[114:117], v[50:53], v[206:209], v[114:117]
	v_mfma_f32_16x16x32_bf16 v[102:105], v[58:61], v[206:209], v[102:105]
	v_mfma_f32_16x16x32_bf16 v[174:177], v[54:57], v[110:113], v[174:177]
	v_mfma_f32_16x16x32_bf16 v[90:93], v[70:73], v[110:113], v[90:93]
	v_mfma_f32_16x16x32_bf16 v[110:113], v[50:53], v[126:129], v[154:157]
	v_mfma_f32_16x16x32_bf16 v[126:129], v[58:61], v[126:129], v[146:149]
	v_mfma_f32_16x16x32_bf16 v[134:137], v[54:57], v[182:185], v[134:137]
	v_mfma_f32_16x16x32_bf16 v[122:125], v[70:73], v[182:185], v[122:125]
	v_mfma_f32_16x16x32_bf16 v[114:117], v[54:57], v[210:213], v[114:117]
	v_mfma_f32_16x16x32_bf16 v[102:105], v[70:73], v[210:213], v[102:105]
	v_mfma_f32_16x16x32_bf16 v[110:113], v[54:57], v[142:145], v[110:113]
	v_mfma_f32_16x16x32_bf16 v[126:129], v[70:73], v[142:145], v[126:129]
	s_setprio 0
	s_barrier
	s_add_i32 s42, s43, s45
	v_lshl_add_u64 v[232:233], s[0:1], 0, v[0:1]
	s_mov_b32 m0, s42
	ds_read_b128 v[142:145], v252 offset:16384
	ds_read_b128 v[146:149], v252 offset:17408
	ds_read_b128 v[154:157], v252 offset:18432
	ds_read_b128 v[162:165], v252 offset:19456
	ds_read_b128 v[166:169], v252 offset:20480
	ds_read_b128 v[182:185], v252 offset:21504
	ds_read_b128 v[206:209], v252 offset:22528
	ds_read_b128 v[210:213], v252 offset:23552
	global_load_lds_dwordx4 v[232:233], off
	s_add_i32 m0, s42, 0x2000
	s_add_u32 s42, s0, 0x10000
	v_lshl_add_u64 v[234:235], s[0:1], 0, v[200:201]
	s_addc_u32 s43, s1, 0
	s_add_i32 s52, s52, s45
	global_load_lds_dwordx4 v[234:235], off
	v_lshl_add_u64 v[214:215], s[42:43], 0, v[0:1]
	s_mov_b32 m0, s52
	v_lshl_add_u64 v[236:237], vcc, 0, v[196:197]
	global_load_lds_dwordx4 v[214:215], off
	v_lshl_add_u64 v[214:215], s[42:43], 0, v[200:201]
	s_add_i32 m0, s52, 0x2000
	v_lshl_add_u64 v[246:247], vcc, 0, v[198:199]
	global_load_lds_dwordx4 v[214:215], off
	s_mov_b32 m0, s46
	s_nop 0
	global_load_lds_dwordx4 v[236:237], off
	s_mov_b32 m0, s47
	s_nop 0
	global_load_lds_dwordx4 v[246:247], off
	s_waitcnt vmcnt(8)
	s_waitcnt lgkmcnt(0)
	s_barrier
	s_setprio 1
	s_waitcnt lgkmcnt(0)
	v_mfma_f32_16x16x32_bf16 v[98:101], v[26:29], v[142:145], v[98:101]
	v_mfma_f32_16x16x32_bf16 v[86:89], v[34:37], v[142:145], v[86:89]
	v_mfma_f32_16x16x32_bf16 v[78:81], v[26:29], v[154:157], v[78:81]
	v_mfma_f32_16x16x32_bf16 v[66:69], v[34:37], v[154:157], v[66:69]
	v_mfma_f32_16x16x32_bf16 v[46:49], v[26:29], v[166:169], v[46:49]
	v_mfma_f32_16x16x32_bf16 v[22:25], v[34:37], v[166:169], v[22:25]
	v_mfma_f32_16x16x32_bf16 v[14:17], v[26:29], v[206:209], v[14:17]
	v_mfma_f32_16x16x32_bf16 v[6:9], v[34:37], v[206:209], v[6:9]
	v_mfma_f32_16x16x32_bf16 v[98:101], v[30:33], v[146:149], v[98:101]
	v_mfma_f32_16x16x32_bf16 v[86:89], v[38:41], v[146:149], v[86:89]
	v_mfma_f32_16x16x32_bf16 v[78:81], v[30:33], v[162:165], v[78:81]
	v_mfma_f32_16x16x32_bf16 v[66:69], v[38:41], v[162:165], v[66:69]
	v_mfma_f32_16x16x32_bf16 v[46:49], v[30:33], v[182:185], v[46:49]
	v_mfma_f32_16x16x32_bf16 v[22:25], v[38:41], v[182:185], v[22:25]
	v_mfma_f32_16x16x32_bf16 v[14:17], v[30:33], v[210:213], v[14:17]
	v_mfma_f32_16x16x32_bf16 v[6:9], v[38:41], v[210:213], v[6:9]
	v_mfma_f32_16x16x32_bf16 v[42:45], v[50:53], v[166:169], v[42:45]
	v_mfma_f32_16x16x32_bf16 v[18:21], v[58:61], v[166:169], v[18:21]
	v_mfma_f32_16x16x32_bf16 v[10:13], v[50:53], v[206:209], v[10:13]
	v_mfma_f32_16x16x32_bf16 v[2:5], v[58:61], v[206:209], v[2:5]
	v_mfma_f32_16x16x32_bf16 v[26:29], v[50:53], v[142:145], v[94:97]
	v_mfma_f32_16x16x32_bf16 v[30:33], v[58:61], v[142:145], v[82:85]
	v_mfma_f32_16x16x32_bf16 v[34:37], v[50:53], v[154:157], v[74:77]
	v_mfma_f32_16x16x32_bf16 v[38:41], v[58:61], v[154:157], v[62:65]
	v_mfma_f32_16x16x32_bf16 v[42:45], v[54:57], v[182:185], v[42:45]
	v_mfma_f32_16x16x32_bf16 v[18:21], v[70:73], v[182:185], v[18:21]
	v_mfma_f32_16x16x32_bf16 v[10:13], v[54:57], v[210:213], v[10:13]
	v_mfma_f32_16x16x32_bf16 v[2:5], v[70:73], v[210:213], v[2:5]
	v_mfma_f32_16x16x32_bf16 v[26:29], v[54:57], v[146:149], v[26:29]
	v_mfma_f32_16x16x32_bf16 v[30:33], v[70:73], v[146:149], v[30:33]
	v_mfma_f32_16x16x32_bf16 v[34:37], v[54:57], v[162:165], v[34:37]
	v_mfma_f32_16x16x32_bf16 v[38:41], v[70:73], v[162:165], v[38:41]
	s_setprio 0
	s_barrier
; #define PG8_STAGE(bufoff, gbase, voff) do { _Pragma("unroll") for (int _i = 0; _i < 2; ++_i) \
;         __builtin_amdgcn_global_load_lds((const unsigned*)((const char*)(gbase) + (voff)[_i]), (LAS unsigned*)(lds + (bufoff) + ldsw + _i * 8192), 16, 0, 0); } while (0)
; #define PG8_LDA(dst, b, h) do { _Pragma("unroll") for (int m = 0; m < 4; ++m) _Pragma("unroll") for (int k = 0; k < 2; ++k) dst[m][k] = *(const LAS bf16x8*)(lds + PG8_SA(b, h) + aoff + m * 2048 + k * 1024); } while (0)
; #define PG8_LDB(dst, b, h) do { _Pragma("unroll") for (int n = 0; n < 2; ++n) _Pragma("unroll") for (int k = 0; k < 2; ++k) dst[n][k] = *(const LAS bf16x8*)(lds + PG8_SB(b, h) + boff + n * 2048 + k * 1024); } while (0)
; #define PG8_MMA(ai, bj, At, Bt) do { __builtin_amdgcn_s_setprio(1); _Pragma("unroll") for (int m = 0; m < 4; ++m) _Pragma("unroll") for (int n = 0; n < 2; ++n) _Pragma("unroll") for (int k = 0; k < 2; ++k) \
;         acc[ai][bj][m][n] = __builtin_amdgcn_mfma_f32_16x16x32_bf16(Bt[n][k], At[m][k], acc[ai][bj][m][n], 0, 0, 0); __builtin_amdgcn_s_setprio(0); } while (0)
; #define PG8_WAIT_V(n) asm volatile("s_waitcnt vmcnt(" #n ")" ::: "memory")
; #define PG8_WAIT_L(n) asm volatile("s_waitcnt lgkmcnt(" #n ")" ::: "memory")
; #define PG8_BAR __builtin_amdgcn_s_barrier()
; #define PG8_SCHED __builtin_amdgcn_sched_barrier(0)
; template <class Epi, class Sched>
; __device__ __forceinline__ void gemm_phase(LAS unsigned char* lds, const Gemm g, const Sched& S, const Epi& E) {
;     ...
;             PG8_LDB(B0, 1, 0); PG8_LDB(B1, 1, 1); PG8_SCHED; PG8_LDA(At, 1, 0); PG8_STAGE(PG8_SA(0, 1), a2 + hstepA, voffA);
;             PG8_WAIT_V(8); PG8_WAIT_L(0); PG8_BAR; PG8_MMA(0, 0, At, B0); PG8_MMA(0, 1, At, B1); PG8_BAR; PG8_SCHED;
	s_add_i32 s52, 0, 0x18000
	s_add_i32 s53, 0, 0x1c000
	v_add_u32_e32 v62, s52, v251
	v_add_u32_e32 v74, s53, v251
	ds_read_b128 v[50:53], v62
	ds_read_b128 v[54:57], v62 offset:1024
	ds_read_b128 v[58:61], v62 offset:2048
	ds_read_b128 v[62:65], v62 offset:3072
	ds_read_b128 v[70:73], v74
	ds_read_b128 v[142:145], v74 offset:1024
	ds_read_b128 v[162:165], v74 offset:2048
	ds_read_b128 v[182:185], v74 offset:3072
	s_add_u32 s42, vcc_lo, 0x10000
	s_addc_u32 s43, vcc_hi, 0
	s_mov_b32 m0, s48
	v_lshl_add_u64 v[154:155], s[42:43], 0, v[196:197]
	ds_read_b128 v[74:77], v252 offset:32768
	ds_read_b128 v[82:85], v252 offset:33792
	ds_read_b128 v[94:97], v252 offset:34816
	ds_read_b128 v[146:149], v252 offset:35840
	ds_read_b128 v[206:209], v252 offset:36864
	ds_read_b128 v[210:213], v252 offset:37888
	ds_read_b128 v[214:217], v252 offset:38912
	ds_read_b128 v[218:221], v252 offset:39936
	global_load_lds_dwordx4 v[154:155], off
	v_lshl_add_u64 v[154:155], s[42:43], 0, v[198:199]
	s_mov_b32 m0, s65
	s_nop 0
	global_load_lds_dwordx4 v[154:155], off
	s_waitcnt vmcnt(8)
	s_waitcnt lgkmcnt(0)
	s_barrier
	s_setprio 1
	s_waitcnt lgkmcnt(0)
	v_mfma_f32_16x16x32_bf16 v[154:157], v[50:53], v[74:77], v[178:181]
	v_mfma_f32_16x16x32_bf16 v[178:181], v[54:57], v[82:85], v[154:157]
	v_mfma_f32_16x16x32_bf16 v[154:157], v[58:61], v[74:77], v[170:173]
	v_mfma_f32_16x16x32_bf16 v[170:173], v[62:65], v[82:85], v[154:157]
	v_mfma_f32_16x16x32_bf16 v[154:157], v[50:53], v[94:97], v[158:161]
	v_mfma_f32_16x16x32_bf16 v[150:153], v[58:61], v[94:97], v[150:153]
	v_mfma_f32_16x16x32_bf16 v[138:141], v[50:53], v[206:209], v[138:141]
	v_mfma_f32_16x16x32_bf16 v[130:133], v[58:61], v[206:209], v[130:133]
	v_mfma_f32_16x16x32_bf16 v[118:121], v[50:53], v[214:217], v[118:121]
	v_mfma_f32_16x16x32_bf16 v[106:109], v[58:61], v[214:217], v[106:109]
	v_mfma_f32_16x16x32_bf16 v[158:161], v[54:57], v[146:149], v[154:157]
	v_mfma_f32_16x16x32_bf16 v[150:153], v[62:65], v[146:149], v[150:153]
	v_mfma_f32_16x16x32_bf16 v[138:141], v[54:57], v[210:213], v[138:141]
	v_mfma_f32_16x16x32_bf16 v[130:133], v[62:65], v[210:213], v[130:133]
	v_mfma_f32_16x16x32_bf16 v[118:121], v[54:57], v[218:221], v[118:121]
	v_mfma_f32_16x16x32_bf16 v[106:109], v[62:65], v[218:221], v[106:109]
	v_mfma_f32_16x16x32_bf16 v[154:157], v[70:73], v[74:77], v[174:177]
	v_mfma_f32_16x16x32_bf16 v[74:77], v[162:165], v[74:77], v[90:93]
	v_mfma_f32_16x16x32_bf16 v[166:169], v[182:185], v[82:85], v[74:77]
	v_mfma_f32_16x16x32_bf16 v[74:77], v[70:73], v[94:97], v[110:113]
	v_mfma_f32_16x16x32_bf16 v[174:177], v[142:145], v[82:85], v[154:157]
	v_mfma_f32_16x16x32_bf16 v[154:157], v[142:145], v[146:149], v[74:77]
	v_mfma_f32_16x16x32_bf16 v[74:77], v[162:165], v[94:97], v[126:129]
	v_mfma_f32_16x16x32_bf16 v[146:149], v[182:185], v[146:149], v[74:77]
	v_mfma_f32_16x16x32_bf16 v[74:77], v[70:73], v[206:209], v[134:137]
	v_mfma_f32_16x16x32_bf16 v[134:137], v[142:145], v[210:213], v[74:77]
	v_mfma_f32_16x16x32_bf16 v[74:77], v[162:165], v[206:209], v[122:125]
	v_mfma_f32_16x16x32_bf16 v[122:125], v[182:185], v[210:213], v[74:77]
	v_mfma_f32_16x16x32_bf16 v[74:77], v[70:73], v[214:217], v[114:117]
	v_mfma_f32_16x16x32_bf16 v[114:117], v[142:145], v[218:221], v[74:77]
	v_mfma_f32_16x16x32_bf16 v[74:77], v[162:165], v[214:217], v[102:105]
	v_mfma_f32_16x16x32_bf16 v[102:105], v[182:185], v[218:221], v[74:77]
	s_setprio 0
	s_barrier
; #define PG8_STAGE(bufoff, gbase, voff) do { _Pragma("unroll") for (int _i = 0; _i < 2; ++_i) \
;         __builtin_amdgcn_global_load_lds((const unsigned*)((const char*)(gbase) + (voff)[_i]), (LAS unsigned*)(lds + (bufoff) + ldsw + _i * 8192), 16, 0, 0); } while (0)
; #define PG8_LDA(dst, b, h) do { _Pragma("unroll") for (int m = 0; m < 4; ++m) _Pragma("unroll") for (int k = 0; k < 2; ++k) dst[m][k] = *(const LAS bf16x8*)(lds + PG8_SA(b, h) + aoff + m * 2048 + k * 1024); } while (0)
; #define PG8_MMA(ai, bj, At, Bt) do { __builtin_amdgcn_s_setprio(1); _Pragma("unroll") for (int m = 0; m < 4; ++m) _Pragma("unroll") for (int n = 0; n < 2; ++n) _Pragma("unroll") for (int k = 0; k < 2; ++k) \
;         acc[ai][bj][m][n] = __builtin_amdgcn_mfma_f32_16x16x32_bf16(Bt[n][k], At[m][k], acc[ai][bj][m][n], 0, 0, 0); __builtin_amdgcn_s_setprio(0); } while (0)
; #define PG8_WAIT_V(n) asm volatile("s_waitcnt vmcnt(" #n ")" ::: "memory")
; #define PG8_WAIT_L(n) asm volatile("s_waitcnt lgkmcnt(" #n ")" ::: "memory")
; #define PG8_BAR __builtin_amdgcn_s_barrier()
; #define PG8_SCHED __builtin_amdgcn_sched_barrier(0)
; template <class Epi, class Sched>
; __device__ __forceinline__ void gemm_phase(LAS unsigned char* lds, const Gemm g, const Sched& S, const Epi& E) {
;     ...
;         for (int t = 0; t < nt; t += 2) {
;             if constexpr (Epi::HOOKS) { if (cur.kind == 3 && (t == 4 || t == 12)) { int fr_ = fr, fq_ = fq; asm volatile("" : "+v"(fr_), "+v"(fq_)); E.hook(acc, cur, t == 4 ? 0 : 1, wr, wc, fr_, fq_); } }
;             const bool last = (t == nt - 2);
;             const char* a1 = cA + (size_t)(t + 1) * kstep;
;             const char* a2 = last ? nA : cA + (size_t)(t + 2) * kstep; const char* b2 = last ? nB : cB + (size_t)(t + 2) * kstep;
;             const char* a3 = a2 + kstep; const char* b3 = b2 + kstep;
;     ...
;             PG8_LDA(At, 1, 1); PG8_STAGE(PG8_SB(1, 0), b3, voffB); PG8_STAGE(PG8_SB(1, 1), b3 + hstepB, voffB); PG8_STAGE(PG8_SA(1, 0), a3, voffA);
;             PG8_WAIT_V(8); PG8_WAIT_L(0); PG8_BAR; PG8_MMA(1, 0, At, B0); PG8_MMA(1, 1, At, B1); PG8_BAR; PG8_SCHED;
	s_add_i32 s42, s52, s45
	v_lshl_add_u64 v[94:95], v[232:233], 0, s[26:27]
	s_mov_b32 m0, s42
	s_nop 1
	ds_read_b128 v[74:77], v252 offset:49152
	ds_read_b128 v[82:85], v252 offset:50176
	ds_read_b128 v[90:93], v252 offset:51200
	ds_read_b128 v[110:113], v252 offset:52224
	ds_read_b128 v[126:129], v252 offset:53248
	ds_read_b128 v[206:209], v252 offset:54272
	ds_read_b128 v[210:213], v252 offset:55296
	ds_read_b128 v[214:217], v252 offset:56320
	global_load_lds_dwordx4 v[94:95], off
	s_add_i32 m0, s42, 0x2000
	s_add_u32 s0, s0, 0x10080
	v_lshl_add_u64 v[94:95], v[234:235], 0, s[26:27]
	s_addc_u32 s1, s1, 0
	s_add_i32 s42, s53, s45
	global_load_lds_dwordx4 v[94:95], off
	v_lshl_add_u64 v[94:95], s[0:1], 0, v[0:1]
	s_mov_b32 m0, s42
	s_nop 0
	global_load_lds_dwordx4 v[94:95], off
	v_lshl_add_u64 v[94:95], s[0:1], 0, v[200:201]
	s_add_i32 m0, s42, 0x2000
	s_nop 0
	global_load_lds_dwordx4 v[94:95], off
	v_lshl_add_u64 v[94:95], v[236:237], 0, s[26:27]
	s_mov_b32 m0, s96
	s_nop 0
	global_load_lds_dwordx4 v[94:95], off
	v_lshl_add_u64 v[94:95], v[246:247], 0, s[26:27]
	s_mov_b32 m0, s97
	s_nop 0
	global_load_lds_dwordx4 v[94:95], off
	s_waitcnt vmcnt(8)
	s_waitcnt lgkmcnt(0)
	s_barrier
	s_setprio 1
	s_waitcnt lgkmcnt(0)
	v_mfma_f32_16x16x32_bf16 v[94:97], v[50:53], v[74:77], v[98:101]
	v_mfma_f32_16x16x32_bf16 v[86:89], v[58:61], v[74:77], v[86:89]
	v_mfma_f32_16x16x32_bf16 v[78:81], v[50:53], v[90:93], v[78:81]
	v_mfma_f32_16x16x32_bf16 v[66:69], v[58:61], v[90:93], v[66:69]
	v_mfma_f32_16x16x32_bf16 v[46:49], v[50:53], v[126:129], v[46:49]
	v_mfma_f32_16x16x32_bf16 v[22:25], v[58:61], v[126:129], v[22:25]
	v_mfma_f32_16x16x32_bf16 v[14:17], v[50:53], v[210:213], v[14:17]
	v_mfma_f32_16x16x32_bf16 v[6:9], v[58:61], v[210:213], v[6:9]
	v_mfma_f32_16x16x32_bf16 v[98:101], v[54:57], v[82:85], v[94:97]
	v_mfma_f32_16x16x32_bf16 v[86:89], v[62:65], v[82:85], v[86:89]
	v_mfma_f32_16x16x32_bf16 v[78:81], v[54:57], v[110:113], v[78:81]
	v_mfma_f32_16x16x32_bf16 v[66:69], v[62:65], v[110:113], v[66:69]
	v_mfma_f32_16x16x32_bf16 v[46:49], v[54:57], v[206:209], v[46:49]
	v_mfma_f32_16x16x32_bf16 v[22:25], v[62:65], v[206:209], v[22:25]
	v_mfma_f32_16x16x32_bf16 v[14:17], v[54:57], v[214:217], v[14:17]
	v_mfma_f32_16x16x32_bf16 v[6:9], v[62:65], v[214:217], v[6:9]
	v_mfma_f32_16x16x32_bf16 v[26:29], v[70:73], v[74:77], v[26:29]
	v_mfma_f32_16x16x32_bf16 v[94:97], v[142:145], v[82:85], v[26:29]
	v_mfma_f32_16x16x32_bf16 v[26:29], v[162:165], v[74:77], v[30:33]
	v_mfma_f32_16x16x32_bf16 v[82:85], v[182:185], v[82:85], v[26:29]
	v_mfma_f32_16x16x32_bf16 v[26:29], v[70:73], v[90:93], v[34:37]
	v_mfma_f32_16x16x32_bf16 v[74:77], v[142:145], v[110:113], v[26:29]
	v_mfma_f32_16x16x32_bf16 v[26:29], v[162:165], v[90:93], v[38:41]
	v_mfma_f32_16x16x32_bf16 v[62:65], v[182:185], v[110:113], v[26:29]
	v_mfma_f32_16x16x32_bf16 v[26:29], v[70:73], v[126:129], v[42:45]
	v_mfma_f32_16x16x32_bf16 v[18:21], v[162:165], v[126:129], v[18:21]
	v_mfma_f32_16x16x32_bf16 v[10:13], v[70:73], v[210:213], v[10:13]
	v_mfma_f32_16x16x32_bf16 v[2:5], v[162:165], v[210:213], v[2:5]
	v_mfma_f32_16x16x32_bf16 v[42:45], v[142:145], v[206:209], v[26:29]
	v_mfma_f32_16x16x32_bf16 v[18:21], v[182:185], v[206:209], v[18:21]
	v_mfma_f32_16x16x32_bf16 v[10:13], v[142:145], v[214:217], v[10:13]
	v_mfma_f32_16x16x32_bf16 v[2:5], v[182:185], v[214:217], v[2:5]
	s_setprio 0
	s_add_u32 s69, s69, 0x100
	s_addc_u32 s72, s72, 0
	s_add_u32 s20, s20, 0x100
	s_addc_u32 s21, s21, 0
	s_cmp_ge_i32 s62, s14
	s_mov_b32 s0, s62
	s_cbranch_scc1 .Lrot_exit_7
	s_add_i32 s62, s0, 2
	s_add_u32 s1, s20, 0xffff0080
	s_addc_u32 s42, s21, -1
	s_add_i32 s43, 0, 0x10000
	s_cmp_eq_u32 s71, s0
	s_cselect_b32 vcc_hi, s19, s42
	s_cselect_b32 vcc_lo, s25, s1
	s_cselect_b32 s1, s41, s72
	s_cselect_b32 s0, s67, s69
	s_add_i32 s52, 0, 0x14000
	s_branch .Lrot_head_7

; template <class Epi, class Sched>
; __device__ __forceinline__ void gemm_phase(LAS unsigned char* lds, const Gemm g, const Sched& S, const Epi& E) {
;     ...
;         for (int t = 0; t < nt; t += 2) {
;             if constexpr (Epi::HOOKS) { if (cur.kind == 3 && (t == 4 || t == 12)) { int fr_ = fr, fq_ = fq; asm volatile("" : "+v"(fr_), "+v"(fq_)); E.hook(acc, cur, t == 4 ? 0 : 1, wr, wc, fr_, fq_); } }
;             const bool last = (t == nt - 2);
;             const char* a1 = cA + (size_t)(t + 1) * kstep;
;             const char* a2 = last ? nA : cA + (size_t)(t + 2) * kstep; const char* b2 = last ? nB : cB + (size_t)(t + 2) * kstep;
;             const char* a3 = a2 + kstep; const char* b3 = b2 + kstep;
.LBB0_742:
	s_add_i32 s68, s0, 2
	s_add_u32 s1, s20, 0xfffc0080
	s_addc_u32 s44, s21, -1
	s_add_i32 s76, 0, 0x10000
	s_cmp_eq_u32 s69, s0
	s_cselect_b32 s45, s41, s44
	s_cselect_b32 s44, s43, s1
	s_cselect_b32 s1, s48, s77
	s_cselect_b32 s0, s53, s55
	s_add_i32 s82, 0, 0x14000
	s_branch .Lrot_body_8

; #define PG8_STAGE(bufoff, gbase, voff) do { _Pragma("unroll") for (int _i = 0; _i < 2; ++_i) \
;         __builtin_amdgcn_global_load_lds((const unsigned*)((const char*)(gbase) + (voff)[_i]), (LAS unsigned*)(lds + (bufoff) + ldsw + _i * 8192), 16, 0, 0); } while (0)
; #define PG8_LDA(dst, b, h) do { _Pragma("unroll") for (int m = 0; m < 4; ++m) _Pragma("unroll") for (int k = 0; k < 2; ++k) dst[m][k] = *(const LAS bf16x8*)(lds + PG8_SA(b, h) + aoff + m * 2048 + k * 1024); } while (0)
; #define PG8_LDB(dst, b, h) do { _Pragma("unroll") for (int n = 0; n < 2; ++n) _Pragma("unroll") for (int k = 0; k < 2; ++k) dst[n][k] = *(const LAS bf16x8*)(lds + PG8_SB(b, h) + boff + n * 2048 + k * 1024); } while (0)
; #define PG8_MMA(ai, bj, At, Bt) do { __builtin_amdgcn_s_setprio(1); _Pragma("unroll") for (int m = 0; m < 4; ++m) _Pragma("unroll") for (int n = 0; n < 2; ++n) _Pragma("unroll") for (int k = 0; k < 2; ++k) \
;         acc[ai][bj][m][n] = __builtin_amdgcn_mfma_f32_16x16x32_bf16(Bt[n][k], At[m][k], acc[ai][bj][m][n], 0, 0, 0); __builtin_amdgcn_s_setprio(0); } while (0)
; #define PG8_WAIT_V(n) asm volatile("s_waitcnt vmcnt(" #n ")" ::: "memory")
; #define PG8_WAIT_L(n) asm volatile("s_waitcnt lgkmcnt(" #n ")" ::: "memory")
; #define PG8_BAR __builtin_amdgcn_s_barrier()
; #define PG8_SCHED __builtin_amdgcn_sched_barrier(0)
; template <class Epi, class Sched>
; __device__ __forceinline__ void gemm_phase(LAS unsigned char* lds, const Gemm g, const Sched& S, const Epi& E) {
;     ...
;             const char* a1 = cA + (size_t)(t + 1) * kstep;
;             const char* a2 = last ? nA : cA + (size_t)(t + 2) * kstep; const char* b2 = last ? nB : cB + (size_t)(t + 2) * kstep;
;             const char* a3 = a2 + kstep; const char* b3 = b2 + kstep;
;             PG8_LDB(B0, 0, 0); PG8_LDB(B1, 0, 1); PG8_SCHED; PG8_LDA(At, 0, 0); PG8_STAGE(PG8_SA(1, 1), a1 + hstepA, voffA);
;             PG8_WAIT_V(8); PG8_WAIT_L(0); PG8_BAR; PG8_MMA(0, 0, At, B0); PG8_MMA(0, 1, At, B1); PG8_BAR; PG8_SCHED;
;             PG8_LDA(At, 0, 1); PG8_STAGE(PG8_SB(0, 0), b2, voffB); PG8_STAGE(PG8_SB(0, 1), b2 + hstepB, voffB); PG8_STAGE(PG8_SA(0, 0), a2, voffA);
;             PG8_WAIT_V(8); PG8_WAIT_L(0); PG8_BAR; PG8_MMA(1, 0, At, B0); PG8_MMA(1, 1, At, B1); PG8_BAR; PG8_SCHED;
.Lrot_body_8:
	v_add_u32_e32 v152, s76, v176
	v_add_u32_e32 v168, s82, v176
	ds_read_b128 v[140:143], v152
	ds_read_b128 v[144:147], v152 offset:1024
	ds_read_b128 v[148:151], v152 offset:2048
	ds_read_b128 v[152:155], v152 offset:3072
	ds_read_b128 v[156:159], v168
	ds_read_b128 v[160:163], v168 offset:1024
	ds_read_b128 v[164:167], v168 offset:2048
	ds_read_b128 v[168:171], v168 offset:3072
	v_lshl_add_u64 v[172:173], s[20:21], 0, v[138:139]
	s_add_i32 m0, s13, 0xc000
	ds_read_b128 v[178:181], v177
	ds_read_b128 v[182:185], v177 offset:1024
	ds_read_b128 v[196:199], v177 offset:2048
	ds_read_b128 v[200:203], v177 offset:3072
	ds_read_b128 v[204:207], v177 offset:4096
	ds_read_b128 v[208:211], v177 offset:5120
	ds_read_b128 v[212:215], v177 offset:6144
	ds_read_b128 v[216:219], v177 offset:7168
	global_load_lds_dwordx4 v[172:173], off
	v_lshl_add_u64 v[172:173], s[20:21], 0, v[136:137]
	s_add_i32 m0, s13, 0xe000
	s_nop 0
	global_load_lds_dwordx4 v[172:173], off
	s_waitcnt vmcnt(8)
	s_waitcnt lgkmcnt(0)
	s_barrier
	s_setprio 1
	s_waitcnt lgkmcnt(0)
	v_mfma_f32_16x16x32_bf16 v[126:129], v[140:143], v[178:181], v[126:129]
	v_mfma_f32_16x16x32_bf16 v[122:125], v[148:151], v[178:181], v[122:125]
	v_mfma_f32_16x16x32_bf16 v[110:113], v[140:143], v[196:199], v[110:113]
	v_mfma_f32_16x16x32_bf16 v[106:109], v[148:151], v[196:199], v[106:109]
	v_mfma_f32_16x16x32_bf16 v[94:97], v[140:143], v[204:207], v[94:97]
	v_mfma_f32_16x16x32_bf16 v[90:93], v[148:151], v[204:207], v[90:93]
	v_mfma_f32_16x16x32_bf16 v[78:81], v[140:143], v[212:215], v[78:81]
	v_mfma_f32_16x16x32_bf16 v[74:77], v[148:151], v[212:215], v[74:77]
	v_mfma_f32_16x16x32_bf16 v[126:129], v[144:147], v[182:185], v[126:129]
	v_mfma_f32_16x16x32_bf16 v[122:125], v[152:155], v[182:185], v[122:125]
	v_mfma_f32_16x16x32_bf16 v[110:113], v[144:147], v[200:203], v[110:113]
	v_mfma_f32_16x16x32_bf16 v[106:109], v[152:155], v[200:203], v[106:109]
	v_mfma_f32_16x16x32_bf16 v[94:97], v[144:147], v[208:211], v[94:97]
	v_mfma_f32_16x16x32_bf16 v[90:93], v[152:155], v[208:211], v[90:93]
	v_mfma_f32_16x16x32_bf16 v[78:81], v[144:147], v[216:219], v[78:81]
	v_mfma_f32_16x16x32_bf16 v[74:77], v[152:155], v[216:219], v[74:77]
	v_mfma_f32_16x16x32_bf16 v[118:121], v[156:159], v[178:181], v[118:121]
	v_mfma_f32_16x16x32_bf16 v[114:117], v[164:167], v[178:181], v[114:117]
	v_mfma_f32_16x16x32_bf16 v[102:105], v[156:159], v[196:199], v[102:105]
	v_mfma_f32_16x16x32_bf16 v[98:101], v[164:167], v[196:199], v[98:101]
	v_mfma_f32_16x16x32_bf16 v[86:89], v[156:159], v[204:207], v[86:89]
	v_mfma_f32_16x16x32_bf16 v[82:85], v[164:167], v[204:207], v[82:85]
	v_mfma_f32_16x16x32_bf16 v[70:73], v[156:159], v[212:215], v[70:73]
	v_mfma_f32_16x16x32_bf16 v[66:69], v[164:167], v[212:215], v[66:69]
	v_mfma_f32_16x16x32_bf16 v[118:121], v[160:163], v[182:185], v[118:121]
	v_mfma_f32_16x16x32_bf16 v[114:117], v[168:171], v[182:185], v[114:117]
	v_mfma_f32_16x16x32_bf16 v[102:105], v[160:163], v[200:203], v[102:105]
	v_mfma_f32_16x16x32_bf16 v[98:101], v[168:171], v[200:203], v[98:101]
	v_mfma_f32_16x16x32_bf16 v[86:89], v[160:163], v[208:211], v[86:89]
	v_mfma_f32_16x16x32_bf16 v[82:85], v[168:171], v[208:211], v[82:85]
	v_mfma_f32_16x16x32_bf16 v[70:73], v[160:163], v[216:219], v[70:73]
	v_mfma_f32_16x16x32_bf16 v[66:69], v[168:171], v[216:219], v[66:69]
	s_setprio 0
	s_barrier
	s_add_i32 s76, s76, s12
	v_lshl_add_u64 v[172:173], s[0:1], 0, v[0:1]
	s_mov_b32 m0, s76
	ds_read_b128 v[178:181], v177 offset:16384
	ds_read_b128 v[182:185], v177 offset:17408
	ds_read_b128 v[196:199], v177 offset:18432
	ds_read_b128 v[200:203], v177 offset:19456
	ds_read_b128 v[204:207], v177 offset:20480
	ds_read_b128 v[208:211], v177 offset:21504
	ds_read_b128 v[212:215], v177 offset:22528
	ds_read_b128 v[216:219], v177 offset:23552
	global_load_lds_dwordx4 v[172:173], off
	s_add_i32 m0, s76, 0x2000
	s_add_u32 s80, s0, 0x40000
	v_lshl_add_u64 v[220:221], s[0:1], 0, v[134:135]
	s_addc_u32 s81, s1, 0
	s_add_i32 s76, s82, s12
	global_load_lds_dwordx4 v[220:221], off
	v_lshl_add_u64 v[232:233], s[80:81], 0, v[0:1]
	s_mov_b32 m0, s76
	v_lshl_add_u64 v[234:235], s[44:45], 0, v[132:133]
	global_load_lds_dwordx4 v[232:233], off
	v_lshl_add_u64 v[232:233], s[80:81], 0, v[134:135]
	s_add_i32 m0, s76, 0x2000
	s_nop 0
	global_load_lds_dwordx4 v[232:233], off
	v_lshl_add_u64 v[232:233], s[44:45], 0, v[130:131]
	s_mov_b32 m0, s13
	s_nop 0
	global_load_lds_dwordx4 v[232:233], off
	s_mov_b32 m0, s14
	s_nop 0
	global_load_lds_dwordx4 v[234:235], off
	s_waitcnt vmcnt(8)
	s_waitcnt lgkmcnt(0)
	s_barrier
; #define PG8_STAGE(bufoff, gbase, voff) do { _Pragma("unroll") for (int _i = 0; _i < 2; ++_i) \
;         __builtin_amdgcn_global_load_lds((const unsigned*)((const char*)(gbase) + (voff)[_i]), (LAS unsigned*)(lds + (bufoff) + ldsw + _i * 8192), 16, 0, 0); } while (0)
; #define PG8_LDA(dst, b, h) do { _Pragma("unroll") for (int m = 0; m < 4; ++m) _Pragma("unroll") for (int k = 0; k < 2; ++k) dst[m][k] = *(const LAS bf16x8*)(lds + PG8_SA(b, h) + aoff + m * 2048 + k * 1024); } while (0)
; #define PG8_LDB(dst, b, h) do { _Pragma("unroll") for (int n = 0; n < 2; ++n) _Pragma("unroll") for (int k = 0; k < 2; ++k) dst[n][k] = *(const LAS bf16x8*)(lds + PG8_SB(b, h) + boff + n * 2048 + k * 1024); } while (0)
; #define PG8_MMA(ai, bj, At, Bt) do { __builtin_amdgcn_s_setprio(1); _Pragma("unroll") for (int m = 0; m < 4; ++m) _Pragma("unroll") for (int n = 0; n < 2; ++n) _Pragma("unroll") for (int k = 0; k < 2; ++k) \
;         acc[ai][bj][m][n] = __builtin_amdgcn_mfma_f32_16x16x32_bf16(Bt[n][k], At[m][k], acc[ai][bj][m][n], 0, 0, 0); __builtin_amdgcn_s_setprio(0); } while (0)
; #define PG8_WAIT_V(n) asm volatile("s_waitcnt vmcnt(" #n ")" ::: "memory")
; #define PG8_WAIT_L(n) asm volatile("s_waitcnt lgkmcnt(" #n ")" ::: "memory")
; #define PG8_BAR __builtin_amdgcn_s_barrier()
; #define PG8_SCHED __builtin_amdgcn_sched_barrier(0)
; template <class Epi, class Sched>
; __device__ __forceinline__ void gemm_phase(LAS unsigned char* lds, const Gemm g, const Sched& S, const Epi& E) {
;     ...
;             PG8_WAIT_V(8); PG8_WAIT_L(0); PG8_BAR; PG8_MMA(1, 0, At, B0); PG8_MMA(1, 1, At, B1); PG8_BAR; PG8_SCHED;
;             PG8_LDB(B0, 1, 0); PG8_LDB(B1, 1, 1); PG8_SCHED; PG8_LDA(At, 1, 0); PG8_STAGE(PG8_SA(0, 1), a2 + hstepA, voffA);
;             PG8_WAIT_V(8); PG8_WAIT_L(0); PG8_BAR; PG8_MMA(0, 0, At, B0); PG8_MMA(0, 1, At, B1); PG8_BAR; PG8_SCHED;
	s_setprio 1
	s_waitcnt lgkmcnt(0)
	v_mfma_f32_16x16x32_bf16 v[62:65], v[140:143], v[178:181], v[62:65]
	v_mfma_f32_16x16x32_bf16 v[58:61], v[148:151], v[178:181], v[58:61]
	v_mfma_f32_16x16x32_bf16 v[46:49], v[140:143], v[196:199], v[46:49]
	v_mfma_f32_16x16x32_bf16 v[42:45], v[148:151], v[196:199], v[42:45]
	v_mfma_f32_16x16x32_bf16 v[30:33], v[140:143], v[204:207], v[30:33]
	v_mfma_f32_16x16x32_bf16 v[26:29], v[148:151], v[204:207], v[26:29]
	v_mfma_f32_16x16x32_bf16 v[14:17], v[140:143], v[212:215], v[14:17]
	v_mfma_f32_16x16x32_bf16 v[10:13], v[148:151], v[212:215], v[10:13]
	v_mfma_f32_16x16x32_bf16 v[62:65], v[144:147], v[182:185], v[62:65]
	v_mfma_f32_16x16x32_bf16 v[58:61], v[152:155], v[182:185], v[58:61]
	v_mfma_f32_16x16x32_bf16 v[46:49], v[144:147], v[200:203], v[46:49]
	v_mfma_f32_16x16x32_bf16 v[42:45], v[152:155], v[200:203], v[42:45]
	v_mfma_f32_16x16x32_bf16 v[30:33], v[144:147], v[208:211], v[30:33]
	v_mfma_f32_16x16x32_bf16 v[26:29], v[152:155], v[208:211], v[26:29]
	v_mfma_f32_16x16x32_bf16 v[14:17], v[144:147], v[216:219], v[14:17]
	v_mfma_f32_16x16x32_bf16 v[10:13], v[152:155], v[216:219], v[10:13]
	v_mfma_f32_16x16x32_bf16 v[54:57], v[156:159], v[178:181], v[54:57]
	v_mfma_f32_16x16x32_bf16 v[50:53], v[164:167], v[178:181], v[50:53]
	v_mfma_f32_16x16x32_bf16 v[38:41], v[156:159], v[196:199], v[38:41]
	v_mfma_f32_16x16x32_bf16 v[34:37], v[164:167], v[196:199], v[34:37]
	v_mfma_f32_16x16x32_bf16 v[22:25], v[156:159], v[204:207], v[22:25]
	v_mfma_f32_16x16x32_bf16 v[18:21], v[164:167], v[204:207], v[18:21]
	v_mfma_f32_16x16x32_bf16 v[6:9], v[156:159], v[212:215], v[6:9]
	v_mfma_f32_16x16x32_bf16 v[2:5], v[164:167], v[212:215], v[2:5]
	v_mfma_f32_16x16x32_bf16 v[54:57], v[160:163], v[182:185], v[54:57]
	v_mfma_f32_16x16x32_bf16 v[50:53], v[168:171], v[182:185], v[50:53]
	v_mfma_f32_16x16x32_bf16 v[38:41], v[160:163], v[200:203], v[38:41]
	v_mfma_f32_16x16x32_bf16 v[34:37], v[168:171], v[200:203], v[34:37]
	v_mfma_f32_16x16x32_bf16 v[22:25], v[160:163], v[208:211], v[22:25]
	v_mfma_f32_16x16x32_bf16 v[18:21], v[168:171], v[208:211], v[18:21]
	v_mfma_f32_16x16x32_bf16 v[6:9], v[160:163], v[216:219], v[6:9]
	v_mfma_f32_16x16x32_bf16 v[2:5], v[168:171], v[216:219], v[2:5]
	s_setprio 0
	s_barrier
	s_add_i32 s76, 0, 0x18000
	s_add_i32 s80, 0, 0x1c000
	v_add_u32_e32 v152, s76, v176
	v_add_u32_e32 v168, s80, v176
	ds_read_b128 v[140:143], v152
	ds_read_b128 v[144:147], v152 offset:1024
	ds_read_b128 v[148:151], v152 offset:2048
	ds_read_b128 v[152:155], v152 offset:3072
	ds_read_b128 v[156:159], v168
	ds_read_b128 v[160:163], v168 offset:1024
	ds_read_b128 v[164:167], v168 offset:2048
	ds_read_b128 v[168:171], v168 offset:3072
	s_add_u32 s44, s44, 0x40000
	s_addc_u32 s45, s45, 0
	s_mov_b32 m0, s15
	v_lshl_add_u64 v[248:249], s[44:45], 0, v[130:131]
	ds_read_b128 v[178:181], v177 offset:32768
	ds_read_b128 v[182:185], v177 offset:33792
	ds_read_b128 v[196:199], v177 offset:34816
	ds_read_b128 v[200:203], v177 offset:35840
	ds_read_b128 v[204:207], v177 offset:36864
	ds_read_b128 v[208:211], v177 offset:37888
	ds_read_b128 v[212:215], v177 offset:38912
	ds_read_b128 v[216:219], v177 offset:39936
	global_load_lds_dwordx4 v[248:249], off
	v_lshl_add_u64 v[248:249], s[44:45], 0, v[132:133]
	s_mov_b32 m0, s16
	s_nop 0
	global_load_lds_dwordx4 v[248:249], off
	s_waitcnt vmcnt(8)
	s_waitcnt lgkmcnt(0)
	s_barrier
	s_setprio 1
	s_waitcnt lgkmcnt(0)
	v_mfma_f32_16x16x32_bf16 v[126:129], v[140:143], v[178:181], v[126:129]
	v_mfma_f32_16x16x32_bf16 v[122:125], v[148:151], v[178:181], v[122:125]
	v_mfma_f32_16x16x32_bf16 v[110:113], v[140:143], v[196:199], v[110:113]
	v_mfma_f32_16x16x32_bf16 v[106:109], v[148:151], v[196:199], v[106:109]
	v_mfma_f32_16x16x32_bf16 v[94:97], v[140:143], v[204:207], v[94:97]
	v_mfma_f32_16x16x32_bf16 v[90:93], v[148:151], v[204:207], v[90:93]
	v_mfma_f32_16x16x32_bf16 v[78:81], v[140:143], v[212:215], v[78:81]
	v_mfma_f32_16x16x32_bf16 v[74:77], v[148:151], v[212:215], v[74:77]
	v_mfma_f32_16x16x32_bf16 v[126:129], v[144:147], v[182:185], v[126:129]
	v_mfma_f32_16x16x32_bf16 v[122:125], v[152:155], v[182:185], v[122:125]
	v_mfma_f32_16x16x32_bf16 v[110:113], v[144:147], v[200:203], v[110:113]
	v_mfma_f32_16x16x32_bf16 v[106:109], v[152:155], v[200:203], v[106:109]
	v_mfma_f32_16x16x32_bf16 v[94:97], v[144:147], v[208:211], v[94:97]
	v_mfma_f32_16x16x32_bf16 v[90:93], v[152:155], v[208:211], v[90:93]
	v_mfma_f32_16x16x32_bf16 v[78:81], v[144:147], v[216:219], v[78:81]
	v_mfma_f32_16x16x32_bf16 v[74:77], v[152:155], v[216:219], v[74:77]
	v_mfma_f32_16x16x32_bf16 v[118:121], v[156:159], v[178:181], v[118:121]
	v_mfma_f32_16x16x32_bf16 v[114:117], v[164:167], v[178:181], v[114:117]
	v_mfma_f32_16x16x32_bf16 v[102:105], v[156:159], v[196:199], v[102:105]
	v_mfma_f32_16x16x32_bf16 v[98:101], v[164:167], v[196:199], v[98:101]
	v_mfma_f32_16x16x32_bf16 v[86:89], v[156:159], v[204:207], v[86:89]
	v_mfma_f32_16x16x32_bf16 v[82:85], v[164:167], v[204:207], v[82:85]
	v_mfma_f32_16x16x32_bf16 v[70:73], v[156:159], v[212:215], v[70:73]
	v_mfma_f32_16x16x32_bf16 v[66:69], v[164:167], v[212:215], v[66:69]
	v_mfma_f32_16x16x32_bf16 v[118:121], v[160:163], v[182:185], v[118:121]
	v_mfma_f32_16x16x32_bf16 v[114:117], v[168:171], v[182:185], v[114:117]
	v_mfma_f32_16x16x32_bf16 v[102:105], v[160:163], v[200:203], v[102:105]
	v_mfma_f32_16x16x32_bf16 v[98:101], v[168:171], v[200:203], v[98:101]
	v_mfma_f32_16x16x32_bf16 v[86:89], v[160:163], v[208:211], v[86:89]
	v_mfma_f32_16x16x32_bf16 v[82:85], v[168:171], v[208:211], v[82:85]
	v_mfma_f32_16x16x32_bf16 v[70:73], v[160:163], v[216:219], v[70:73]
	v_mfma_f32_16x16x32_bf16 v[66:69], v[168:171], v[216:219], v[66:69]
	s_setprio 0
	s_barrier
; #define PG8_STAGE(bufoff, gbase, voff) do { _Pragma("unroll") for (int _i = 0; _i < 2; ++_i) \
;         __builtin_amdgcn_global_load_lds((const unsigned*)((const char*)(gbase) + (voff)[_i]), (LAS unsigned*)(lds + (bufoff) + ldsw + _i * 8192), 16, 0, 0); } while (0)
; #define PG8_LDA(dst, b, h) do { _Pragma("unroll") for (int m = 0; m < 4; ++m) _Pragma("unroll") for (int k = 0; k < 2; ++k) dst[m][k] = *(const LAS bf16x8*)(lds + PG8_SA(b, h) + aoff + m * 2048 + k * 1024); } while (0)
; #define PG8_MMA(ai, bj, At, Bt) do { __builtin_amdgcn_s_setprio(1); _Pragma("unroll") for (int m = 0; m < 4; ++m) _Pragma("unroll") for (int n = 0; n < 2; ++n) _Pragma("unroll") for (int k = 0; k < 2; ++k) \
;         acc[ai][bj][m][n] = __builtin_amdgcn_mfma_f32_16x16x32_bf16(Bt[n][k], At[m][k], acc[ai][bj][m][n], 0, 0, 0); __builtin_amdgcn_s_setprio(0); } while (0)
; #define PG8_WAIT_V(n) asm volatile("s_waitcnt vmcnt(" #n ")" ::: "memory")
; #define PG8_WAIT_L(n) asm volatile("s_waitcnt lgkmcnt(" #n ")" ::: "memory")
; #define PG8_BAR __builtin_amdgcn_s_barrier()
; #define PG8_SCHED __builtin_amdgcn_sched_barrier(0)
; template <class Epi, class Sched>
; __device__ __forceinline__ void gemm_phase(LAS unsigned char* lds, const Gemm g, const Sched& S, const Epi& E) {
;     ...
;         for (int t = 0; t < nt; t += 2) {
;             if constexpr (Epi::HOOKS) { if (cur.kind == 3 && (t == 4 || t == 12)) { int fr_ = fr, fq_ = fq; asm volatile("" : "+v"(fr_), "+v"(fq_)); E.hook(acc, cur, t == 4 ? 0 : 1, wr, wc, fr_, fq_); } }
;             const bool last = (t == nt - 2);
;             const char* a1 = cA + (size_t)(t + 1) * kstep;
;             const char* a2 = last ? nA : cA + (size_t)(t + 2) * kstep; const char* b2 = last ? nB : cB + (size_t)(t + 2) * kstep;
;             const char* a3 = a2 + kstep; const char* b3 = b2 + kstep;
;     ...
;             PG8_LDA(At, 1, 1); PG8_STAGE(PG8_SB(1, 0), b3, voffB); PG8_STAGE(PG8_SB(1, 1), b3 + hstepB, voffB); PG8_STAGE(PG8_SA(1, 0), a3, voffA);
;             PG8_WAIT_V(8); PG8_WAIT_L(0); PG8_BAR; PG8_MMA(1, 0, At, B0); PG8_MMA(1, 1, At, B1); PG8_BAR; PG8_SCHED;
	s_add_i32 s44, s76, s12
	v_lshl_add_u64 v[172:173], v[172:173], 0, s[26:27]
	s_mov_b32 m0, s44
	ds_read_b128 v[178:181], v177 offset:49152
	ds_read_b128 v[182:185], v177 offset:50176
	ds_read_b128 v[196:199], v177 offset:51200
	ds_read_b128 v[200:203], v177 offset:52224
	ds_read_b128 v[204:207], v177 offset:53248
	ds_read_b128 v[208:211], v177 offset:54272
	ds_read_b128 v[212:215], v177 offset:55296
	ds_read_b128 v[216:219], v177 offset:56320
	global_load_lds_dwordx4 v[172:173], off
	s_add_i32 m0, s44, 0x2000
	s_add_u32 s0, s0, 0x40080
	v_lshl_add_u64 v[172:173], v[220:221], 0, s[26:27]
	s_addc_u32 s1, s1, 0
	s_add_i32 s44, s80, s12
	global_load_lds_dwordx4 v[172:173], off
	v_lshl_add_u64 v[172:173], s[0:1], 0, v[0:1]
	s_mov_b32 m0, s44
	s_nop 0
	global_load_lds_dwordx4 v[172:173], off
	v_lshl_add_u64 v[172:173], s[0:1], 0, v[134:135]
	s_add_i32 m0, s44, 0x2000
	s_nop 0
	global_load_lds_dwordx4 v[172:173], off
	v_lshl_add_u64 v[172:173], v[232:233], 0, s[26:27]
	s_mov_b32 m0, s65
	s_nop 0
	global_load_lds_dwordx4 v[172:173], off
	v_lshl_add_u64 v[172:173], v[234:235], 0, s[26:27]
	s_mov_b32 m0, s67
	s_nop 0
	global_load_lds_dwordx4 v[172:173], off
	s_waitcnt vmcnt(8)
	s_waitcnt lgkmcnt(0)
	s_barrier
	s_setprio 1
	s_waitcnt lgkmcnt(0)
	v_mfma_f32_16x16x32_bf16 v[62:65], v[140:143], v[178:181], v[62:65]
	v_mfma_f32_16x16x32_bf16 v[58:61], v[148:151], v[178:181], v[58:61]
	v_mfma_f32_16x16x32_bf16 v[46:49], v[140:143], v[196:199], v[46:49]
	v_mfma_f32_16x16x32_bf16 v[42:45], v[148:151], v[196:199], v[42:45]
	v_mfma_f32_16x16x32_bf16 v[30:33], v[140:143], v[204:207], v[30:33]
	v_mfma_f32_16x16x32_bf16 v[26:29], v[148:151], v[204:207], v[26:29]
	v_mfma_f32_16x16x32_bf16 v[14:17], v[140:143], v[212:215], v[14:17]
	v_mfma_f32_16x16x32_bf16 v[10:13], v[148:151], v[212:215], v[10:13]
	v_mfma_f32_16x16x32_bf16 v[62:65], v[144:147], v[182:185], v[62:65]
	v_mfma_f32_16x16x32_bf16 v[58:61], v[152:155], v[182:185], v[58:61]
	v_mfma_f32_16x16x32_bf16 v[46:49], v[144:147], v[200:203], v[46:49]
	v_mfma_f32_16x16x32_bf16 v[42:45], v[152:155], v[200:203], v[42:45]
	v_mfma_f32_16x16x32_bf16 v[30:33], v[144:147], v[208:211], v[30:33]
	v_mfma_f32_16x16x32_bf16 v[26:29], v[152:155], v[208:211], v[26:29]
	v_mfma_f32_16x16x32_bf16 v[14:17], v[144:147], v[216:219], v[14:17]
	v_mfma_f32_16x16x32_bf16 v[10:13], v[152:155], v[216:219], v[10:13]
	v_mfma_f32_16x16x32_bf16 v[54:57], v[156:159], v[178:181], v[54:57]
	v_mfma_f32_16x16x32_bf16 v[50:53], v[164:167], v[178:181], v[50:53]
	v_mfma_f32_16x16x32_bf16 v[38:41], v[156:159], v[196:199], v[38:41]
	v_mfma_f32_16x16x32_bf16 v[34:37], v[164:167], v[196:199], v[34:37]
	v_mfma_f32_16x16x32_bf16 v[22:25], v[156:159], v[204:207], v[22:25]
	v_mfma_f32_16x16x32_bf16 v[18:21], v[164:167], v[204:207], v[18:21]
	v_mfma_f32_16x16x32_bf16 v[6:9], v[156:159], v[212:215], v[6:9]
	v_mfma_f32_16x16x32_bf16 v[2:5], v[164:167], v[212:215], v[2:5]
	v_mfma_f32_16x16x32_bf16 v[54:57], v[160:163], v[182:185], v[54:57]
	v_mfma_f32_16x16x32_bf16 v[50:53], v[168:171], v[182:185], v[50:53]
	v_mfma_f32_16x16x32_bf16 v[38:41], v[160:163], v[200:203], v[38:41]
	v_mfma_f32_16x16x32_bf16 v[34:37], v[168:171], v[200:203], v[34:37]
	v_mfma_f32_16x16x32_bf16 v[22:25], v[160:163], v[208:211], v[22:25]
	v_mfma_f32_16x16x32_bf16 v[18:21], v[168:171], v[208:211], v[18:21]
	v_mfma_f32_16x16x32_bf16 v[6:9], v[160:163], v[216:219], v[6:9]
	v_mfma_f32_16x16x32_bf16 v[2:5], v[168:171], v[216:219], v[2:5]
	s_setprio 0
	s_add_u32 s55, s55, 0x100
	s_addc_u32 s77, s77, 0
	s_add_u32 s20, s20, 0x100
	s_addc_u32 s21, s21, 0
	s_cmp_ge_i32 s68, s19
	s_mov_b32 s0, s68
	s_cbranch_scc1 .Lrot_exit_8
	s_add_i32 s68, s0, 2
	s_add_u32 s1, s20, 0xfffc0080
	s_addc_u32 s44, s21, -1
	s_add_i32 s76, 0, 0x10000
	s_cmp_eq_u32 s69, s0
	s_cselect_b32 s45, s41, s44
	s_cselect_b32 s44, s43, s1
	s_cselect_b32 s1, s48, s77
	s_cselect_b32 s0, s53, s55
	s_add_i32 s82, 0, 0x14000
	s_branch .Lrot_head_8
